# s_setprio 1 issued before the barrier that opens each MFMA segment (wave already prioritised at release), on v32
# baseline (speedup 1.0000x reference)
; #define PG8_STAGE(bufoff, gbase, voff) do { _Pragma("unroll") for (int _i = 0; _i < 2; ++_i) \
;         __builtin_amdgcn_global_load_lds((const unsigned*)((const char*)(gbase) + (voff)[_i]), (LAS unsigned*)(lds + (bufoff) + ldsw + _i * 8192), 16, 0, 0); } while (0)
; #define PG8_LDA(dst, b, h) do { _Pragma("unroll") for (int m = 0; m < 4; ++m) _Pragma("unroll") for (int k = 0; k < 2; ++k) dst[m][k] = *(const LAS bf16x8*)(lds + PG8_SA(b, h) + aoff + m * 2048 + k * 1024); } while (0)
; #define PG8_LDB(dst, b, h) do { _Pragma("unroll") for (int n = 0; n < 2; ++n) _Pragma("unroll") for (int k = 0; k < 2; ++k) dst[n][k] = *(const LAS bf16x8*)(lds + PG8_SB(b, h) + boff + n * 2048 + k * 1024); } while (0)
; #define PG8_MMA(ai, bj, At, Bt) do { __builtin_amdgcn_s_setprio(1); _Pragma("unroll") for (int m = 0; m < 4; ++m) _Pragma("unroll") for (int n = 0; n < 2; ++n) _Pragma("unroll") for (int k = 0; k < 2; ++k) \
;         acc[ai][bj][m][n] = __builtin_amdgcn_mfma_f32_16x16x32_bf16(Bt[n][k], At[m][k], acc[ai][bj][m][n], 0, 0, 0); __builtin_amdgcn_s_setprio(0); } while (0)
; #define PG8_WAIT_V(n) asm volatile("s_waitcnt vmcnt(" #n ")" ::: "memory")
; #define PG8_WAIT_L(n) asm volatile("s_waitcnt lgkmcnt(" #n ")" ::: "memory")
; #define PG8_BAR __builtin_amdgcn_s_barrier()
; #define PG8_SCHED __builtin_amdgcn_sched_barrier(0)
; template <class Epi>
; __device__ __forceinline__ void gemm_phase(LAS unsigned char* lds, const Gemm g, const StaticOrder& S, const Epi& E) {
;     ...
;         for (int t = 0; t < nt; t += 2) {
;             const bool last = (t == nt - 2);
;             const char* a1 = cA + (size_t)(t + 1) * kstep;
;             const char* a2 = last ? nA : cA + (size_t)(t + 2) * kstep; const char* b2 = last ? nB : cB + (size_t)(t + 2) * kstep;
;             const char* a3 = a2 + kstep; const char* b3 = b2 + kstep;
;             PG8_LDB(B0, 0, 0); PG8_LDB(B1, 0, 1); PG8_SCHED; PG8_LDA(At, 0, 0); PG8_STAGE(PG8_SA(1, 1), a1 + hstepA, voffA);
;             PG8_WAIT_V(8); PG8_WAIT_L(0); PG8_BAR; PG8_MMA(0, 0, At, B0); PG8_MMA(0, 1, At, B1); PG8_BAR; PG8_SCHED;
;             PG8_LDA(At, 0, 1); PG8_STAGE(PG8_SB(0, 0), b2, voffB); PG8_STAGE(PG8_SB(0, 1), b2 + hstepB, voffB); PG8_STAGE(PG8_SA(0, 0), a2, voffA);
.LBB0_245:
	ds_read_b128 v[152:155], v148
	ds_read_b128 v[156:159], v148 offset:1024
	ds_read_b128 v[160:163], v148 offset:2048
	ds_read_b128 v[164:167], v148 offset:3072
	ds_read_b128 v[168:171], v149
	ds_read_b128 v[172:175], v149 offset:1024
	ds_read_b128 v[176:179], v149 offset:2048
	ds_read_b128 v[180:183], v149 offset:3072
	s_add_i32 s64, s26, 2
	s_add_u32 s27, s24, 0xfff80080
	s_addc_u32 s30, s25, -1
	s_cmp_eq_u32 s54, s26
	s_cselect_b32 s26, s61, s62
	s_cselect_b32 s31, s15, s30
	s_cselect_b32 s30, s17, s27
	s_cselect_b32 s27, s60, s63
	v_lshl_add_u64 v[220:221], s[24:25], 0, v[138:139]
	s_add_i32 m0, s44, 0xc000
	ds_read_b128 v[184:187], v150
	ds_read_b128 v[188:191], v150 offset:1024
	ds_read_b128 v[192:195], v150 offset:2048
	ds_read_b128 v[196:199], v150 offset:3072
	ds_read_b128 v[200:203], v150 offset:4096
	ds_read_b128 v[208:211], v150 offset:5120
	ds_read_b128 v[212:215], v150 offset:6144
	ds_read_b128 v[216:219], v150 offset:7168
	global_load_lds_dwordx4 v[220:221], off
	v_lshl_add_u64 v[220:221], s[24:25], 0, v[140:141]
	s_add_i32 m0, s44, 0xe000
	s_nop 0
	global_load_lds_dwordx4 v[220:221], off
	s_waitcnt vmcnt(8)
	s_waitcnt lgkmcnt(0)
	s_setprio 1
	s_barrier
	s_waitcnt lgkmcnt(0)
	v_mfma_f32_16x16x32_bf16 v[120:123], v[152:155], v[184:187], v[120:123]
	v_mfma_f32_16x16x32_bf16 v[120:123], v[156:159], v[188:191], v[120:123]
	v_mfma_f32_16x16x32_bf16 v[116:119], v[164:167], v[188:191], v[116:119]
	v_mfma_f32_16x16x32_bf16 v[116:119], v[160:163], v[184:187], v[116:119]
	v_mfma_f32_16x16x32_bf16 v[124:127], v[168:171], v[184:187], v[124:127]
	v_mfma_f32_16x16x32_bf16 v[124:127], v[172:175], v[188:191], v[124:127]
	v_mfma_f32_16x16x32_bf16 v[112:115], v[180:183], v[188:191], v[112:115]
	v_mfma_f32_16x16x32_bf16 v[112:115], v[176:179], v[184:187], v[112:115]
	v_mfma_f32_16x16x32_bf16 v[96:99], v[176:179], v[192:195], v[96:99]
	v_mfma_f32_16x16x32_bf16 v[96:99], v[180:183], v[196:199], v[96:99]
	v_mfma_f32_16x16x32_bf16 v[104:107], v[172:175], v[196:199], v[104:107]
	v_mfma_f32_16x16x32_bf16 v[104:107], v[168:171], v[192:195], v[104:107]
	v_mfma_f32_16x16x32_bf16 v[100:103], v[160:163], v[192:195], v[100:103]
	v_mfma_f32_16x16x32_bf16 v[100:103], v[164:167], v[196:199], v[100:103]
	v_mfma_f32_16x16x32_bf16 v[108:111], v[156:159], v[196:199], v[108:111]
	v_mfma_f32_16x16x32_bf16 v[108:111], v[152:155], v[192:195], v[108:111]
	s_setprio 0
	s_setprio 1
	v_mfma_f32_16x16x32_bf16 v[92:95], v[152:155], v[200:203], v[92:95]
	v_mfma_f32_16x16x32_bf16 v[92:95], v[156:159], v[208:211], v[92:95]
	v_mfma_f32_16x16x32_bf16 v[84:87], v[164:167], v[208:211], v[84:87]
	v_mfma_f32_16x16x32_bf16 v[84:87], v[160:163], v[200:203], v[84:87]
	v_mfma_f32_16x16x32_bf16 v[88:91], v[168:171], v[200:203], v[88:91]
	v_mfma_f32_16x16x32_bf16 v[88:91], v[172:175], v[208:211], v[88:91]
	v_mfma_f32_16x16x32_bf16 v[80:83], v[180:183], v[208:211], v[80:83]
	v_mfma_f32_16x16x32_bf16 v[80:83], v[176:179], v[200:203], v[80:83]
	v_mfma_f32_16x16x32_bf16 v[64:67], v[176:179], v[212:215], v[64:67]
	v_mfma_f32_16x16x32_bf16 v[64:67], v[180:183], v[216:219], v[64:67]
	v_mfma_f32_16x16x32_bf16 v[72:75], v[172:175], v[216:219], v[72:75]
	v_mfma_f32_16x16x32_bf16 v[72:75], v[168:171], v[212:215], v[72:75]
	v_mfma_f32_16x16x32_bf16 v[68:71], v[160:163], v[212:215], v[68:71]
	v_mfma_f32_16x16x32_bf16 v[68:71], v[164:167], v[216:219], v[68:71]
	v_mfma_f32_16x16x32_bf16 v[76:79], v[156:159], v[216:219], v[76:79]
	v_mfma_f32_16x16x32_bf16 v[76:79], v[152:155], v[212:215], v[76:79]
	s_setprio 0
	s_barrier
	s_add_i32 s65, s57, s33
	v_lshl_add_u64 v[220:221], s[26:27], 0, v[132:133]
	s_mov_b32 m0, s65
	ds_read_b128 v[184:187], v150 offset:16384
	ds_read_b128 v[188:191], v150 offset:17408
	ds_read_b128 v[192:195], v150 offset:18432
	ds_read_b128 v[196:199], v150 offset:19456
	ds_read_b128 v[200:203], v150 offset:20480
	ds_read_b128 v[208:211], v150 offset:21504
	ds_read_b128 v[212:215], v150 offset:22528
	ds_read_b128 v[216:219], v150 offset:23552
	global_load_lds_dwordx4 v[220:221], off
	s_add_i32 m0, s65, 0x2000
	s_add_u32 s66, s26, 0x80000
	v_lshl_add_u64 v[222:223], s[26:27], 0, v[128:129]
	s_addc_u32 s67, s27, 0
	s_add_i32 s65, s58, s33
	global_load_lds_dwordx4 v[222:223], off
	v_lshl_add_u64 v[224:225], s[66:67], 0, v[132:133]
	s_mov_b32 m0, s65
	v_lshl_add_u64 v[226:227], s[30:31], 0, v[130:131]
	global_load_lds_dwordx4 v[224:225], off
	v_lshl_add_u64 v[224:225], s[66:67], 0, v[128:129]
	s_add_i32 m0, s65, 0x2000
	s_nop 0
	global_load_lds_dwordx4 v[224:225], off
	v_lshl_add_u64 v[224:225], s[30:31], 0, v[134:135]
	s_mov_b32 m0, s44
	s_nop 0
	global_load_lds_dwordx4 v[224:225], off
	s_mov_b32 m0, s45
	s_nop 0
	global_load_lds_dwordx4 v[226:227], off
	s_waitcnt vmcnt(8)
	s_waitcnt lgkmcnt(0)
	s_setprio 1
	s_barrier
; #define PG8_STAGE(bufoff, gbase, voff) do { _Pragma("unroll") for (int _i = 0; _i < 2; ++_i) \
;         __builtin_amdgcn_global_load_lds((const unsigned*)((const char*)(gbase) + (voff)[_i]), (LAS unsigned*)(lds + (bufoff) + ldsw + _i * 8192), 16, 0, 0); } while (0)
; #define PG8_LDA(dst, b, h) do { _Pragma("unroll") for (int m = 0; m < 4; ++m) _Pragma("unroll") for (int k = 0; k < 2; ++k) dst[m][k] = *(const LAS bf16x8*)(lds + PG8_SA(b, h) + aoff + m * 2048 + k * 1024); } while (0)
; #define PG8_LDB(dst, b, h) do { _Pragma("unroll") for (int n = 0; n < 2; ++n) _Pragma("unroll") for (int k = 0; k < 2; ++k) dst[n][k] = *(const LAS bf16x8*)(lds + PG8_SB(b, h) + boff + n * 2048 + k * 1024); } while (0)
; #define PG8_MMA(ai, bj, At, Bt) do { __builtin_amdgcn_s_setprio(1); _Pragma("unroll") for (int m = 0; m < 4; ++m) _Pragma("unroll") for (int n = 0; n < 2; ++n) _Pragma("unroll") for (int k = 0; k < 2; ++k) \
;         acc[ai][bj][m][n] = __builtin_amdgcn_mfma_f32_16x16x32_bf16(Bt[n][k], At[m][k], acc[ai][bj][m][n], 0, 0, 0); __builtin_amdgcn_s_setprio(0); } while (0)
; #define PG8_WAIT_V(n) asm volatile("s_waitcnt vmcnt(" #n ")" ::: "memory")
; #define PG8_WAIT_L(n) asm volatile("s_waitcnt lgkmcnt(" #n ")" ::: "memory")
; #define PG8_BAR __builtin_amdgcn_s_barrier()
; #define PG8_SCHED __builtin_amdgcn_sched_barrier(0)
; template <class Epi>
; __device__ __forceinline__ void gemm_phase(LAS unsigned char* lds, const Gemm g, const StaticOrder& S, const Epi& E) {
;     ...
;             PG8_WAIT_V(8); PG8_WAIT_L(0); PG8_BAR; PG8_MMA(1, 0, At, B0); PG8_MMA(1, 1, At, B1); PG8_BAR; PG8_SCHED;
;             PG8_LDB(B0, 1, 0); PG8_LDB(B1, 1, 1); PG8_SCHED; PG8_LDA(At, 1, 0); PG8_STAGE(PG8_SA(0, 1), a2 + hstepA, voffA);
;             PG8_WAIT_V(8); PG8_WAIT_L(0); PG8_BAR; PG8_MMA(0, 0, At, B0); PG8_MMA(0, 1, At, B1); PG8_BAR; PG8_SCHED;
	s_waitcnt lgkmcnt(0)
	v_mfma_f32_16x16x32_bf16 v[60:63], v[152:155], v[184:187], v[60:63]
	v_mfma_f32_16x16x32_bf16 v[60:63], v[156:159], v[188:191], v[60:63]
	v_mfma_f32_16x16x32_bf16 v[52:55], v[164:167], v[188:191], v[52:55]
	v_mfma_f32_16x16x32_bf16 v[52:55], v[160:163], v[184:187], v[52:55]
	v_mfma_f32_16x16x32_bf16 v[56:59], v[168:171], v[184:187], v[56:59]
	v_mfma_f32_16x16x32_bf16 v[56:59], v[172:175], v[188:191], v[56:59]
	v_mfma_f32_16x16x32_bf16 v[48:51], v[180:183], v[188:191], v[48:51]
	v_mfma_f32_16x16x32_bf16 v[48:51], v[176:179], v[184:187], v[48:51]
	v_mfma_f32_16x16x32_bf16 v[32:35], v[176:179], v[192:195], v[32:35]
	v_mfma_f32_16x16x32_bf16 v[32:35], v[180:183], v[196:199], v[32:35]
	v_mfma_f32_16x16x32_bf16 v[40:43], v[172:175], v[196:199], v[40:43]
	v_mfma_f32_16x16x32_bf16 v[40:43], v[168:171], v[192:195], v[40:43]
	v_mfma_f32_16x16x32_bf16 v[36:39], v[160:163], v[192:195], v[36:39]
	v_mfma_f32_16x16x32_bf16 v[36:39], v[164:167], v[196:199], v[36:39]
	v_mfma_f32_16x16x32_bf16 v[44:47], v[156:159], v[196:199], v[44:47]
	v_mfma_f32_16x16x32_bf16 v[44:47], v[152:155], v[192:195], v[44:47]
	s_setprio 0
	s_setprio 1
	v_mfma_f32_16x16x32_bf16 v[28:31], v[152:155], v[200:203], v[28:31]
	v_mfma_f32_16x16x32_bf16 v[28:31], v[156:159], v[208:211], v[28:31]
	v_mfma_f32_16x16x32_bf16 v[20:23], v[164:167], v[208:211], v[20:23]
	v_mfma_f32_16x16x32_bf16 v[20:23], v[160:163], v[200:203], v[20:23]
	v_mfma_f32_16x16x32_bf16 v[24:27], v[168:171], v[200:203], v[24:27]
	v_mfma_f32_16x16x32_bf16 v[24:27], v[172:175], v[208:211], v[24:27]
	v_mfma_f32_16x16x32_bf16 v[16:19], v[180:183], v[208:211], v[16:19]
	v_mfma_f32_16x16x32_bf16 v[16:19], v[176:179], v[200:203], v[16:19]
	v_mfma_f32_16x16x32_bf16 v[0:3], v[176:179], v[212:215], v[0:3]
	v_mfma_f32_16x16x32_bf16 v[0:3], v[180:183], v[216:219], v[0:3]
	v_mfma_f32_16x16x32_bf16 v[8:11], v[172:175], v[216:219], v[8:11]
	v_mfma_f32_16x16x32_bf16 v[8:11], v[168:171], v[212:215], v[8:11]
	v_mfma_f32_16x16x32_bf16 v[4:7], v[160:163], v[212:215], v[4:7]
	v_mfma_f32_16x16x32_bf16 v[4:7], v[164:167], v[216:219], v[4:7]
	v_mfma_f32_16x16x32_bf16 v[12:15], v[156:159], v[216:219], v[12:15]
	v_mfma_f32_16x16x32_bf16 v[12:15], v[152:155], v[212:215], v[12:15]
	s_setprio 0
	s_barrier
	s_add_i32 s65, 0, 0x18000
	v_add_u32_e32 v151, s65, v146
	s_add_i32 s66, 0, 0x1c000
	ds_read_b128 v[152:155], v151
	ds_read_b128 v[156:159], v151 offset:1024
	ds_read_b128 v[160:163], v151 offset:2048
	ds_read_b128 v[164:167], v151 offset:3072
	v_add_u32_e32 v151, s66, v146
	ds_read_b128 v[168:171], v151
	ds_read_b128 v[172:175], v151 offset:1024
	ds_read_b128 v[176:179], v151 offset:2048
	ds_read_b128 v[180:183], v151 offset:3072
	s_add_u32 s30, s30, 0x80000
	s_addc_u32 s31, s31, 0
	s_mov_b32 m0, s46
	v_lshl_add_u64 v[230:231], s[30:31], 0, v[134:135]
	ds_read_b128 v[184:187], v150 offset:32768
	ds_read_b128 v[188:191], v150 offset:33792
	ds_read_b128 v[192:195], v150 offset:34816
	ds_read_b128 v[196:199], v150 offset:35840
	ds_read_b128 v[200:203], v150 offset:36864
	ds_read_b128 v[208:211], v150 offset:37888
	ds_read_b128 v[212:215], v150 offset:38912
	ds_read_b128 v[216:219], v150 offset:39936
	global_load_lds_dwordx4 v[230:231], off
	v_lshl_add_u64 v[230:231], s[30:31], 0, v[130:131]
	s_mov_b32 m0, s47
	s_nop 0
	global_load_lds_dwordx4 v[230:231], off
	s_waitcnt vmcnt(8)
	s_waitcnt lgkmcnt(0)
	s_setprio 1
	s_barrier
	s_waitcnt lgkmcnt(0)
	v_mfma_f32_16x16x32_bf16 v[120:123], v[152:155], v[184:187], v[120:123]
	v_mfma_f32_16x16x32_bf16 v[120:123], v[156:159], v[188:191], v[120:123]
	v_mfma_f32_16x16x32_bf16 v[116:119], v[164:167], v[188:191], v[116:119]
	v_mfma_f32_16x16x32_bf16 v[116:119], v[160:163], v[184:187], v[116:119]
	v_mfma_f32_16x16x32_bf16 v[124:127], v[168:171], v[184:187], v[124:127]
	v_mfma_f32_16x16x32_bf16 v[124:127], v[172:175], v[188:191], v[124:127]
	v_mfma_f32_16x16x32_bf16 v[112:115], v[180:183], v[188:191], v[112:115]
	v_mfma_f32_16x16x32_bf16 v[112:115], v[176:179], v[184:187], v[112:115]
	v_mfma_f32_16x16x32_bf16 v[96:99], v[176:179], v[192:195], v[96:99]
	v_mfma_f32_16x16x32_bf16 v[96:99], v[180:183], v[196:199], v[96:99]
	v_mfma_f32_16x16x32_bf16 v[104:107], v[172:175], v[196:199], v[104:107]
	v_mfma_f32_16x16x32_bf16 v[104:107], v[168:171], v[192:195], v[104:107]
	v_mfma_f32_16x16x32_bf16 v[100:103], v[160:163], v[192:195], v[100:103]
	v_mfma_f32_16x16x32_bf16 v[100:103], v[164:167], v[196:199], v[100:103]
	v_mfma_f32_16x16x32_bf16 v[108:111], v[156:159], v[196:199], v[108:111]
	v_mfma_f32_16x16x32_bf16 v[108:111], v[152:155], v[192:195], v[108:111]
	s_setprio 0
	s_setprio 1
	v_mfma_f32_16x16x32_bf16 v[92:95], v[152:155], v[200:203], v[92:95]
	v_mfma_f32_16x16x32_bf16 v[92:95], v[156:159], v[208:211], v[92:95]
	v_mfma_f32_16x16x32_bf16 v[84:87], v[164:167], v[208:211], v[84:87]
	v_mfma_f32_16x16x32_bf16 v[84:87], v[160:163], v[200:203], v[84:87]
	v_mfma_f32_16x16x32_bf16 v[88:91], v[168:171], v[200:203], v[88:91]
	v_mfma_f32_16x16x32_bf16 v[88:91], v[172:175], v[208:211], v[88:91]
	v_mfma_f32_16x16x32_bf16 v[80:83], v[180:183], v[208:211], v[80:83]
	v_mfma_f32_16x16x32_bf16 v[80:83], v[176:179], v[200:203], v[80:83]
	v_mfma_f32_16x16x32_bf16 v[64:67], v[176:179], v[212:215], v[64:67]
	v_mfma_f32_16x16x32_bf16 v[64:67], v[180:183], v[216:219], v[64:67]
	v_mfma_f32_16x16x32_bf16 v[72:75], v[172:175], v[216:219], v[72:75]
	v_mfma_f32_16x16x32_bf16 v[72:75], v[168:171], v[212:215], v[72:75]
	v_mfma_f32_16x16x32_bf16 v[68:71], v[160:163], v[212:215], v[68:71]
	v_mfma_f32_16x16x32_bf16 v[68:71], v[164:167], v[216:219], v[68:71]
	v_mfma_f32_16x16x32_bf16 v[76:79], v[156:159], v[216:219], v[76:79]
	v_mfma_f32_16x16x32_bf16 v[76:79], v[152:155], v[212:215], v[76:79]
	s_setprio 0
	s_barrier
; #define PG8_STAGE(bufoff, gbase, voff) do { _Pragma("unroll") for (int _i = 0; _i < 2; ++_i) \
;         __builtin_amdgcn_global_load_lds((const unsigned*)((const char*)(gbase) + (voff)[_i]), (LAS unsigned*)(lds + (bufoff) + ldsw + _i * 8192), 16, 0, 0); } while (0)
; #define PG8_LDA(dst, b, h) do { _Pragma("unroll") for (int m = 0; m < 4; ++m) _Pragma("unroll") for (int k = 0; k < 2; ++k) dst[m][k] = *(const LAS bf16x8*)(lds + PG8_SA(b, h) + aoff + m * 2048 + k * 1024); } while (0)
; #define PG8_MMA(ai, bj, At, Bt) do { __builtin_amdgcn_s_setprio(1); _Pragma("unroll") for (int m = 0; m < 4; ++m) _Pragma("unroll") for (int n = 0; n < 2; ++n) _Pragma("unroll") for (int k = 0; k < 2; ++k) \
;         acc[ai][bj][m][n] = __builtin_amdgcn_mfma_f32_16x16x32_bf16(Bt[n][k], At[m][k], acc[ai][bj][m][n], 0, 0, 0); __builtin_amdgcn_s_setprio(0); } while (0)
; #define PG8_WAIT_V(n) asm volatile("s_waitcnt vmcnt(" #n ")" ::: "memory")
; #define PG8_WAIT_L(n) asm volatile("s_waitcnt lgkmcnt(" #n ")" ::: "memory")
; #define PG8_BAR __builtin_amdgcn_s_barrier()
; #define PG8_SCHED __builtin_amdgcn_sched_barrier(0)
; template <class Epi>
; __device__ __forceinline__ void gemm_phase(LAS unsigned char* lds, const Gemm g, const StaticOrder& S, const Epi& E) {
;     ...
;             PG8_LDA(At, 1, 1); PG8_STAGE(PG8_SB(1, 0), b3, voffB); PG8_STAGE(PG8_SB(1, 1), b3 + hstepB, voffB); PG8_STAGE(PG8_SA(1, 0), a3, voffA);
;             PG8_WAIT_V(8); PG8_WAIT_L(0); PG8_BAR; PG8_MMA(1, 0, At, B0); PG8_MMA(1, 1, At, B1); PG8_BAR; PG8_SCHED;
;         }
	s_add_i32 s30, s65, s33
	v_lshl_add_u64 v[220:221], v[220:221], 0, s[8:9]
	s_mov_b32 m0, s30
	ds_read_b128 v[184:187], v150 offset:49152
	ds_read_b128 v[188:191], v150 offset:50176
	ds_read_b128 v[192:195], v150 offset:51200
	ds_read_b128 v[196:199], v150 offset:52224
	ds_read_b128 v[200:203], v150 offset:53248
	ds_read_b128 v[208:211], v150 offset:54272
	ds_read_b128 v[212:215], v150 offset:55296
	ds_read_b128 v[216:219], v150 offset:56320
	global_load_lds_dwordx4 v[220:221], off
	s_add_i32 m0, s30, 0x2000
	s_add_u32 s26, s26, 0x80080
	v_lshl_add_u64 v[220:221], v[222:223], 0, s[8:9]
	s_addc_u32 s27, s27, 0
	s_add_i32 s30, s66, s33
	global_load_lds_dwordx4 v[220:221], off
	v_lshl_add_u64 v[220:221], s[26:27], 0, v[132:133]
	s_mov_b32 m0, s30
	s_nop 0
	global_load_lds_dwordx4 v[220:221], off
	v_lshl_add_u64 v[220:221], s[26:27], 0, v[128:129]
	s_add_i32 m0, s30, 0x2000
	s_nop 0
	global_load_lds_dwordx4 v[220:221], off
	v_lshl_add_u64 v[220:221], v[224:225], 0, s[8:9]
	s_mov_b32 m0, s52
	s_nop 0
	global_load_lds_dwordx4 v[220:221], off
	v_lshl_add_u64 v[220:221], v[226:227], 0, s[8:9]
	s_mov_b32 m0, s53
	s_nop 0
	global_load_lds_dwordx4 v[220:221], off
	s_waitcnt vmcnt(8)
	s_waitcnt lgkmcnt(0)
	s_setprio 1
	s_barrier
	s_waitcnt lgkmcnt(0)
	v_mfma_f32_16x16x32_bf16 v[60:63], v[152:155], v[184:187], v[60:63]
	v_mfma_f32_16x16x32_bf16 v[60:63], v[156:159], v[188:191], v[60:63]
	v_mfma_f32_16x16x32_bf16 v[52:55], v[164:167], v[188:191], v[52:55]
	v_mfma_f32_16x16x32_bf16 v[52:55], v[160:163], v[184:187], v[52:55]
	v_mfma_f32_16x16x32_bf16 v[56:59], v[168:171], v[184:187], v[56:59]
	v_mfma_f32_16x16x32_bf16 v[56:59], v[172:175], v[188:191], v[56:59]
	v_mfma_f32_16x16x32_bf16 v[48:51], v[180:183], v[188:191], v[48:51]
	v_mfma_f32_16x16x32_bf16 v[48:51], v[176:179], v[184:187], v[48:51]
	v_mfma_f32_16x16x32_bf16 v[32:35], v[176:179], v[192:195], v[32:35]
	v_mfma_f32_16x16x32_bf16 v[32:35], v[180:183], v[196:199], v[32:35]
	v_mfma_f32_16x16x32_bf16 v[40:43], v[172:175], v[196:199], v[40:43]
	v_mfma_f32_16x16x32_bf16 v[40:43], v[168:171], v[192:195], v[40:43]
	v_mfma_f32_16x16x32_bf16 v[36:39], v[160:163], v[192:195], v[36:39]
	v_mfma_f32_16x16x32_bf16 v[36:39], v[164:167], v[196:199], v[36:39]
	v_mfma_f32_16x16x32_bf16 v[44:47], v[156:159], v[196:199], v[44:47]
	v_mfma_f32_16x16x32_bf16 v[44:47], v[152:155], v[192:195], v[44:47]
	s_setprio 0
	s_setprio 1
	v_mfma_f32_16x16x32_bf16 v[28:31], v[152:155], v[200:203], v[28:31]
	v_mfma_f32_16x16x32_bf16 v[28:31], v[156:159], v[208:211], v[28:31]
	v_mfma_f32_16x16x32_bf16 v[20:23], v[164:167], v[208:211], v[20:23]
	v_mfma_f32_16x16x32_bf16 v[20:23], v[160:163], v[200:203], v[20:23]
	v_mfma_f32_16x16x32_bf16 v[24:27], v[168:171], v[200:203], v[24:27]
	v_mfma_f32_16x16x32_bf16 v[24:27], v[172:175], v[208:211], v[24:27]
	v_mfma_f32_16x16x32_bf16 v[16:19], v[180:183], v[208:211], v[16:19]
	v_mfma_f32_16x16x32_bf16 v[16:19], v[176:179], v[200:203], v[16:19]
	v_mfma_f32_16x16x32_bf16 v[0:3], v[176:179], v[212:215], v[0:3]
	v_mfma_f32_16x16x32_bf16 v[0:3], v[180:183], v[216:219], v[0:3]
	v_mfma_f32_16x16x32_bf16 v[8:11], v[172:175], v[216:219], v[8:11]
	v_mfma_f32_16x16x32_bf16 v[8:11], v[168:171], v[212:215], v[8:11]
	v_mfma_f32_16x16x32_bf16 v[4:7], v[160:163], v[212:215], v[4:7]
	v_mfma_f32_16x16x32_bf16 v[4:7], v[164:167], v[216:219], v[4:7]
	v_mfma_f32_16x16x32_bf16 v[12:15], v[156:159], v[216:219], v[12:15]
	v_mfma_f32_16x16x32_bf16 v[12:15], v[152:155], v[212:215], v[12:15]
	s_setprio 0
	s_barrier
	s_add_u32 s24, s24, 0x100
	s_addc_u32 s25, s25, 0
	s_add_u32 s62, s62, 0x100
	s_addc_u32 s63, s63, 0
	s_cmp_ge_i32 s64, s49
	s_mov_b32 s26, s64
	s_cbranch_scc0 .LBB0_245

; #define PG8_STAGE(bufoff, gbase, voff) do { _Pragma("unroll") for (int _i = 0; _i < 2; ++_i) \
;         __builtin_amdgcn_global_load_lds((const unsigned*)((const char*)(gbase) + (voff)[_i]), (LAS unsigned*)(lds + (bufoff) + ldsw + _i * 8192), 16, 0, 0); } while (0)
; #define PG8_LDA(dst, b, h) do { _Pragma("unroll") for (int m = 0; m < 4; ++m) _Pragma("unroll") for (int k = 0; k < 2; ++k) dst[m][k] = *(const LAS bf16x8*)(lds + PG8_SA(b, h) + aoff + m * 2048 + k * 1024); } while (0)
; #define PG8_LDB(dst, b, h) do { _Pragma("unroll") for (int n = 0; n < 2; ++n) _Pragma("unroll") for (int k = 0; k < 2; ++k) dst[n][k] = *(const LAS bf16x8*)(lds + PG8_SB(b, h) + boff + n * 2048 + k * 1024); } while (0)
; #define PG8_MMA(ai, bj, At, Bt) do { __builtin_amdgcn_s_setprio(1); _Pragma("unroll") for (int m = 0; m < 4; ++m) _Pragma("unroll") for (int n = 0; n < 2; ++n) _Pragma("unroll") for (int k = 0; k < 2; ++k) \
;         acc[ai][bj][m][n] = __builtin_amdgcn_mfma_f32_16x16x32_bf16(Bt[n][k], At[m][k], acc[ai][bj][m][n], 0, 0, 0); __builtin_amdgcn_s_setprio(0); } while (0)
; #define PG8_WAIT_V(n) asm volatile("s_waitcnt vmcnt(" #n ")" ::: "memory")
; #define PG8_WAIT_L(n) asm volatile("s_waitcnt lgkmcnt(" #n ")" ::: "memory")
; #define PG8_BAR __builtin_amdgcn_s_barrier()
; #define PG8_SCHED __builtin_amdgcn_sched_barrier(0)
; template <class Epi>
; __device__ __forceinline__ void gemm_phase(LAS unsigned char* lds, const Gemm g, const StaticOrder& S, const Epi& E) {
;     ...
;             const bool last = (t == nt - 2);
;             const char* a1 = cA + (size_t)(t + 1) * kstep;
;             const char* a2 = last ? nA : cA + (size_t)(t + 2) * kstep; const char* b2 = last ? nB : cB + (size_t)(t + 2) * kstep;
;             const char* a3 = a2 + kstep; const char* b3 = b2 + kstep;
;             PG8_LDB(B0, 0, 0); PG8_LDB(B1, 0, 1); PG8_SCHED; PG8_LDA(At, 0, 0); PG8_STAGE(PG8_SA(1, 1), a1 + hstepA, voffA);
;             PG8_WAIT_V(8); PG8_WAIT_L(0); PG8_BAR; PG8_MMA(0, 0, At, B0); PG8_MMA(0, 1, At, B1); PG8_BAR; PG8_SCHED;
;             PG8_LDA(At, 0, 1); PG8_STAGE(PG8_SB(0, 0), b2, voffB); PG8_STAGE(PG8_SB(0, 1), b2 + hstepB, voffB); PG8_STAGE(PG8_SA(0, 0), a2, voffA);
;             PG8_WAIT_V(8); PG8_WAIT_L(0); PG8_BAR; PG8_MMA(1, 0, At, B0); PG8_MMA(1, 1, At, B1); PG8_BAR; PG8_SCHED;
.LBB0_445:
	ds_read_b128 v[148:151], v218
	ds_read_b128 v[152:155], v218 offset:1024
	ds_read_b128 v[156:159], v218 offset:2048
	ds_read_b128 v[160:163], v218 offset:3072
	ds_read_b128 v[164:167], v219
	ds_read_b128 v[168:171], v219 offset:1024
	ds_read_b128 v[172:175], v219 offset:2048
	ds_read_b128 v[176:179], v219 offset:3072
	s_add_i32 s65, s34, 2
	s_add_u32 s30, s4, 0x100
	s_addc_u32 s31, s5, 0
	s_cmp_eq_u32 s49, s34
	s_cselect_b32 s34, s26, s1
	s_cselect_b32 s37, s11, s31
	s_cselect_b32 s36, s10, s30
	s_cselect_b32 s35, s27, s64
	v_lshl_add_u64 v[216:217], s[4:5], 0, v[140:141]
	s_add_i32 m0, s41, 0xc000
	ds_read_b128 v[180:183], v220
	ds_read_b128 v[184:187], v220 offset:1024
	ds_read_b128 v[188:191], v220 offset:2048
	ds_read_b128 v[192:195], v220 offset:3072
	ds_read_b128 v[196:199], v220 offset:4096
	ds_read_b128 v[200:203], v220 offset:5120
	ds_read_b128 v[208:211], v220 offset:6144
	ds_read_b128 v[212:215], v220 offset:7168
	global_load_lds_dwordx4 v[216:217], off
	v_lshl_add_u64 v[216:217], s[4:5], 0, v[142:143]
	s_add_i32 m0, s41, 0xe000
	s_nop 0
	global_load_lds_dwordx4 v[216:217], off
	s_waitcnt vmcnt(8)
	s_waitcnt lgkmcnt(0)
	s_setprio 1
	s_barrier
	s_waitcnt lgkmcnt(0)
	v_mfma_f32_16x16x32_bf16 v[124:127], v[148:151], v[180:183], v[124:127]
	v_mfma_f32_16x16x32_bf16 v[124:127], v[152:155], v[184:187], v[124:127]
	v_mfma_f32_16x16x32_bf16 v[120:123], v[160:163], v[184:187], v[120:123]
	v_mfma_f32_16x16x32_bf16 v[120:123], v[156:159], v[180:183], v[120:123]
	v_mfma_f32_16x16x32_bf16 v[108:111], v[164:167], v[180:183], v[108:111]
	v_mfma_f32_16x16x32_bf16 v[108:111], v[168:171], v[184:187], v[108:111]
	v_mfma_f32_16x16x32_bf16 v[100:103], v[176:179], v[184:187], v[100:103]
	v_mfma_f32_16x16x32_bf16 v[100:103], v[172:175], v[180:183], v[100:103]
	v_mfma_f32_16x16x32_bf16 v[84:87], v[172:175], v[188:191], v[84:87]
	v_mfma_f32_16x16x32_bf16 v[84:87], v[176:179], v[192:195], v[84:87]
	v_mfma_f32_16x16x32_bf16 v[92:95], v[168:171], v[192:195], v[92:95]
	v_mfma_f32_16x16x32_bf16 v[92:95], v[164:167], v[188:191], v[92:95]
	v_mfma_f32_16x16x32_bf16 v[112:115], v[156:159], v[188:191], v[112:115]
	v_mfma_f32_16x16x32_bf16 v[112:115], v[160:163], v[192:195], v[112:115]
	v_mfma_f32_16x16x32_bf16 v[116:119], v[152:155], v[192:195], v[116:119]
	v_mfma_f32_16x16x32_bf16 v[116:119], v[148:151], v[188:191], v[116:119]
	s_setprio 0
	s_setprio 1
	v_mfma_f32_16x16x32_bf16 v[104:107], v[148:151], v[196:199], v[104:107]
	v_mfma_f32_16x16x32_bf16 v[104:107], v[152:155], v[200:203], v[104:107]
	v_mfma_f32_16x16x32_bf16 v[96:99], v[160:163], v[200:203], v[96:99]
	v_mfma_f32_16x16x32_bf16 v[96:99], v[156:159], v[196:199], v[96:99]
	v_mfma_f32_16x16x32_bf16 v[76:79], v[164:167], v[196:199], v[76:79]
	v_mfma_f32_16x16x32_bf16 v[76:79], v[168:171], v[200:203], v[76:79]
	v_mfma_f32_16x16x32_bf16 v[72:75], v[176:179], v[200:203], v[72:75]
	v_mfma_f32_16x16x32_bf16 v[72:75], v[172:175], v[196:199], v[72:75]
	v_mfma_f32_16x16x32_bf16 v[64:67], v[172:175], v[208:211], v[64:67]
	v_mfma_f32_16x16x32_bf16 v[64:67], v[176:179], v[212:215], v[64:67]
	v_mfma_f32_16x16x32_bf16 v[68:71], v[168:171], v[212:215], v[68:71]
	v_mfma_f32_16x16x32_bf16 v[68:71], v[164:167], v[208:211], v[68:71]
	v_mfma_f32_16x16x32_bf16 v[80:83], v[156:159], v[208:211], v[80:83]
	v_mfma_f32_16x16x32_bf16 v[80:83], v[160:163], v[212:215], v[80:83]
	v_mfma_f32_16x16x32_bf16 v[88:91], v[152:155], v[212:215], v[88:91]
	v_mfma_f32_16x16x32_bf16 v[88:91], v[148:151], v[208:211], v[88:91]
	s_setprio 0
	s_barrier
	s_add_i32 s4, s54, s40
	v_lshl_add_u64 v[216:217], s[34:35], 0, v[130:131]
	s_mov_b32 m0, s4
	ds_read_b128 v[180:183], v220 offset:16384
	ds_read_b128 v[184:187], v220 offset:17408
	ds_read_b128 v[188:191], v220 offset:18432
	ds_read_b128 v[192:195], v220 offset:19456
	ds_read_b128 v[196:199], v220 offset:20480
	ds_read_b128 v[200:203], v220 offset:21504
	ds_read_b128 v[208:211], v220 offset:22528
	ds_read_b128 v[212:215], v220 offset:23552
	global_load_lds_dwordx4 v[216:217], off
	s_add_i32 m0, s4, 0x2000
	s_add_u32 s4, s34, 0x158000
	v_lshl_add_u64 v[222:223], s[34:35], 0, v[134:135]
	s_addc_u32 s5, s35, 0
	s_add_i32 s66, s55, s40
	global_load_lds_dwordx4 v[222:223], off
	v_lshl_add_u64 v[224:225], s[4:5], 0, v[130:131]
	s_mov_b32 m0, s66
	v_lshl_add_u64 v[226:227], s[36:37], 0, v[132:133]
	global_load_lds_dwordx4 v[224:225], off
	v_lshl_add_u64 v[224:225], s[4:5], 0, v[134:135]
	s_add_i32 m0, s66, 0x2000
	s_nop 0
	global_load_lds_dwordx4 v[224:225], off
	v_lshl_add_u64 v[224:225], s[36:37], 0, v[128:129]
	s_mov_b32 m0, s41
	s_nop 0
	global_load_lds_dwordx4 v[224:225], off
	s_mov_b32 m0, s42
	s_nop 0
	global_load_lds_dwordx4 v[226:227], off
	s_waitcnt vmcnt(8)
	s_waitcnt lgkmcnt(0)
	s_setprio 1
	s_barrier
; #define PG8_STAGE(bufoff, gbase, voff) do { _Pragma("unroll") for (int _i = 0; _i < 2; ++_i) \
;         __builtin_amdgcn_global_load_lds((const unsigned*)((const char*)(gbase) + (voff)[_i]), (LAS unsigned*)(lds + (bufoff) + ldsw + _i * 8192), 16, 0, 0); } while (0)
; #define PG8_LDA(dst, b, h) do { _Pragma("unroll") for (int m = 0; m < 4; ++m) _Pragma("unroll") for (int k = 0; k < 2; ++k) dst[m][k] = *(const LAS bf16x8*)(lds + PG8_SA(b, h) + aoff + m * 2048 + k * 1024); } while (0)
; #define PG8_LDB(dst, b, h) do { _Pragma("unroll") for (int n = 0; n < 2; ++n) _Pragma("unroll") for (int k = 0; k < 2; ++k) dst[n][k] = *(const LAS bf16x8*)(lds + PG8_SB(b, h) + boff + n * 2048 + k * 1024); } while (0)
; #define PG8_MMA(ai, bj, At, Bt) do { __builtin_amdgcn_s_setprio(1); _Pragma("unroll") for (int m = 0; m < 4; ++m) _Pragma("unroll") for (int n = 0; n < 2; ++n) _Pragma("unroll") for (int k = 0; k < 2; ++k) \
;         acc[ai][bj][m][n] = __builtin_amdgcn_mfma_f32_16x16x32_bf16(Bt[n][k], At[m][k], acc[ai][bj][m][n], 0, 0, 0); __builtin_amdgcn_s_setprio(0); } while (0)
; #define PG8_WAIT_V(n) asm volatile("s_waitcnt vmcnt(" #n ")" ::: "memory")
; #define PG8_WAIT_L(n) asm volatile("s_waitcnt lgkmcnt(" #n ")" ::: "memory")
; #define PG8_BAR __builtin_amdgcn_s_barrier()
; #define PG8_SCHED __builtin_amdgcn_sched_barrier(0)
; template <class Epi>
; __device__ __forceinline__ void gemm_phase(LAS unsigned char* lds, const Gemm g, const StaticOrder& S, const Epi& E) {
;     ...
;             PG8_WAIT_V(8); PG8_WAIT_L(0); PG8_BAR; PG8_MMA(1, 0, At, B0); PG8_MMA(1, 1, At, B1); PG8_BAR; PG8_SCHED;
;             PG8_LDB(B0, 1, 0); PG8_LDB(B1, 1, 1); PG8_SCHED; PG8_LDA(At, 1, 0); PG8_STAGE(PG8_SA(0, 1), a2 + hstepA, voffA);
;             PG8_WAIT_V(8); PG8_WAIT_L(0); PG8_BAR; PG8_MMA(0, 0, At, B0); PG8_MMA(0, 1, At, B1); PG8_BAR; PG8_SCHED;
	s_waitcnt lgkmcnt(0)
	v_mfma_f32_16x16x32_bf16 v[60:63], v[148:151], v[180:183], v[60:63]
	v_mfma_f32_16x16x32_bf16 v[60:63], v[152:155], v[184:187], v[60:63]
	v_mfma_f32_16x16x32_bf16 v[56:59], v[160:163], v[184:187], v[56:59]
	v_mfma_f32_16x16x32_bf16 v[56:59], v[156:159], v[180:183], v[56:59]
	v_mfma_f32_16x16x32_bf16 v[44:47], v[164:167], v[180:183], v[44:47]
	v_mfma_f32_16x16x32_bf16 v[44:47], v[168:171], v[184:187], v[44:47]
	v_mfma_f32_16x16x32_bf16 v[36:39], v[176:179], v[184:187], v[36:39]
	v_mfma_f32_16x16x32_bf16 v[36:39], v[172:175], v[180:183], v[36:39]
	v_mfma_f32_16x16x32_bf16 v[20:23], v[172:175], v[188:191], v[20:23]
	v_mfma_f32_16x16x32_bf16 v[20:23], v[176:179], v[192:195], v[20:23]
	v_mfma_f32_16x16x32_bf16 v[28:31], v[168:171], v[192:195], v[28:31]
	v_mfma_f32_16x16x32_bf16 v[28:31], v[164:167], v[188:191], v[28:31]
	v_mfma_f32_16x16x32_bf16 v[48:51], v[156:159], v[188:191], v[48:51]
	v_mfma_f32_16x16x32_bf16 v[48:51], v[160:163], v[192:195], v[48:51]
	v_mfma_f32_16x16x32_bf16 v[52:55], v[152:155], v[192:195], v[52:55]
	v_mfma_f32_16x16x32_bf16 v[52:55], v[148:151], v[188:191], v[52:55]
	s_setprio 0
	s_setprio 1
	v_mfma_f32_16x16x32_bf16 v[40:43], v[148:151], v[196:199], v[40:43]
	v_mfma_f32_16x16x32_bf16 v[40:43], v[152:155], v[200:203], v[40:43]
	v_mfma_f32_16x16x32_bf16 v[32:35], v[160:163], v[200:203], v[32:35]
	v_mfma_f32_16x16x32_bf16 v[32:35], v[156:159], v[196:199], v[32:35]
	v_mfma_f32_16x16x32_bf16 v[12:15], v[164:167], v[196:199], v[12:15]
	v_mfma_f32_16x16x32_bf16 v[12:15], v[168:171], v[200:203], v[12:15]
	v_mfma_f32_16x16x32_bf16 v[8:11], v[176:179], v[200:203], v[8:11]
	v_mfma_f32_16x16x32_bf16 v[8:11], v[172:175], v[196:199], v[8:11]
	v_mfma_f32_16x16x32_bf16 v[0:3], v[172:175], v[208:211], v[0:3]
	v_mfma_f32_16x16x32_bf16 v[0:3], v[176:179], v[212:215], v[0:3]
	v_mfma_f32_16x16x32_bf16 v[4:7], v[168:171], v[212:215], v[4:7]
	v_mfma_f32_16x16x32_bf16 v[4:7], v[164:167], v[208:211], v[4:7]
	v_mfma_f32_16x16x32_bf16 v[16:19], v[156:159], v[208:211], v[16:19]
	v_mfma_f32_16x16x32_bf16 v[16:19], v[160:163], v[212:215], v[16:19]
	v_mfma_f32_16x16x32_bf16 v[24:27], v[152:155], v[212:215], v[24:27]
	v_mfma_f32_16x16x32_bf16 v[24:27], v[148:151], v[208:211], v[24:27]
	s_setprio 0
	s_barrier
	s_add_i32 s66, 0, 0x18000
	s_add_i32 s67, 0, 0x1c000
	v_add_u32_e32 v160, s66, v207
	v_add_u32_e32 v176, s67, v207
	ds_read_b128 v[148:151], v160
	ds_read_b128 v[152:155], v160 offset:1024
	ds_read_b128 v[156:159], v160 offset:2048
	ds_read_b128 v[160:163], v160 offset:3072
	ds_read_b128 v[164:167], v176
	ds_read_b128 v[168:171], v176 offset:1024
	ds_read_b128 v[172:175], v176 offset:2048
	ds_read_b128 v[176:179], v176 offset:3072
	s_add_u32 s4, s36, 0x158000
	s_addc_u32 s5, s37, 0
	s_mov_b32 m0, s43
	v_lshl_add_u64 v[230:231], s[4:5], 0, v[128:129]
	ds_read_b128 v[180:183], v220 offset:32768
	ds_read_b128 v[184:187], v220 offset:33792
	ds_read_b128 v[188:191], v220 offset:34816
	ds_read_b128 v[192:195], v220 offset:35840
	ds_read_b128 v[196:199], v220 offset:36864
	ds_read_b128 v[200:203], v220 offset:37888
	ds_read_b128 v[208:211], v220 offset:38912
	ds_read_b128 v[212:215], v220 offset:39936
	global_load_lds_dwordx4 v[230:231], off
	v_lshl_add_u64 v[230:231], s[4:5], 0, v[132:133]
	s_mov_b32 m0, s44
	s_nop 0
	global_load_lds_dwordx4 v[230:231], off
	s_waitcnt vmcnt(8)
	s_waitcnt lgkmcnt(0)
	s_setprio 1
	s_barrier
	s_waitcnt lgkmcnt(0)
	v_mfma_f32_16x16x32_bf16 v[124:127], v[148:151], v[180:183], v[124:127]
	v_mfma_f32_16x16x32_bf16 v[124:127], v[152:155], v[184:187], v[124:127]
	v_mfma_f32_16x16x32_bf16 v[120:123], v[160:163], v[184:187], v[120:123]
	v_mfma_f32_16x16x32_bf16 v[120:123], v[156:159], v[180:183], v[120:123]
	v_mfma_f32_16x16x32_bf16 v[108:111], v[164:167], v[180:183], v[108:111]
	v_mfma_f32_16x16x32_bf16 v[108:111], v[168:171], v[184:187], v[108:111]
	v_mfma_f32_16x16x32_bf16 v[100:103], v[176:179], v[184:187], v[100:103]
	v_mfma_f32_16x16x32_bf16 v[100:103], v[172:175], v[180:183], v[100:103]
	v_mfma_f32_16x16x32_bf16 v[84:87], v[172:175], v[188:191], v[84:87]
	v_mfma_f32_16x16x32_bf16 v[84:87], v[176:179], v[192:195], v[84:87]
	v_mfma_f32_16x16x32_bf16 v[92:95], v[168:171], v[192:195], v[92:95]
	v_mfma_f32_16x16x32_bf16 v[92:95], v[164:167], v[188:191], v[92:95]
	v_mfma_f32_16x16x32_bf16 v[112:115], v[156:159], v[188:191], v[112:115]
	v_mfma_f32_16x16x32_bf16 v[112:115], v[160:163], v[192:195], v[112:115]
	v_mfma_f32_16x16x32_bf16 v[116:119], v[152:155], v[192:195], v[116:119]
	v_mfma_f32_16x16x32_bf16 v[116:119], v[148:151], v[188:191], v[116:119]
	s_setprio 0
	s_setprio 1
	v_mfma_f32_16x16x32_bf16 v[104:107], v[148:151], v[196:199], v[104:107]
	v_mfma_f32_16x16x32_bf16 v[104:107], v[152:155], v[200:203], v[104:107]
	v_mfma_f32_16x16x32_bf16 v[96:99], v[160:163], v[200:203], v[96:99]
	v_mfma_f32_16x16x32_bf16 v[96:99], v[156:159], v[196:199], v[96:99]
	v_mfma_f32_16x16x32_bf16 v[76:79], v[164:167], v[196:199], v[76:79]
	v_mfma_f32_16x16x32_bf16 v[76:79], v[168:171], v[200:203], v[76:79]
	v_mfma_f32_16x16x32_bf16 v[72:75], v[176:179], v[200:203], v[72:75]
	v_mfma_f32_16x16x32_bf16 v[72:75], v[172:175], v[196:199], v[72:75]
	v_mfma_f32_16x16x32_bf16 v[64:67], v[172:175], v[208:211], v[64:67]
	v_mfma_f32_16x16x32_bf16 v[64:67], v[176:179], v[212:215], v[64:67]
	v_mfma_f32_16x16x32_bf16 v[68:71], v[168:171], v[212:215], v[68:71]
	v_mfma_f32_16x16x32_bf16 v[68:71], v[164:167], v[208:211], v[68:71]
	v_mfma_f32_16x16x32_bf16 v[80:83], v[156:159], v[208:211], v[80:83]
	v_mfma_f32_16x16x32_bf16 v[80:83], v[160:163], v[212:215], v[80:83]
	v_mfma_f32_16x16x32_bf16 v[88:91], v[152:155], v[212:215], v[88:91]
	v_mfma_f32_16x16x32_bf16 v[88:91], v[148:151], v[208:211], v[88:91]
	s_setprio 0
	s_barrier
; #define PG8_STAGE(bufoff, gbase, voff) do { _Pragma("unroll") for (int _i = 0; _i < 2; ++_i) \
;         __builtin_amdgcn_global_load_lds((const unsigned*)((const char*)(gbase) + (voff)[_i]), (LAS unsigned*)(lds + (bufoff) + ldsw + _i * 8192), 16, 0, 0); } while (0)
; #define PG8_LDA(dst, b, h) do { _Pragma("unroll") for (int m = 0; m < 4; ++m) _Pragma("unroll") for (int k = 0; k < 2; ++k) dst[m][k] = *(const LAS bf16x8*)(lds + PG8_SA(b, h) + aoff + m * 2048 + k * 1024); } while (0)
; #define PG8_MMA(ai, bj, At, Bt) do { __builtin_amdgcn_s_setprio(1); _Pragma("unroll") for (int m = 0; m < 4; ++m) _Pragma("unroll") for (int n = 0; n < 2; ++n) _Pragma("unroll") for (int k = 0; k < 2; ++k) \
;         acc[ai][bj][m][n] = __builtin_amdgcn_mfma_f32_16x16x32_bf16(Bt[n][k], At[m][k], acc[ai][bj][m][n], 0, 0, 0); __builtin_amdgcn_s_setprio(0); } while (0)
; #define PG8_WAIT_V(n) asm volatile("s_waitcnt vmcnt(" #n ")" ::: "memory")
; #define PG8_WAIT_L(n) asm volatile("s_waitcnt lgkmcnt(" #n ")" ::: "memory")
; #define PG8_BAR __builtin_amdgcn_s_barrier()
; #define PG8_SCHED __builtin_amdgcn_sched_barrier(0)
; template <class Epi>
; __device__ __forceinline__ void gemm_phase(LAS unsigned char* lds, const Gemm g, const StaticOrder& S, const Epi& E) {
;     ...
;             PG8_LDA(At, 1, 1); PG8_STAGE(PG8_SB(1, 0), b3, voffB); PG8_STAGE(PG8_SB(1, 1), b3 + hstepB, voffB); PG8_STAGE(PG8_SA(1, 0), a3, voffA);
;             PG8_WAIT_V(8); PG8_WAIT_L(0); PG8_BAR; PG8_MMA(1, 0, At, B0); PG8_MMA(1, 1, At, B1); PG8_BAR; PG8_SCHED;
;         }
	s_add_i32 s4, s66, s40
	v_lshl_add_u64 v[216:217], v[216:217], 0, s[16:17]
	s_mov_b32 m0, s4
	ds_read_b128 v[180:183], v220 offset:49152
	ds_read_b128 v[184:187], v220 offset:50176
	ds_read_b128 v[188:191], v220 offset:51200
	ds_read_b128 v[192:195], v220 offset:52224
	ds_read_b128 v[196:199], v220 offset:53248
	ds_read_b128 v[200:203], v220 offset:54272
	ds_read_b128 v[208:211], v220 offset:55296
	ds_read_b128 v[212:215], v220 offset:56320
	global_load_lds_dwordx4 v[216:217], off
	s_add_i32 m0, s4, 0x2000
	s_add_u32 s4, s34, 0x158080
	v_lshl_add_u64 v[216:217], v[222:223], 0, s[16:17]
	s_addc_u32 s5, s35, 0
	s_add_i32 s34, s67, s40
	global_load_lds_dwordx4 v[216:217], off
	v_lshl_add_u64 v[216:217], s[4:5], 0, v[130:131]
	s_mov_b32 m0, s34
	s_nop 0
	global_load_lds_dwordx4 v[216:217], off
	v_lshl_add_u64 v[216:217], s[4:5], 0, v[134:135]
	s_add_i32 m0, s34, 0x2000
	s_nop 0
	global_load_lds_dwordx4 v[216:217], off
	v_lshl_add_u64 v[216:217], v[224:225], 0, s[16:17]
	s_mov_b32 m0, s47
	s_nop 0
	global_load_lds_dwordx4 v[216:217], off
	v_lshl_add_u64 v[216:217], v[226:227], 0, s[16:17]
	s_mov_b32 m0, s48
	s_nop 0
	global_load_lds_dwordx4 v[216:217], off
	s_waitcnt vmcnt(8)
	s_waitcnt lgkmcnt(0)
	s_setprio 1
	s_barrier
	s_waitcnt lgkmcnt(0)
	v_mfma_f32_16x16x32_bf16 v[60:63], v[148:151], v[180:183], v[60:63]
	v_mfma_f32_16x16x32_bf16 v[60:63], v[152:155], v[184:187], v[60:63]
	v_mfma_f32_16x16x32_bf16 v[56:59], v[160:163], v[184:187], v[56:59]
	v_mfma_f32_16x16x32_bf16 v[56:59], v[156:159], v[180:183], v[56:59]
	v_mfma_f32_16x16x32_bf16 v[44:47], v[164:167], v[180:183], v[44:47]
	v_mfma_f32_16x16x32_bf16 v[44:47], v[168:171], v[184:187], v[44:47]
	v_mfma_f32_16x16x32_bf16 v[36:39], v[176:179], v[184:187], v[36:39]
	v_mfma_f32_16x16x32_bf16 v[36:39], v[172:175], v[180:183], v[36:39]
	v_mfma_f32_16x16x32_bf16 v[20:23], v[172:175], v[188:191], v[20:23]
	v_mfma_f32_16x16x32_bf16 v[20:23], v[176:179], v[192:195], v[20:23]
	v_mfma_f32_16x16x32_bf16 v[28:31], v[168:171], v[192:195], v[28:31]
	v_mfma_f32_16x16x32_bf16 v[28:31], v[164:167], v[188:191], v[28:31]
	v_mfma_f32_16x16x32_bf16 v[48:51], v[156:159], v[188:191], v[48:51]
	v_mfma_f32_16x16x32_bf16 v[48:51], v[160:163], v[192:195], v[48:51]
	v_mfma_f32_16x16x32_bf16 v[52:55], v[152:155], v[192:195], v[52:55]
	v_mfma_f32_16x16x32_bf16 v[52:55], v[148:151], v[188:191], v[52:55]
	s_setprio 0
	s_setprio 1
	v_mfma_f32_16x16x32_bf16 v[40:43], v[148:151], v[196:199], v[40:43]
	v_mfma_f32_16x16x32_bf16 v[40:43], v[152:155], v[200:203], v[40:43]
	v_mfma_f32_16x16x32_bf16 v[32:35], v[160:163], v[200:203], v[32:35]
	v_mfma_f32_16x16x32_bf16 v[32:35], v[156:159], v[196:199], v[32:35]
	v_mfma_f32_16x16x32_bf16 v[12:15], v[164:167], v[196:199], v[12:15]
	v_mfma_f32_16x16x32_bf16 v[12:15], v[168:171], v[200:203], v[12:15]
	v_mfma_f32_16x16x32_bf16 v[8:11], v[176:179], v[200:203], v[8:11]
	v_mfma_f32_16x16x32_bf16 v[8:11], v[172:175], v[196:199], v[8:11]
	v_mfma_f32_16x16x32_bf16 v[0:3], v[172:175], v[208:211], v[0:3]
	v_mfma_f32_16x16x32_bf16 v[0:3], v[176:179], v[212:215], v[0:3]
	v_mfma_f32_16x16x32_bf16 v[4:7], v[168:171], v[212:215], v[4:7]
	v_mfma_f32_16x16x32_bf16 v[4:7], v[164:167], v[208:211], v[4:7]
	v_mfma_f32_16x16x32_bf16 v[16:19], v[156:159], v[208:211], v[16:19]
	v_mfma_f32_16x16x32_bf16 v[16:19], v[160:163], v[212:215], v[16:19]
	v_mfma_f32_16x16x32_bf16 v[24:27], v[152:155], v[212:215], v[24:27]
	v_mfma_f32_16x16x32_bf16 v[24:27], v[148:151], v[208:211], v[24:27]
	s_setprio 0
	s_barrier
	s_add_u32 s1, s1, 0x100
	s_addc_u32 s64, s64, 0
	s_cmp_ge_i32 s65, s46
	s_mov_b64 s[4:5], s[30:31]
	s_mov_b32 s34, s65
	s_cbranch_scc0 .LBB0_445
; #define ER_LOAD(ai, mp) _Pragma("unroll") for (int mm = 0; mm < 2; ++mm) _Pragma("unroll") for (int bj = 0; bj < 2; ++bj) { const size_t o2 = off0 + (size_t)((ai) * HALF + (2 * (mp) + mm) * 16) * DM + bj * HALF; \
;             if constexpr (XBASE) { pa[mm][bj] = *(const u32x4*)(basef + o2); pb[mm][bj] = *(const u32x4*)(basef + o2 + 4); } else { pa[mm][bj] = *(const u32x4*)(H + o2); } }
;     __device__ __forceinline__ void operator()(Acc& acc, const Unit& u, int wr, int wc, int fr, int fq) const {
;     ...
;         ER_LOAD(0, 0) ER_SUM(0, 0) asm volatile("" ::: "memory"); ER_LOAD(0, 1) asm volatile("" ::: "memory"); ER_STORE(0, 0) ER_SUM(0, 1) asm volatile("" ::: "memory");
	v_pk_mul_f32 v[164:165], v[126:127], 0.5 op_sel_hi:[1,0]
	v_pk_mul_f32 v[200:201], v[124:125], 0.5 op_sel_hi:[1,0]
	v_pk_mul_f32 v[202:203], v[122:123], 0.5 op_sel_hi:[1,0]
	v_pk_mul_f32 v[208:209], v[120:121], 0.5 op_sel_hi:[1,0]
	v_pk_mul_f32 v[210:211], v[110:111], 0.5 op_sel_hi:[1,0]
	v_pk_mul_f32 v[212:213], v[108:109], 0.5 op_sel_hi:[1,0]
	v_pk_mul_f32 v[214:215], v[102:103], 0.5 op_sel_hi:[1,0]
	v_pk_mul_f32 v[216:217], v[100:101], 0.5 op_sel_hi:[1,0]
	v_pk_mul_f32 v[188:189], v[118:119], 0.5 op_sel_hi:[1,0]
	v_pk_mul_f32 v[186:187], v[116:117], 0.5 op_sel_hi:[1,0]
	v_pk_mul_f32 v[184:185], v[114:115], 0.5 op_sel_hi:[1,0]
	v_pk_mul_f32 v[182:183], v[112:113], 0.5 op_sel_hi:[1,0]
	v_pk_mul_f32 v[196:197], v[94:95], 0.5 op_sel_hi:[1,0]
	v_pk_mul_f32 v[194:195], v[92:93], 0.5 op_sel_hi:[1,0]
	v_pk_mul_f32 v[192:193], v[86:87], 0.5 op_sel_hi:[1,0]
	v_pk_mul_f32 v[190:191], v[84:85], 0.5 op_sel_hi:[1,0]
	v_pk_mul_f32 v[166:167], v[106:107], 0.5 op_sel_hi:[1,0]
	v_pk_mul_f32 v[168:169], v[104:105], 0.5 op_sel_hi:[1,0]
	v_pk_mul_f32 v[170:171], v[98:99], 0.5 op_sel_hi:[1,0]
	v_pk_mul_f32 v[172:173], v[96:97], 0.5 op_sel_hi:[1,0]
	v_pk_mul_f32 v[174:175], v[78:79], 0.5 op_sel_hi:[1,0]
	v_pk_mul_f32 v[176:177], v[76:77], 0.5 op_sel_hi:[1,0]
	v_pk_mul_f32 v[178:179], v[74:75], 0.5 op_sel_hi:[1,0]
	v_pk_mul_f32 v[180:181], v[72:73], 0.5 op_sel_hi:[1,0]
	v_pk_mul_f32 v[154:155], v[90:91], 0.5 op_sel_hi:[1,0]
	v_pk_mul_f32 v[152:153], v[88:89], 0.5 op_sel_hi:[1,0]
	v_pk_mul_f32 v[150:151], v[82:83], 0.5 op_sel_hi:[1,0]
	v_pk_mul_f32 v[148:149], v[80:81], 0.5 op_sel_hi:[1,0]
	v_pk_mul_f32 v[162:163], v[70:71], 0.5 op_sel_hi:[1,0]
	v_pk_mul_f32 v[160:161], v[68:69], 0.5 op_sel_hi:[1,0]
	v_pk_mul_f32 v[158:159], v[66:67], 0.5 op_sel_hi:[1,0]
	v_pk_mul_f32 v[156:157], v[64:65], 0.5 op_sel_hi:[1,0]
	v_pk_mul_f32 v[112:113], v[62:63], 0.5 op_sel_hi:[1,0]
	v_pk_mul_f32 v[114:115], v[60:61], 0.5 op_sel_hi:[1,0]
	v_pk_mul_f32 v[116:117], v[58:59], 0.5 op_sel_hi:[1,0]
	v_pk_mul_f32 v[118:119], v[56:57], 0.5 op_sel_hi:[1,0]
	v_pk_mul_f32 v[120:121], v[46:47], 0.5 op_sel_hi:[1,0]
	v_pk_mul_f32 v[122:123], v[44:45], 0.5 op_sel_hi:[1,0]
	v_pk_mul_f32 v[124:125], v[38:39], 0.5 op_sel_hi:[1,0]
	v_pk_mul_f32 v[126:127], v[36:37], 0.5 op_sel_hi:[1,0]
	v_pk_mul_f32 v[102:103], v[54:55], 0.5 op_sel_hi:[1,0]
	v_pk_mul_f32 v[100:101], v[52:53], 0.5 op_sel_hi:[1,0]
	v_pk_mul_f32 v[98:99], v[50:51], 0.5 op_sel_hi:[1,0]
	v_pk_mul_f32 v[96:97], v[48:49], 0.5 op_sel_hi:[1,0]
	v_pk_mul_f32 v[110:111], v[30:31], 0.5 op_sel_hi:[1,0]
	v_pk_mul_f32 v[108:109], v[28:29], 0.5 op_sel_hi:[1,0]
	v_pk_mul_f32 v[106:107], v[22:23], 0.5 op_sel_hi:[1,0]
	v_pk_mul_f32 v[104:105], v[20:21], 0.5 op_sel_hi:[1,0]
	v_pk_mul_f32 v[86:87], v[42:43], 0.5 op_sel_hi:[1,0]
	v_pk_mul_f32 v[84:85], v[40:41], 0.5 op_sel_hi:[1,0]
	v_pk_mul_f32 v[82:83], v[34:35], 0.5 op_sel_hi:[1,0]
	v_pk_mul_f32 v[80:81], v[32:33], 0.5 op_sel_hi:[1,0]
	v_pk_mul_f32 v[94:95], v[14:15], 0.5 op_sel_hi:[1,0]
	v_pk_mul_f32 v[92:93], v[12:13], 0.5 op_sel_hi:[1,0]
	v_pk_mul_f32 v[90:91], v[10:11], 0.5 op_sel_hi:[1,0]
	v_pk_mul_f32 v[88:89], v[8:9], 0.5 op_sel_hi:[1,0]
	v_pk_mul_f32 v[70:71], v[26:27], 0.5 op_sel_hi:[1,0]
	v_pk_mul_f32 v[68:69], v[24:25], 0.5 op_sel_hi:[1,0]
	v_pk_mul_f32 v[66:67], v[18:19], 0.5 op_sel_hi:[1,0]
	v_pk_mul_f32 v[64:65], v[16:17], 0.5 op_sel_hi:[1,0]
	v_pk_mul_f32 v[78:79], v[6:7], 0.5 op_sel_hi:[1,0]
	v_pk_mul_f32 v[76:77], v[4:5], 0.5 op_sel_hi:[1,0]
	v_pk_mul_f32 v[74:75], v[2:3], 0.5 op_sel_hi:[1,0]
	v_pk_mul_f32 v[72:73], v[0:1], 0.5 op_sel_hi:[1,0]

; #define PG8_STAGE(bufoff, gbase, voff) do { _Pragma("unroll") for (int _i = 0; _i < 2; ++_i) \
;         __builtin_amdgcn_global_load_lds((const unsigned*)((const char*)(gbase) + (voff)[_i]), (LAS unsigned*)(lds + (bufoff) + ldsw + _i * 8192), 16, 0, 0); } while (0)
; #define PG8_LDA(dst, b, h) do { _Pragma("unroll") for (int m = 0; m < 4; ++m) _Pragma("unroll") for (int k = 0; k < 2; ++k) dst[m][k] = *(const LAS bf16x8*)(lds + PG8_SA(b, h) + aoff + m * 2048 + k * 1024); } while (0)
; #define PG8_LDB(dst, b, h) do { _Pragma("unroll") for (int n = 0; n < 2; ++n) _Pragma("unroll") for (int k = 0; k < 2; ++k) dst[n][k] = *(const LAS bf16x8*)(lds + PG8_SB(b, h) + boff + n * 2048 + k * 1024); } while (0)
; #define PG8_MMA(ai, bj, At, Bt) do { __builtin_amdgcn_s_setprio(1); _Pragma("unroll") for (int m = 0; m < 4; ++m) _Pragma("unroll") for (int n = 0; n < 2; ++n) _Pragma("unroll") for (int k = 0; k < 2; ++k) \
;         acc[ai][bj][m][n] = __builtin_amdgcn_mfma_f32_16x16x32_bf16(Bt[n][k], At[m][k], acc[ai][bj][m][n], 0, 0, 0); __builtin_amdgcn_s_setprio(0); } while (0)
; #define PG8_WAIT_V(n) asm volatile("s_waitcnt vmcnt(" #n ")" ::: "memory")
; #define PG8_WAIT_L(n) asm volatile("s_waitcnt lgkmcnt(" #n ")" ::: "memory")
; #define PG8_BAR __builtin_amdgcn_s_barrier()
; #define PG8_SCHED __builtin_amdgcn_sched_barrier(0)
; template <class Epi>
; __device__ __forceinline__ void gemm_phase(LAS unsigned char* lds, const Gemm g, const StaticOrder& S, const Epi& E) {
;     ...
;             const bool last = (t == nt - 2);
;             const char* a1 = cA + (size_t)(t + 1) * kstep;
;             const char* a2 = last ? nA : cA + (size_t)(t + 2) * kstep; const char* b2 = last ? nB : cB + (size_t)(t + 2) * kstep;
;             const char* a3 = a2 + kstep; const char* b3 = b2 + kstep;
;             PG8_LDB(B0, 0, 0); PG8_LDB(B1, 0, 1); PG8_SCHED; PG8_LDA(At, 0, 0); PG8_STAGE(PG8_SA(1, 1), a1 + hstepA, voffA);
;             PG8_WAIT_V(8); PG8_WAIT_L(0); PG8_BAR; PG8_MMA(0, 0, At, B0); PG8_MMA(0, 1, At, B1); PG8_BAR; PG8_SCHED;
;             PG8_LDA(At, 0, 1); PG8_STAGE(PG8_SB(0, 0), b2, voffB); PG8_STAGE(PG8_SB(0, 1), b2 + hstepB, voffB); PG8_STAGE(PG8_SA(0, 0), a2, voffA);
;             PG8_WAIT_V(8); PG8_WAIT_L(0); PG8_BAR; PG8_MMA(1, 0, At, B0); PG8_MMA(1, 1, At, B1); PG8_BAR; PG8_SCHED;
.LBB0_541:
	ds_read_b128 v[148:151], v155
	ds_read_b128 v[160:163], v155 offset:1024
	ds_read_b128 v[164:167], v155 offset:2048
	ds_read_b128 v[168:171], v155 offset:3072
	ds_read_b128 v[172:175], v156
	ds_read_b128 v[176:179], v156 offset:1024
	ds_read_b128 v[180:183], v156 offset:2048
	ds_read_b128 v[184:187], v156 offset:3072
	s_add_i32 s35, s26, 2
	s_add_u32 s27, s8, 0xfff80080
	s_addc_u32 s30, s9, -1
	s_cmp_eq_u32 s49, s26
	s_cselect_b32 s26, s21, s33
	s_cselect_b32 s31, s1, s30
	s_cselect_b32 s30, s5, s27
	s_cselect_b32 s27, s19, s34
	v_lshl_add_u64 v[224:225], s[8:9], 0, v[140:141]
	s_add_i32 m0, s39, 0xc000
	ds_read_b128 v[188:191], v157
	ds_read_b128 v[192:195], v157 offset:1024
	ds_read_b128 v[196:199], v157 offset:2048
	ds_read_b128 v[200:203], v157 offset:3072
	ds_read_b128 v[208:211], v157 offset:4096
	ds_read_b128 v[212:215], v157 offset:5120
	ds_read_b128 v[216:219], v157 offset:6144
	ds_read_b128 v[220:223], v157 offset:7168
	global_load_lds_dwordx4 v[224:225], off
	v_lshl_add_u64 v[224:225], s[8:9], 0, v[142:143]
	s_add_i32 m0, s39, 0xe000
	s_nop 0
	global_load_lds_dwordx4 v[224:225], off
	s_waitcnt vmcnt(8)
	s_waitcnt lgkmcnt(0)
	s_setprio 1
	s_barrier
	s_waitcnt lgkmcnt(0)
	v_mfma_f32_16x16x32_bf16 v[120:123], v[148:151], v[188:191], v[120:123]
	v_mfma_f32_16x16x32_bf16 v[120:123], v[160:163], v[192:195], v[120:123]
	v_mfma_f32_16x16x32_bf16 v[124:127], v[168:171], v[192:195], v[124:127]
	v_mfma_f32_16x16x32_bf16 v[124:127], v[164:167], v[188:191], v[124:127]
	v_mfma_f32_16x16x32_bf16 v[116:119], v[172:175], v[188:191], v[116:119]
	v_mfma_f32_16x16x32_bf16 v[116:119], v[176:179], v[192:195], v[116:119]
	v_mfma_f32_16x16x32_bf16 v[112:115], v[184:187], v[192:195], v[112:115]
	v_mfma_f32_16x16x32_bf16 v[112:115], v[180:183], v[188:191], v[112:115]
	v_mfma_f32_16x16x32_bf16 v[96:99], v[180:183], v[196:199], v[96:99]
	v_mfma_f32_16x16x32_bf16 v[96:99], v[184:187], v[200:203], v[96:99]
	v_mfma_f32_16x16x32_bf16 v[100:103], v[176:179], v[200:203], v[100:103]
	v_mfma_f32_16x16x32_bf16 v[100:103], v[172:175], v[196:199], v[100:103]
	v_mfma_f32_16x16x32_bf16 v[104:107], v[164:167], v[196:199], v[104:107]
	v_mfma_f32_16x16x32_bf16 v[104:107], v[168:171], v[200:203], v[104:107]
	v_mfma_f32_16x16x32_bf16 v[108:111], v[160:163], v[200:203], v[108:111]
	v_mfma_f32_16x16x32_bf16 v[108:111], v[148:151], v[196:199], v[108:111]
	s_setprio 0
	s_setprio 1
	v_mfma_f32_16x16x32_bf16 v[92:95], v[148:151], v[208:211], v[92:95]
	v_mfma_f32_16x16x32_bf16 v[92:95], v[160:163], v[212:215], v[92:95]
	v_mfma_f32_16x16x32_bf16 v[88:91], v[168:171], v[212:215], v[88:91]
	v_mfma_f32_16x16x32_bf16 v[88:91], v[164:167], v[208:211], v[88:91]
	v_mfma_f32_16x16x32_bf16 v[84:87], v[172:175], v[208:211], v[84:87]
	v_mfma_f32_16x16x32_bf16 v[84:87], v[176:179], v[212:215], v[84:87]
	v_mfma_f32_16x16x32_bf16 v[80:83], v[184:187], v[212:215], v[80:83]
	v_mfma_f32_16x16x32_bf16 v[80:83], v[180:183], v[208:211], v[80:83]
	v_mfma_f32_16x16x32_bf16 v[64:67], v[180:183], v[216:219], v[64:67]
	v_mfma_f32_16x16x32_bf16 v[64:67], v[184:187], v[220:223], v[64:67]
	v_mfma_f32_16x16x32_bf16 v[68:71], v[176:179], v[220:223], v[68:71]
	v_mfma_f32_16x16x32_bf16 v[68:71], v[172:175], v[216:219], v[68:71]
	v_mfma_f32_16x16x32_bf16 v[72:75], v[164:167], v[216:219], v[72:75]
	v_mfma_f32_16x16x32_bf16 v[72:75], v[168:171], v[220:223], v[72:75]
	v_mfma_f32_16x16x32_bf16 v[76:79], v[160:163], v[220:223], v[76:79]
	v_mfma_f32_16x16x32_bf16 v[76:79], v[148:151], v[216:219], v[76:79]
	s_setprio 0
	s_barrier
	s_add_i32 s58, s54, s38
	v_lshl_add_u64 v[224:225], s[26:27], 0, v[130:131]
	s_mov_b32 m0, s58
	ds_read_b128 v[188:191], v157 offset:16384
	ds_read_b128 v[192:195], v157 offset:17408
	ds_read_b128 v[196:199], v157 offset:18432
	ds_read_b128 v[200:203], v157 offset:19456
	ds_read_b128 v[208:211], v157 offset:20480
	ds_read_b128 v[212:215], v157 offset:21504
	ds_read_b128 v[216:219], v157 offset:22528
	ds_read_b128 v[220:223], v157 offset:23552
	global_load_lds_dwordx4 v[224:225], off
	s_add_i32 m0, s58, 0x2000
	s_add_u32 s58, s26, 0x80000
	v_lshl_add_u64 v[226:227], s[26:27], 0, v[134:135]
	s_addc_u32 s59, s27, 0
	s_add_i32 s60, s55, s38
	global_load_lds_dwordx4 v[226:227], off
	v_lshl_add_u64 v[230:231], s[58:59], 0, v[130:131]
	s_mov_b32 m0, s60
	v_lshl_add_u64 v[232:233], s[30:31], 0, v[132:133]
	global_load_lds_dwordx4 v[230:231], off
	v_lshl_add_u64 v[230:231], s[58:59], 0, v[134:135]
	s_add_i32 m0, s60, 0x2000
	s_nop 0
	global_load_lds_dwordx4 v[230:231], off
	v_lshl_add_u64 v[230:231], s[30:31], 0, v[128:129]
	s_mov_b32 m0, s39
	s_nop 0
	global_load_lds_dwordx4 v[230:231], off
	s_mov_b32 m0, s40
	s_nop 0
	global_load_lds_dwordx4 v[232:233], off
	s_waitcnt vmcnt(8)
	s_waitcnt lgkmcnt(0)
	s_setprio 1
	s_barrier
; #define PG8_STAGE(bufoff, gbase, voff) do { _Pragma("unroll") for (int _i = 0; _i < 2; ++_i) \
;         __builtin_amdgcn_global_load_lds((const unsigned*)((const char*)(gbase) + (voff)[_i]), (LAS unsigned*)(lds + (bufoff) + ldsw + _i * 8192), 16, 0, 0); } while (0)
; #define PG8_LDA(dst, b, h) do { _Pragma("unroll") for (int m = 0; m < 4; ++m) _Pragma("unroll") for (int k = 0; k < 2; ++k) dst[m][k] = *(const LAS bf16x8*)(lds + PG8_SA(b, h) + aoff + m * 2048 + k * 1024); } while (0)
; #define PG8_LDB(dst, b, h) do { _Pragma("unroll") for (int n = 0; n < 2; ++n) _Pragma("unroll") for (int k = 0; k < 2; ++k) dst[n][k] = *(const LAS bf16x8*)(lds + PG8_SB(b, h) + boff + n * 2048 + k * 1024); } while (0)
; #define PG8_MMA(ai, bj, At, Bt) do { __builtin_amdgcn_s_setprio(1); _Pragma("unroll") for (int m = 0; m < 4; ++m) _Pragma("unroll") for (int n = 0; n < 2; ++n) _Pragma("unroll") for (int k = 0; k < 2; ++k) \
;         acc[ai][bj][m][n] = __builtin_amdgcn_mfma_f32_16x16x32_bf16(Bt[n][k], At[m][k], acc[ai][bj][m][n], 0, 0, 0); __builtin_amdgcn_s_setprio(0); } while (0)
; #define PG8_WAIT_V(n) asm volatile("s_waitcnt vmcnt(" #n ")" ::: "memory")
; #define PG8_WAIT_L(n) asm volatile("s_waitcnt lgkmcnt(" #n ")" ::: "memory")
; #define PG8_BAR __builtin_amdgcn_s_barrier()
; #define PG8_SCHED __builtin_amdgcn_sched_barrier(0)
; template <class Epi>
; __device__ __forceinline__ void gemm_phase(LAS unsigned char* lds, const Gemm g, const StaticOrder& S, const Epi& E) {
;     ...
;             PG8_WAIT_V(8); PG8_WAIT_L(0); PG8_BAR; PG8_MMA(1, 0, At, B0); PG8_MMA(1, 1, At, B1); PG8_BAR; PG8_SCHED;
;             PG8_LDB(B0, 1, 0); PG8_LDB(B1, 1, 1); PG8_SCHED; PG8_LDA(At, 1, 0); PG8_STAGE(PG8_SA(0, 1), a2 + hstepA, voffA);
;             PG8_WAIT_V(8); PG8_WAIT_L(0); PG8_BAR; PG8_MMA(0, 0, At, B0); PG8_MMA(0, 1, At, B1); PG8_BAR; PG8_SCHED;
	s_waitcnt lgkmcnt(0)
	v_mfma_f32_16x16x32_bf16 v[60:63], v[148:151], v[188:191], v[60:63]
	v_mfma_f32_16x16x32_bf16 v[60:63], v[160:163], v[192:195], v[60:63]
	v_mfma_f32_16x16x32_bf16 v[56:59], v[168:171], v[192:195], v[56:59]
	v_mfma_f32_16x16x32_bf16 v[56:59], v[164:167], v[188:191], v[56:59]
	v_mfma_f32_16x16x32_bf16 v[52:55], v[172:175], v[188:191], v[52:55]
	v_mfma_f32_16x16x32_bf16 v[52:55], v[176:179], v[192:195], v[52:55]
	v_mfma_f32_16x16x32_bf16 v[48:51], v[184:187], v[192:195], v[48:51]
	v_mfma_f32_16x16x32_bf16 v[48:51], v[180:183], v[188:191], v[48:51]
	v_mfma_f32_16x16x32_bf16 v[32:35], v[180:183], v[196:199], v[32:35]
	v_mfma_f32_16x16x32_bf16 v[32:35], v[184:187], v[200:203], v[32:35]
	v_mfma_f32_16x16x32_bf16 v[36:39], v[176:179], v[200:203], v[36:39]
	v_mfma_f32_16x16x32_bf16 v[36:39], v[172:175], v[196:199], v[36:39]
	v_mfma_f32_16x16x32_bf16 v[40:43], v[164:167], v[196:199], v[40:43]
	v_mfma_f32_16x16x32_bf16 v[40:43], v[168:171], v[200:203], v[40:43]
	v_mfma_f32_16x16x32_bf16 v[44:47], v[160:163], v[200:203], v[44:47]
	v_mfma_f32_16x16x32_bf16 v[44:47], v[148:151], v[196:199], v[44:47]
	s_setprio 0
	s_setprio 1
	v_mfma_f32_16x16x32_bf16 v[28:31], v[148:151], v[208:211], v[28:31]
	v_mfma_f32_16x16x32_bf16 v[28:31], v[160:163], v[212:215], v[28:31]
	v_mfma_f32_16x16x32_bf16 v[24:27], v[168:171], v[212:215], v[24:27]
	v_mfma_f32_16x16x32_bf16 v[24:27], v[164:167], v[208:211], v[24:27]
	v_mfma_f32_16x16x32_bf16 v[20:23], v[172:175], v[208:211], v[20:23]
	v_mfma_f32_16x16x32_bf16 v[20:23], v[176:179], v[212:215], v[20:23]
	v_mfma_f32_16x16x32_bf16 v[16:19], v[184:187], v[212:215], v[16:19]
	v_mfma_f32_16x16x32_bf16 v[16:19], v[180:183], v[208:211], v[16:19]
	v_mfma_f32_16x16x32_bf16 v[0:3], v[180:183], v[216:219], v[0:3]
	v_mfma_f32_16x16x32_bf16 v[0:3], v[184:187], v[220:223], v[0:3]
	v_mfma_f32_16x16x32_bf16 v[4:7], v[176:179], v[220:223], v[4:7]
	v_mfma_f32_16x16x32_bf16 v[4:7], v[172:175], v[216:219], v[4:7]
	v_mfma_f32_16x16x32_bf16 v[8:11], v[164:167], v[216:219], v[8:11]
	v_mfma_f32_16x16x32_bf16 v[8:11], v[168:171], v[220:223], v[8:11]
	v_mfma_f32_16x16x32_bf16 v[12:15], v[160:163], v[220:223], v[12:15]
	v_mfma_f32_16x16x32_bf16 v[12:15], v[148:151], v[216:219], v[12:15]
	s_setprio 0
	s_barrier
	s_add_i32 s58, 0, 0x18000
	v_add_u32_e32 v136, s58, v154
	s_add_i32 s59, 0, 0x1c000
	ds_read_b128 v[148:151], v136
	ds_read_b128 v[160:163], v136 offset:1024
	ds_read_b128 v[164:167], v136 offset:2048
	ds_read_b128 v[168:171], v136 offset:3072
	v_add_u32_e32 v136, s59, v154
	ds_read_b128 v[172:175], v136
	ds_read_b128 v[176:179], v136 offset:1024
	ds_read_b128 v[180:183], v136 offset:2048
	ds_read_b128 v[184:187], v136 offset:3072
	s_add_u32 s30, s30, 0x80000
	s_addc_u32 s31, s31, 0
	s_mov_b32 m0, s41
	v_lshl_add_u64 v[234:235], s[30:31], 0, v[128:129]
	ds_read_b128 v[188:191], v157 offset:32768
	ds_read_b128 v[192:195], v157 offset:33792
	ds_read_b128 v[196:199], v157 offset:34816
	ds_read_b128 v[200:203], v157 offset:35840
	ds_read_b128 v[208:211], v157 offset:36864
	ds_read_b128 v[212:215], v157 offset:37888
	ds_read_b128 v[216:219], v157 offset:38912
	ds_read_b128 v[220:223], v157 offset:39936
	global_load_lds_dwordx4 v[234:235], off
	v_lshl_add_u64 v[234:235], s[30:31], 0, v[132:133]
	s_mov_b32 m0, s42
	s_nop 0
	global_load_lds_dwordx4 v[234:235], off
	s_waitcnt vmcnt(8)
	s_waitcnt lgkmcnt(0)
	s_setprio 1
	s_barrier
	s_waitcnt lgkmcnt(0)
	v_mfma_f32_16x16x32_bf16 v[120:123], v[148:151], v[188:191], v[120:123]
	v_mfma_f32_16x16x32_bf16 v[120:123], v[160:163], v[192:195], v[120:123]
	v_mfma_f32_16x16x32_bf16 v[124:127], v[168:171], v[192:195], v[124:127]
	v_mfma_f32_16x16x32_bf16 v[124:127], v[164:167], v[188:191], v[124:127]
	v_mfma_f32_16x16x32_bf16 v[116:119], v[172:175], v[188:191], v[116:119]
	v_mfma_f32_16x16x32_bf16 v[116:119], v[176:179], v[192:195], v[116:119]
	v_mfma_f32_16x16x32_bf16 v[112:115], v[184:187], v[192:195], v[112:115]
	v_mfma_f32_16x16x32_bf16 v[112:115], v[180:183], v[188:191], v[112:115]
	v_mfma_f32_16x16x32_bf16 v[96:99], v[180:183], v[196:199], v[96:99]
	v_mfma_f32_16x16x32_bf16 v[96:99], v[184:187], v[200:203], v[96:99]
	v_mfma_f32_16x16x32_bf16 v[100:103], v[176:179], v[200:203], v[100:103]
	v_mfma_f32_16x16x32_bf16 v[100:103], v[172:175], v[196:199], v[100:103]
	v_mfma_f32_16x16x32_bf16 v[104:107], v[164:167], v[196:199], v[104:107]
	v_mfma_f32_16x16x32_bf16 v[104:107], v[168:171], v[200:203], v[104:107]
	v_mfma_f32_16x16x32_bf16 v[108:111], v[160:163], v[200:203], v[108:111]
	v_mfma_f32_16x16x32_bf16 v[108:111], v[148:151], v[196:199], v[108:111]
	s_setprio 0
	s_setprio 1
	v_mfma_f32_16x16x32_bf16 v[92:95], v[148:151], v[208:211], v[92:95]
	v_mfma_f32_16x16x32_bf16 v[92:95], v[160:163], v[212:215], v[92:95]
	v_mfma_f32_16x16x32_bf16 v[88:91], v[168:171], v[212:215], v[88:91]
	v_mfma_f32_16x16x32_bf16 v[88:91], v[164:167], v[208:211], v[88:91]
	v_mfma_f32_16x16x32_bf16 v[84:87], v[172:175], v[208:211], v[84:87]
	v_mfma_f32_16x16x32_bf16 v[84:87], v[176:179], v[212:215], v[84:87]
	v_mfma_f32_16x16x32_bf16 v[80:83], v[184:187], v[212:215], v[80:83]
	v_mfma_f32_16x16x32_bf16 v[80:83], v[180:183], v[208:211], v[80:83]
	v_mfma_f32_16x16x32_bf16 v[64:67], v[180:183], v[216:219], v[64:67]
	v_mfma_f32_16x16x32_bf16 v[64:67], v[184:187], v[220:223], v[64:67]
	v_mfma_f32_16x16x32_bf16 v[68:71], v[176:179], v[220:223], v[68:71]
	v_mfma_f32_16x16x32_bf16 v[68:71], v[172:175], v[216:219], v[68:71]
	v_mfma_f32_16x16x32_bf16 v[72:75], v[164:167], v[216:219], v[72:75]
	v_mfma_f32_16x16x32_bf16 v[72:75], v[168:171], v[220:223], v[72:75]
	v_mfma_f32_16x16x32_bf16 v[76:79], v[160:163], v[220:223], v[76:79]
	v_mfma_f32_16x16x32_bf16 v[76:79], v[148:151], v[216:219], v[76:79]
	s_setprio 0
	s_barrier
; #define PG8_STAGE(bufoff, gbase, voff) do { _Pragma("unroll") for (int _i = 0; _i < 2; ++_i) \
;         __builtin_amdgcn_global_load_lds((const unsigned*)((const char*)(gbase) + (voff)[_i]), (LAS unsigned*)(lds + (bufoff) + ldsw + _i * 8192), 16, 0, 0); } while (0)
; #define PG8_LDA(dst, b, h) do { _Pragma("unroll") for (int m = 0; m < 4; ++m) _Pragma("unroll") for (int k = 0; k < 2; ++k) dst[m][k] = *(const LAS bf16x8*)(lds + PG8_SA(b, h) + aoff + m * 2048 + k * 1024); } while (0)
; #define PG8_MMA(ai, bj, At, Bt) do { __builtin_amdgcn_s_setprio(1); _Pragma("unroll") for (int m = 0; m < 4; ++m) _Pragma("unroll") for (int n = 0; n < 2; ++n) _Pragma("unroll") for (int k = 0; k < 2; ++k) \
;         acc[ai][bj][m][n] = __builtin_amdgcn_mfma_f32_16x16x32_bf16(Bt[n][k], At[m][k], acc[ai][bj][m][n], 0, 0, 0); __builtin_amdgcn_s_setprio(0); } while (0)
; #define PG8_WAIT_V(n) asm volatile("s_waitcnt vmcnt(" #n ")" ::: "memory")
; #define PG8_WAIT_L(n) asm volatile("s_waitcnt lgkmcnt(" #n ")" ::: "memory")
; #define PG8_BAR __builtin_amdgcn_s_barrier()
; #define PG8_SCHED __builtin_amdgcn_sched_barrier(0)
; template <class Epi>
; __device__ __forceinline__ void gemm_phase(LAS unsigned char* lds, const Gemm g, const StaticOrder& S, const Epi& E) {
;     ...
;             PG8_LDA(At, 1, 1); PG8_STAGE(PG8_SB(1, 0), b3, voffB); PG8_STAGE(PG8_SB(1, 1), b3 + hstepB, voffB); PG8_STAGE(PG8_SA(1, 0), a3, voffA);
;             PG8_WAIT_V(8); PG8_WAIT_L(0); PG8_BAR; PG8_MMA(1, 0, At, B0); PG8_MMA(1, 1, At, B1); PG8_BAR; PG8_SCHED;
;         }
	s_add_i32 s30, s58, s38
	v_lshl_add_u64 v[224:225], v[224:225], 0, s[12:13]
	s_mov_b32 m0, s30
	ds_read_b128 v[188:191], v157 offset:49152
	ds_read_b128 v[192:195], v157 offset:50176
	ds_read_b128 v[196:199], v157 offset:51200
	ds_read_b128 v[200:203], v157 offset:52224
	ds_read_b128 v[208:211], v157 offset:53248
	ds_read_b128 v[212:215], v157 offset:54272
	ds_read_b128 v[216:219], v157 offset:55296
	ds_read_b128 v[220:223], v157 offset:56320
	global_load_lds_dwordx4 v[224:225], off
	s_add_i32 m0, s30, 0x2000
	s_add_u32 s26, s26, 0x80080
	v_lshl_add_u64 v[224:225], v[226:227], 0, s[12:13]
	s_addc_u32 s27, s27, 0
	s_add_i32 s30, s59, s38
	global_load_lds_dwordx4 v[224:225], off
	v_lshl_add_u64 v[224:225], s[26:27], 0, v[130:131]
	s_mov_b32 m0, s30
	s_nop 0
	global_load_lds_dwordx4 v[224:225], off
	v_lshl_add_u64 v[224:225], s[26:27], 0, v[134:135]
	s_add_i32 m0, s30, 0x2000
	s_nop 0
	global_load_lds_dwordx4 v[224:225], off
	v_lshl_add_u64 v[224:225], v[230:231], 0, s[12:13]
	s_mov_b32 m0, s47
	s_nop 0
	global_load_lds_dwordx4 v[224:225], off
	v_lshl_add_u64 v[224:225], v[232:233], 0, s[12:13]
	s_mov_b32 m0, s48
	s_nop 0
	global_load_lds_dwordx4 v[224:225], off
	s_waitcnt vmcnt(8)
	s_waitcnt lgkmcnt(0)
	s_setprio 1
	s_barrier
	s_waitcnt lgkmcnt(0)
	v_mfma_f32_16x16x32_bf16 v[60:63], v[148:151], v[188:191], v[60:63]
	v_mfma_f32_16x16x32_bf16 v[60:63], v[160:163], v[192:195], v[60:63]
	v_mfma_f32_16x16x32_bf16 v[56:59], v[168:171], v[192:195], v[56:59]
	v_mfma_f32_16x16x32_bf16 v[56:59], v[164:167], v[188:191], v[56:59]
	v_mfma_f32_16x16x32_bf16 v[52:55], v[172:175], v[188:191], v[52:55]
	v_mfma_f32_16x16x32_bf16 v[52:55], v[176:179], v[192:195], v[52:55]
	v_mfma_f32_16x16x32_bf16 v[48:51], v[184:187], v[192:195], v[48:51]
	v_mfma_f32_16x16x32_bf16 v[48:51], v[180:183], v[188:191], v[48:51]
	v_mfma_f32_16x16x32_bf16 v[32:35], v[180:183], v[196:199], v[32:35]
	v_mfma_f32_16x16x32_bf16 v[32:35], v[184:187], v[200:203], v[32:35]
	v_mfma_f32_16x16x32_bf16 v[36:39], v[176:179], v[200:203], v[36:39]
	v_mfma_f32_16x16x32_bf16 v[36:39], v[172:175], v[196:199], v[36:39]
	v_mfma_f32_16x16x32_bf16 v[40:43], v[164:167], v[196:199], v[40:43]
	v_mfma_f32_16x16x32_bf16 v[40:43], v[168:171], v[200:203], v[40:43]
	v_mfma_f32_16x16x32_bf16 v[44:47], v[160:163], v[200:203], v[44:47]
	v_mfma_f32_16x16x32_bf16 v[44:47], v[148:151], v[196:199], v[44:47]
	s_setprio 0
	s_setprio 1
	v_mfma_f32_16x16x32_bf16 v[28:31], v[148:151], v[208:211], v[28:31]
	v_mfma_f32_16x16x32_bf16 v[28:31], v[160:163], v[212:215], v[28:31]
	v_mfma_f32_16x16x32_bf16 v[24:27], v[168:171], v[212:215], v[24:27]
	v_mfma_f32_16x16x32_bf16 v[24:27], v[164:167], v[208:211], v[24:27]
	v_mfma_f32_16x16x32_bf16 v[20:23], v[172:175], v[208:211], v[20:23]
	v_mfma_f32_16x16x32_bf16 v[20:23], v[176:179], v[212:215], v[20:23]
	v_mfma_f32_16x16x32_bf16 v[16:19], v[184:187], v[212:215], v[16:19]
	v_mfma_f32_16x16x32_bf16 v[16:19], v[180:183], v[208:211], v[16:19]
	v_mfma_f32_16x16x32_bf16 v[0:3], v[180:183], v[216:219], v[0:3]
	v_mfma_f32_16x16x32_bf16 v[0:3], v[184:187], v[220:223], v[0:3]
	v_mfma_f32_16x16x32_bf16 v[4:7], v[176:179], v[220:223], v[4:7]
	v_mfma_f32_16x16x32_bf16 v[4:7], v[172:175], v[216:219], v[4:7]
	v_mfma_f32_16x16x32_bf16 v[8:11], v[164:167], v[216:219], v[8:11]
	v_mfma_f32_16x16x32_bf16 v[8:11], v[168:171], v[220:223], v[8:11]
	v_mfma_f32_16x16x32_bf16 v[12:15], v[160:163], v[220:223], v[12:15]
	v_mfma_f32_16x16x32_bf16 v[12:15], v[148:151], v[216:219], v[12:15]
	s_setprio 0
	s_barrier
	s_add_u32 s8, s8, 0x100
	s_addc_u32 s9, s9, 0
	s_add_u32 s33, s33, 0x100
	s_addc_u32 s34, s34, 0
	s_cmp_ge_i32 s35, s44
	s_mov_b32 s26, s35
	s_cbranch_scc0 .LBB0_541

; #define PG8_STAGE(bufoff, gbase, voff) do { _Pragma("unroll") for (int _i = 0; _i < 2; ++_i) \
;         __builtin_amdgcn_global_load_lds((const unsigned*)((const char*)(gbase) + (voff)[_i]), (LAS unsigned*)(lds + (bufoff) + ldsw + _i * 8192), 16, 0, 0); } while (0)
; #define PG8_LDA(dst, b, h) do { _Pragma("unroll") for (int m = 0; m < 4; ++m) _Pragma("unroll") for (int k = 0; k < 2; ++k) dst[m][k] = *(const LAS bf16x8*)(lds + PG8_SA(b, h) + aoff + m * 2048 + k * 1024); } while (0)
; #define PG8_LDB(dst, b, h) do { _Pragma("unroll") for (int n = 0; n < 2; ++n) _Pragma("unroll") for (int k = 0; k < 2; ++k) dst[n][k] = *(const LAS bf16x8*)(lds + PG8_SB(b, h) + boff + n * 2048 + k * 1024); } while (0)
; #define PG8_MMA(ai, bj, At, Bt) do { __builtin_amdgcn_s_setprio(1); _Pragma("unroll") for (int m = 0; m < 4; ++m) _Pragma("unroll") for (int n = 0; n < 2; ++n) _Pragma("unroll") for (int k = 0; k < 2; ++k) \
;         acc[ai][bj][m][n] = __builtin_amdgcn_mfma_f32_16x16x32_bf16(Bt[n][k], At[m][k], acc[ai][bj][m][n], 0, 0, 0); __builtin_amdgcn_s_setprio(0); } while (0)
; #define PG8_WAIT_V(n) asm volatile("s_waitcnt vmcnt(" #n ")" ::: "memory")
; #define PG8_WAIT_L(n) asm volatile("s_waitcnt lgkmcnt(" #n ")" ::: "memory")
; #define PG8_BAR __builtin_amdgcn_s_barrier()
; #define PG8_SCHED __builtin_amdgcn_sched_barrier(0)
; template <class Epi>
; __device__ __forceinline__ void gemm_phase(LAS unsigned char* lds, const Gemm g, const StaticOrder& S, const Epi& E) {
;     ...
;             PG8_LDB(B0, 0, 0); PG8_LDB(B1, 0, 1); PG8_SCHED; PG8_LDA(At, 0, 0); PG8_STAGE(PG8_SA(1, 1), a1 + hstepA, voffA);
;             PG8_WAIT_V(8); PG8_WAIT_L(0); PG8_BAR; PG8_MMA(0, 0, At, B0); PG8_MMA(0, 1, At, B1); PG8_BAR; PG8_SCHED;
;             PG8_LDA(At, 0, 1); PG8_STAGE(PG8_SB(0, 0), b2, voffB); PG8_STAGE(PG8_SB(0, 1), b2 + hstepB, voffB); PG8_STAGE(PG8_SA(0, 0), a2, voffA);
;             PG8_WAIT_V(8); PG8_WAIT_L(0); PG8_BAR; PG8_MMA(1, 0, At, B0); PG8_MMA(1, 1, At, B1); PG8_BAR; PG8_SCHED;
.LBB0_685:
	ds_read_b128 v[88:91], v85
	ds_read_b128 v[92:95], v85 offset:1024
	ds_read_b128 v[96:99], v85 offset:2048
	ds_read_b128 v[100:103], v85 offset:3072
	s_add_i32 s61, s34, 2
	s_add_u32 s8, s30, 0x100
	s_addc_u32 s9, s31, 0
	s_cmp_eq_u32 s53, s34
	s_cselect_b32 s34, s25, s59
	s_cselect_b32 s37, s27, s9
	s_cselect_b32 s36, s26, s8
	s_cselect_b32 s35, s17, s60
	v_lshl_add_u64 v[136:137], s[30:31], 0, v[76:77]
	s_add_i32 m0, s40, 0xc000
	ds_read_b128 v[104:107], v86
	ds_read_b128 v[108:111], v86 offset:1024
	ds_read_b128 v[112:115], v86 offset:2048
	ds_read_b128 v[116:119], v86 offset:3072
	ds_read_b128 v[120:123], v86 offset:4096
	ds_read_b128 v[124:127], v86 offset:5120
	ds_read_b128 v[128:131], v86 offset:6144
	ds_read_b128 v[132:135], v86 offset:7168
	global_load_lds_dwordx4 v[136:137], off
	v_lshl_add_u64 v[136:137], s[30:31], 0, v[78:79]
	s_add_i32 m0, s40, 0xe000
	s_nop 0
	global_load_lds_dwordx4 v[136:137], off
	s_waitcnt vmcnt(8)
	s_waitcnt lgkmcnt(0)
	s_setprio 1
	s_barrier
	s_waitcnt lgkmcnt(0)
	v_mfma_f32_16x16x32_bf16 v[60:63], v[88:91], v[104:107], v[60:63]
	v_mfma_f32_16x16x32_bf16 v[60:63], v[92:95], v[108:111], v[60:63]
	v_mfma_f32_16x16x32_bf16 v[56:59], v[100:103], v[108:111], v[56:59]
	v_mfma_f32_16x16x32_bf16 v[56:59], v[96:99], v[104:107], v[56:59]
	v_mfma_f32_16x16x32_bf16 v[48:51], v[96:99], v[112:115], v[48:51]
	v_mfma_f32_16x16x32_bf16 v[48:51], v[100:103], v[116:119], v[48:51]
	v_mfma_f32_16x16x32_bf16 v[52:55], v[92:95], v[116:119], v[52:55]
	v_mfma_f32_16x16x32_bf16 v[52:55], v[88:91], v[112:115], v[52:55]
	v_mfma_f32_16x16x32_bf16 v[44:47], v[88:91], v[120:123], v[44:47]
	v_mfma_f32_16x16x32_bf16 v[44:47], v[92:95], v[124:127], v[44:47]
	v_mfma_f32_16x16x32_bf16 v[40:43], v[100:103], v[124:127], v[40:43]
	v_mfma_f32_16x16x32_bf16 v[40:43], v[96:99], v[120:123], v[40:43]
	v_mfma_f32_16x16x32_bf16 v[32:35], v[96:99], v[128:131], v[32:35]
	v_mfma_f32_16x16x32_bf16 v[32:35], v[100:103], v[132:135], v[32:35]
	v_mfma_f32_16x16x32_bf16 v[36:39], v[92:95], v[132:135], v[36:39]
	v_mfma_f32_16x16x32_bf16 v[36:39], v[88:91], v[128:131], v[36:39]
	s_setprio 0
	s_setprio 1
	s_setprio 0
	s_barrier
	s_add_i32 s30, s56, s39
	v_lshl_add_u64 v[136:137], s[34:35], 0, v[66:67]
	s_mov_b32 m0, s30
	ds_read_b128 v[104:107], v86 offset:16384
	ds_read_b128 v[108:111], v86 offset:17408
	ds_read_b128 v[112:115], v86 offset:18432
	ds_read_b128 v[116:119], v86 offset:19456
	ds_read_b128 v[120:123], v86 offset:20480
	ds_read_b128 v[124:127], v86 offset:21504
	ds_read_b128 v[128:131], v86 offset:22528
	ds_read_b128 v[132:135], v86 offset:23552
	global_load_lds_dwordx4 v[136:137], off
	s_add_i32 m0, s30, 0x2000
	s_add_u32 s30, s34, 0x10000
	v_lshl_add_u64 v[138:139], s[34:35], 0, v[70:71]
	s_addc_u32 s31, s35, 0
	global_load_lds_dwordx4 v[138:139], off
	v_lshl_add_u64 v[140:141], s[30:31], 0, v[66:67]
	s_mov_b32 m0, s41
	v_lshl_add_u64 v[142:143], s[36:37], 0, v[68:69]
	global_load_lds_dwordx4 v[140:141], off
	v_lshl_add_u64 v[140:141], s[30:31], 0, v[70:71]
	s_mov_b32 m0, s42
	s_nop 0
	global_load_lds_dwordx4 v[140:141], off
	v_lshl_add_u64 v[140:141], s[36:37], 0, v[64:65]
	s_mov_b32 m0, s40
	s_nop 0
	global_load_lds_dwordx4 v[140:141], off
	s_mov_b32 m0, s43
	s_nop 0
	global_load_lds_dwordx4 v[142:143], off
	s_waitcnt vmcnt(8)
	s_waitcnt lgkmcnt(0)
	s_setprio 1
	s_barrier
	s_waitcnt lgkmcnt(0)
	v_mfma_f32_16x16x32_bf16 v[28:31], v[88:91], v[104:107], v[28:31]
	v_mfma_f32_16x16x32_bf16 v[28:31], v[92:95], v[108:111], v[28:31]
	v_mfma_f32_16x16x32_bf16 v[24:27], v[100:103], v[108:111], v[24:27]
	v_mfma_f32_16x16x32_bf16 v[24:27], v[96:99], v[104:107], v[24:27]
	v_mfma_f32_16x16x32_bf16 v[16:19], v[96:99], v[112:115], v[16:19]
	v_mfma_f32_16x16x32_bf16 v[16:19], v[100:103], v[116:119], v[16:19]
	v_mfma_f32_16x16x32_bf16 v[20:23], v[92:95], v[116:119], v[20:23]
	v_mfma_f32_16x16x32_bf16 v[20:23], v[88:91], v[112:115], v[20:23]
	v_mfma_f32_16x16x32_bf16 v[12:15], v[88:91], v[120:123], v[12:15]
	v_mfma_f32_16x16x32_bf16 v[12:15], v[92:95], v[124:127], v[12:15]
	v_mfma_f32_16x16x32_bf16 v[8:11], v[100:103], v[124:127], v[8:11]
	v_mfma_f32_16x16x32_bf16 v[8:11], v[96:99], v[120:123], v[8:11]
	v_mfma_f32_16x16x32_bf16 v[0:3], v[96:99], v[128:131], v[0:3]
	v_mfma_f32_16x16x32_bf16 v[0:3], v[100:103], v[132:135], v[0:3]
	v_mfma_f32_16x16x32_bf16 v[4:7], v[92:95], v[132:135], v[4:7]
	v_mfma_f32_16x16x32_bf16 v[4:7], v[88:91], v[128:131], v[4:7]
	s_setprio 0
	s_setprio 1
	s_setprio 0
	s_barrier
; #define PG8_STAGE(bufoff, gbase, voff) do { _Pragma("unroll") for (int _i = 0; _i < 2; ++_i) \
;         __builtin_amdgcn_global_load_lds((const unsigned*)((const char*)(gbase) + (voff)[_i]), (LAS unsigned*)(lds + (bufoff) + ldsw + _i * 8192), 16, 0, 0); } while (0)
; #define PG8_LDA(dst, b, h) do { _Pragma("unroll") for (int m = 0; m < 4; ++m) _Pragma("unroll") for (int k = 0; k < 2; ++k) dst[m][k] = *(const LAS bf16x8*)(lds + PG8_SA(b, h) + aoff + m * 2048 + k * 1024); } while (0)
; #define PG8_LDB(dst, b, h) do { _Pragma("unroll") for (int n = 0; n < 2; ++n) _Pragma("unroll") for (int k = 0; k < 2; ++k) dst[n][k] = *(const LAS bf16x8*)(lds + PG8_SB(b, h) + boff + n * 2048 + k * 1024); } while (0)
; #define PG8_MMA(ai, bj, At, Bt) do { __builtin_amdgcn_s_setprio(1); _Pragma("unroll") for (int m = 0; m < 4; ++m) _Pragma("unroll") for (int n = 0; n < 2; ++n) _Pragma("unroll") for (int k = 0; k < 2; ++k) \
;         acc[ai][bj][m][n] = __builtin_amdgcn_mfma_f32_16x16x32_bf16(Bt[n][k], At[m][k], acc[ai][bj][m][n], 0, 0, 0); __builtin_amdgcn_s_setprio(0); } while (0)
; #define PG8_WAIT_V(n) asm volatile("s_waitcnt vmcnt(" #n ")" ::: "memory")
; #define PG8_WAIT_L(n) asm volatile("s_waitcnt lgkmcnt(" #n ")" ::: "memory")
; #define PG8_BAR __builtin_amdgcn_s_barrier()
; #define PG8_SCHED __builtin_amdgcn_sched_barrier(0)
; template <class Epi>
; __device__ __forceinline__ void gemm_phase(LAS unsigned char* lds, const Gemm g, const StaticOrder& S, const Epi& E) {
;     ...
;             PG8_LDB(B0, 1, 0); PG8_LDB(B1, 1, 1); PG8_SCHED; PG8_LDA(At, 1, 0); PG8_STAGE(PG8_SA(0, 1), a2 + hstepA, voffA);
;             PG8_WAIT_V(8); PG8_WAIT_L(0); PG8_BAR; PG8_MMA(0, 0, At, B0); PG8_MMA(0, 1, At, B1); PG8_BAR; PG8_SCHED;
;             PG8_LDA(At, 1, 1); PG8_STAGE(PG8_SB(1, 0), b3, voffB); PG8_STAGE(PG8_SB(1, 1), b3 + hstepB, voffB); PG8_STAGE(PG8_SA(1, 0), a3, voffA);
;             PG8_WAIT_V(8); PG8_WAIT_L(0); PG8_BAR; PG8_MMA(1, 0, At, B0); PG8_MMA(1, 1, At, B1); PG8_BAR; PG8_SCHED;
;         }
	s_add_i32 s62, 0, 0x18000
	v_add_u32_e32 v87, s62, v84
	ds_read_b128 v[88:91], v87
	ds_read_b128 v[92:95], v87 offset:1024
	ds_read_b128 v[96:99], v87 offset:2048
	ds_read_b128 v[100:103], v87 offset:3072
	s_add_u32 s30, s36, 0x18000
	s_addc_u32 s31, s37, 0
	s_mov_b32 m0, s44
	v_lshl_add_u64 v[144:145], s[30:31], 0, v[64:65]
	ds_read_b128 v[104:107], v86 offset:32768
	ds_read_b128 v[108:111], v86 offset:33792
	ds_read_b128 v[112:115], v86 offset:34816
	ds_read_b128 v[116:119], v86 offset:35840
	ds_read_b128 v[120:123], v86 offset:36864
	ds_read_b128 v[124:127], v86 offset:37888
	ds_read_b128 v[128:131], v86 offset:38912
	ds_read_b128 v[132:135], v86 offset:39936
	global_load_lds_dwordx4 v[144:145], off
	v_lshl_add_u64 v[144:145], s[30:31], 0, v[68:69]
	s_mov_b32 m0, s45
	s_nop 0
	global_load_lds_dwordx4 v[144:145], off
	s_waitcnt vmcnt(8)
	s_waitcnt lgkmcnt(0)
	s_setprio 1
	s_barrier
	s_waitcnt lgkmcnt(0)
	v_mfma_f32_16x16x32_bf16 v[60:63], v[88:91], v[104:107], v[60:63]
	v_mfma_f32_16x16x32_bf16 v[60:63], v[92:95], v[108:111], v[60:63]
	v_mfma_f32_16x16x32_bf16 v[56:59], v[100:103], v[108:111], v[56:59]
	v_mfma_f32_16x16x32_bf16 v[56:59], v[96:99], v[104:107], v[56:59]
	v_mfma_f32_16x16x32_bf16 v[48:51], v[96:99], v[112:115], v[48:51]
	v_mfma_f32_16x16x32_bf16 v[48:51], v[100:103], v[116:119], v[48:51]
	v_mfma_f32_16x16x32_bf16 v[52:55], v[92:95], v[116:119], v[52:55]
	v_mfma_f32_16x16x32_bf16 v[52:55], v[88:91], v[112:115], v[52:55]
	v_mfma_f32_16x16x32_bf16 v[44:47], v[88:91], v[120:123], v[44:47]
	v_mfma_f32_16x16x32_bf16 v[44:47], v[92:95], v[124:127], v[44:47]
	v_mfma_f32_16x16x32_bf16 v[40:43], v[100:103], v[124:127], v[40:43]
	v_mfma_f32_16x16x32_bf16 v[40:43], v[96:99], v[120:123], v[40:43]
	v_mfma_f32_16x16x32_bf16 v[32:35], v[96:99], v[128:131], v[32:35]
	v_mfma_f32_16x16x32_bf16 v[32:35], v[100:103], v[132:135], v[32:35]
	v_mfma_f32_16x16x32_bf16 v[36:39], v[92:95], v[132:135], v[36:39]
	v_mfma_f32_16x16x32_bf16 v[36:39], v[88:91], v[128:131], v[36:39]
	s_setprio 0
	s_setprio 1
	s_setprio 0
	s_barrier
	s_add_i32 s30, s62, s39
	v_lshl_add_u64 v[136:137], v[136:137], 0, s[10:11]
	s_mov_b32 m0, s30
	ds_read_b128 v[104:107], v86 offset:49152
	ds_read_b128 v[108:111], v86 offset:50176
	ds_read_b128 v[112:115], v86 offset:51200
	ds_read_b128 v[116:119], v86 offset:52224
	ds_read_b128 v[120:123], v86 offset:53248
	ds_read_b128 v[124:127], v86 offset:54272
	ds_read_b128 v[128:131], v86 offset:55296
	ds_read_b128 v[132:135], v86 offset:56320
	global_load_lds_dwordx4 v[136:137], off
	s_add_i32 m0, s30, 0x2000
	s_add_u32 s30, s34, 0x10080
	v_lshl_add_u64 v[136:137], v[138:139], 0, s[10:11]
	s_addc_u32 s31, s35, 0
	global_load_lds_dwordx4 v[136:137], off
	v_lshl_add_u64 v[136:137], s[30:31], 0, v[66:67]
	s_mov_b32 m0, s49
	s_nop 0
	global_load_lds_dwordx4 v[136:137], off
	v_lshl_add_u64 v[136:137], s[30:31], 0, v[70:71]
	s_mov_b32 m0, s52
	s_nop 0
	global_load_lds_dwordx4 v[136:137], off
	v_lshl_add_u64 v[136:137], v[140:141], 0, s[10:11]
	s_mov_b32 m0, s47
	s_nop 0
	global_load_lds_dwordx4 v[136:137], off
	v_lshl_add_u64 v[136:137], v[142:143], 0, s[10:11]
	s_mov_b32 m0, s48
	s_nop 0
	global_load_lds_dwordx4 v[136:137], off
	s_waitcnt vmcnt(8)
	s_waitcnt lgkmcnt(0)
	s_setprio 1
	s_barrier
	s_waitcnt lgkmcnt(0)
	v_mfma_f32_16x16x32_bf16 v[28:31], v[88:91], v[104:107], v[28:31]
	v_mfma_f32_16x16x32_bf16 v[28:31], v[92:95], v[108:111], v[28:31]
	v_mfma_f32_16x16x32_bf16 v[24:27], v[100:103], v[108:111], v[24:27]
	v_mfma_f32_16x16x32_bf16 v[24:27], v[96:99], v[104:107], v[24:27]
	v_mfma_f32_16x16x32_bf16 v[16:19], v[96:99], v[112:115], v[16:19]
	v_mfma_f32_16x16x32_bf16 v[16:19], v[100:103], v[116:119], v[16:19]
	v_mfma_f32_16x16x32_bf16 v[20:23], v[92:95], v[116:119], v[20:23]
	v_mfma_f32_16x16x32_bf16 v[20:23], v[88:91], v[112:115], v[20:23]
	v_mfma_f32_16x16x32_bf16 v[12:15], v[88:91], v[120:123], v[12:15]
	v_mfma_f32_16x16x32_bf16 v[12:15], v[92:95], v[124:127], v[12:15]
	v_mfma_f32_16x16x32_bf16 v[8:11], v[100:103], v[124:127], v[8:11]
	v_mfma_f32_16x16x32_bf16 v[8:11], v[96:99], v[120:123], v[8:11]
	v_mfma_f32_16x16x32_bf16 v[0:3], v[96:99], v[128:131], v[0:3]
	v_mfma_f32_16x16x32_bf16 v[0:3], v[100:103], v[132:135], v[0:3]
	v_mfma_f32_16x16x32_bf16 v[4:7], v[92:95], v[132:135], v[4:7]
	v_mfma_f32_16x16x32_bf16 v[4:7], v[88:91], v[128:131], v[4:7]
	s_setprio 0
	s_setprio 1
	s_setprio 0
	s_barrier
	s_add_u32 s59, s59, 0x100
	s_addc_u32 s60, s60, 0
	s_cmp_ge_i32 s61, s46
	s_mov_b64 s[30:31], s[8:9]
	s_mov_b32 s34, s61
	s_cbranch_scc0 .LBB0_685

; #define PG8_STAGE(bufoff, gbase, voff) do { _Pragma("unroll") for (int _i = 0; _i < 2; ++_i) \
;         __builtin_amdgcn_global_load_lds((const unsigned*)((const char*)(gbase) + (voff)[_i]), (LAS unsigned*)(lds + (bufoff) + ldsw + _i * 8192), 16, 0, 0); } while (0)
; #define PG8_LDA(dst, b, h) do { _Pragma("unroll") for (int m = 0; m < 4; ++m) _Pragma("unroll") for (int k = 0; k < 2; ++k) dst[m][k] = *(const LAS bf16x8*)(lds + PG8_SA(b, h) + aoff + m * 2048 + k * 1024); } while (0)
; #define PG8_LDB(dst, b, h) do { _Pragma("unroll") for (int n = 0; n < 2; ++n) _Pragma("unroll") for (int k = 0; k < 2; ++k) dst[n][k] = *(const LAS bf16x8*)(lds + PG8_SB(b, h) + boff + n * 2048 + k * 1024); } while (0)
; #define PG8_MMA(ai, bj, At, Bt) do { __builtin_amdgcn_s_setprio(1); _Pragma("unroll") for (int m = 0; m < 4; ++m) _Pragma("unroll") for (int n = 0; n < 2; ++n) _Pragma("unroll") for (int k = 0; k < 2; ++k) \
;         acc[ai][bj][m][n] = __builtin_amdgcn_mfma_f32_16x16x32_bf16(Bt[n][k], At[m][k], acc[ai][bj][m][n], 0, 0, 0); __builtin_amdgcn_s_setprio(0); } while (0)
; #define PG8_WAIT_V(n) asm volatile("s_waitcnt vmcnt(" #n ")" ::: "memory")
; #define PG8_WAIT_L(n) asm volatile("s_waitcnt lgkmcnt(" #n ")" ::: "memory")
; #define PG8_BAR __builtin_amdgcn_s_barrier()
; #define PG8_SCHED __builtin_amdgcn_sched_barrier(0)
; template <class Epi>
; __device__ __forceinline__ void gemm_phase(LAS unsigned char* lds, const Gemm g, const StaticOrder& S, const Epi& E) {
;     ...
;             const bool last = (t == nt - 2);
;             const char* a1 = cA + (size_t)(t + 1) * kstep;
;             const char* a2 = last ? nA : cA + (size_t)(t + 2) * kstep; const char* b2 = last ? nB : cB + (size_t)(t + 2) * kstep;
;             const char* a3 = a2 + kstep; const char* b3 = b2 + kstep;
;             PG8_LDB(B0, 0, 0); PG8_LDB(B1, 0, 1); PG8_SCHED; PG8_LDA(At, 0, 0); PG8_STAGE(PG8_SA(1, 1), a1 + hstepA, voffA);
;             PG8_WAIT_V(8); PG8_WAIT_L(0); PG8_BAR; PG8_MMA(0, 0, At, B0); PG8_MMA(0, 1, At, B1); PG8_BAR; PG8_SCHED;
;             PG8_LDA(At, 0, 1); PG8_STAGE(PG8_SB(0, 0), b2, voffB); PG8_STAGE(PG8_SB(0, 1), b2 + hstepB, voffB); PG8_STAGE(PG8_SA(0, 0), a2, voffA);
;             PG8_WAIT_V(8); PG8_WAIT_L(0); PG8_BAR; PG8_MMA(1, 0, At, B0); PG8_MMA(1, 1, At, B1); PG8_BAR; PG8_SCHED;
.LBB0_834:
	ds_read_b128 v[156:159], v152
	ds_read_b128 v[160:163], v152 offset:1024
	ds_read_b128 v[164:167], v152 offset:2048
	ds_read_b128 v[168:171], v152 offset:3072
	ds_read_b128 v[172:175], v153
	ds_read_b128 v[176:179], v153 offset:1024
	ds_read_b128 v[180:183], v153 offset:2048
	ds_read_b128 v[184:187], v153 offset:3072
	s_add_i32 s49, s22, 2
	s_add_u32 s4, s0, 0x100
	s_addc_u32 s5, s1, 0
	s_cmp_eq_u32 s40, s22
	s_cselect_b32 s22, s20, s47
	s_cselect_b32 s25, s11, s5
	s_cselect_b32 s24, s10, s4
	s_cselect_b32 s23, s21, s48
	v_lshl_add_u64 v[224:225], s[0:1], 0, v[138:139]
	s_add_i32 m0, s29, 0xc000
	ds_read_b128 v[188:191], v154
	ds_read_b128 v[192:195], v154 offset:1024
	ds_read_b128 v[196:199], v154 offset:2048
	ds_read_b128 v[200:203], v154 offset:3072
	ds_read_b128 v[208:211], v154 offset:4096
	ds_read_b128 v[212:215], v154 offset:5120
	ds_read_b128 v[216:219], v154 offset:6144
	ds_read_b128 v[220:223], v154 offset:7168
	global_load_lds_dwordx4 v[224:225], off
	v_lshl_add_u64 v[224:225], s[0:1], 0, v[140:141]
	s_add_i32 m0, s29, 0xe000
	s_nop 0
	global_load_lds_dwordx4 v[224:225], off
	s_waitcnt vmcnt(8)
	s_waitcnt lgkmcnt(0)
	s_setprio 1
	s_barrier
	s_waitcnt lgkmcnt(0)
	v_mfma_f32_16x16x32_bf16 v[124:127], v[156:159], v[188:191], v[124:127]
	v_mfma_f32_16x16x32_bf16 v[124:127], v[160:163], v[192:195], v[124:127]
	v_mfma_f32_16x16x32_bf16 v[120:123], v[168:171], v[192:195], v[120:123]
	v_mfma_f32_16x16x32_bf16 v[120:123], v[164:167], v[188:191], v[120:123]
	v_mfma_f32_16x16x32_bf16 v[116:119], v[172:175], v[188:191], v[116:119]
	v_mfma_f32_16x16x32_bf16 v[116:119], v[176:179], v[192:195], v[116:119]
	v_mfma_f32_16x16x32_bf16 v[112:115], v[184:187], v[192:195], v[112:115]
	v_mfma_f32_16x16x32_bf16 v[112:115], v[180:183], v[188:191], v[112:115]
	v_mfma_f32_16x16x32_bf16 v[96:99], v[180:183], v[196:199], v[96:99]
	v_mfma_f32_16x16x32_bf16 v[96:99], v[184:187], v[200:203], v[96:99]
	v_mfma_f32_16x16x32_bf16 v[100:103], v[176:179], v[200:203], v[100:103]
	v_mfma_f32_16x16x32_bf16 v[100:103], v[172:175], v[196:199], v[100:103]
	v_mfma_f32_16x16x32_bf16 v[104:107], v[164:167], v[196:199], v[104:107]
	v_mfma_f32_16x16x32_bf16 v[104:107], v[168:171], v[200:203], v[104:107]
	v_mfma_f32_16x16x32_bf16 v[108:111], v[160:163], v[200:203], v[108:111]
	v_mfma_f32_16x16x32_bf16 v[108:111], v[156:159], v[196:199], v[108:111]
	s_setprio 0
	s_setprio 1
	v_mfma_f32_16x16x32_bf16 v[92:95], v[156:159], v[208:211], v[92:95]
	v_mfma_f32_16x16x32_bf16 v[92:95], v[160:163], v[212:215], v[92:95]
	v_mfma_f32_16x16x32_bf16 v[88:91], v[168:171], v[212:215], v[88:91]
	v_mfma_f32_16x16x32_bf16 v[88:91], v[164:167], v[208:211], v[88:91]
	v_mfma_f32_16x16x32_bf16 v[84:87], v[172:175], v[208:211], v[84:87]
	v_mfma_f32_16x16x32_bf16 v[84:87], v[176:179], v[212:215], v[84:87]
	v_mfma_f32_16x16x32_bf16 v[80:83], v[184:187], v[212:215], v[80:83]
	v_mfma_f32_16x16x32_bf16 v[80:83], v[180:183], v[208:211], v[80:83]
	v_mfma_f32_16x16x32_bf16 v[64:67], v[180:183], v[216:219], v[64:67]
	v_mfma_f32_16x16x32_bf16 v[64:67], v[184:187], v[220:223], v[64:67]
	v_mfma_f32_16x16x32_bf16 v[68:71], v[176:179], v[220:223], v[68:71]
	v_mfma_f32_16x16x32_bf16 v[68:71], v[172:175], v[216:219], v[68:71]
	v_mfma_f32_16x16x32_bf16 v[72:75], v[164:167], v[216:219], v[72:75]
	v_mfma_f32_16x16x32_bf16 v[72:75], v[168:171], v[220:223], v[72:75]
	v_mfma_f32_16x16x32_bf16 v[76:79], v[160:163], v[220:223], v[76:79]
	v_mfma_f32_16x16x32_bf16 v[76:79], v[156:159], v[216:219], v[76:79]
	s_setprio 0
	s_barrier
	s_add_i32 s0, s43, s28
	v_lshl_add_u64 v[224:225], s[22:23], 0, v[130:131]
	s_mov_b32 m0, s0
	ds_read_b128 v[188:191], v154 offset:16384
	ds_read_b128 v[192:195], v154 offset:17408
	ds_read_b128 v[196:199], v154 offset:18432
	ds_read_b128 v[200:203], v154 offset:19456
	ds_read_b128 v[208:211], v154 offset:20480
	ds_read_b128 v[212:215], v154 offset:21504
	ds_read_b128 v[216:219], v154 offset:22528
	ds_read_b128 v[220:223], v154 offset:23552
	global_load_lds_dwordx4 v[224:225], off
	s_add_i32 m0, s0, 0x2000
	s_add_u32 s0, s22, 0x18000
	v_lshl_add_u64 v[226:227], s[22:23], 0, v[134:135]
	s_addc_u32 s1, s23, 0
	s_add_i32 s50, s44, s28
	global_load_lds_dwordx4 v[226:227], off
	v_lshl_add_u64 v[230:231], s[0:1], 0, v[130:131]
	s_mov_b32 m0, s50
	v_lshl_add_u64 v[232:233], s[24:25], 0, v[132:133]
	global_load_lds_dwordx4 v[230:231], off
	v_lshl_add_u64 v[230:231], s[0:1], 0, v[134:135]
	s_add_i32 m0, s50, 0x2000
	s_nop 0
	global_load_lds_dwordx4 v[230:231], off
	v_lshl_add_u64 v[230:231], s[24:25], 0, v[128:129]
	s_mov_b32 m0, s29
	s_nop 0
	global_load_lds_dwordx4 v[230:231], off
	s_mov_b32 m0, s30
	s_nop 0
	global_load_lds_dwordx4 v[232:233], off
	s_waitcnt vmcnt(8)
	s_waitcnt lgkmcnt(0)
	s_setprio 1
	s_barrier
; #define PG8_STAGE(bufoff, gbase, voff) do { _Pragma("unroll") for (int _i = 0; _i < 2; ++_i) \
;         __builtin_amdgcn_global_load_lds((const unsigned*)((const char*)(gbase) + (voff)[_i]), (LAS unsigned*)(lds + (bufoff) + ldsw + _i * 8192), 16, 0, 0); } while (0)
; #define PG8_LDA(dst, b, h) do { _Pragma("unroll") for (int m = 0; m < 4; ++m) _Pragma("unroll") for (int k = 0; k < 2; ++k) dst[m][k] = *(const LAS bf16x8*)(lds + PG8_SA(b, h) + aoff + m * 2048 + k * 1024); } while (0)
; #define PG8_LDB(dst, b, h) do { _Pragma("unroll") for (int n = 0; n < 2; ++n) _Pragma("unroll") for (int k = 0; k < 2; ++k) dst[n][k] = *(const LAS bf16x8*)(lds + PG8_SB(b, h) + boff + n * 2048 + k * 1024); } while (0)
; #define PG8_MMA(ai, bj, At, Bt) do { __builtin_amdgcn_s_setprio(1); _Pragma("unroll") for (int m = 0; m < 4; ++m) _Pragma("unroll") for (int n = 0; n < 2; ++n) _Pragma("unroll") for (int k = 0; k < 2; ++k) \
;         acc[ai][bj][m][n] = __builtin_amdgcn_mfma_f32_16x16x32_bf16(Bt[n][k], At[m][k], acc[ai][bj][m][n], 0, 0, 0); __builtin_amdgcn_s_setprio(0); } while (0)
; #define PG8_WAIT_V(n) asm volatile("s_waitcnt vmcnt(" #n ")" ::: "memory")
; #define PG8_WAIT_L(n) asm volatile("s_waitcnt lgkmcnt(" #n ")" ::: "memory")
; #define PG8_BAR __builtin_amdgcn_s_barrier()
; #define PG8_SCHED __builtin_amdgcn_sched_barrier(0)
; template <class Epi>
; __device__ __forceinline__ void gemm_phase(LAS unsigned char* lds, const Gemm g, const StaticOrder& S, const Epi& E) {
;     ...
;             PG8_WAIT_V(8); PG8_WAIT_L(0); PG8_BAR; PG8_MMA(1, 0, At, B0); PG8_MMA(1, 1, At, B1); PG8_BAR; PG8_SCHED;
;             PG8_LDB(B0, 1, 0); PG8_LDB(B1, 1, 1); PG8_SCHED; PG8_LDA(At, 1, 0); PG8_STAGE(PG8_SA(0, 1), a2 + hstepA, voffA);
;             PG8_WAIT_V(8); PG8_WAIT_L(0); PG8_BAR; PG8_MMA(0, 0, At, B0); PG8_MMA(0, 1, At, B1); PG8_BAR; PG8_SCHED;
	s_waitcnt lgkmcnt(0)
	v_mfma_f32_16x16x32_bf16 v[60:63], v[156:159], v[188:191], v[60:63]
	v_mfma_f32_16x16x32_bf16 v[60:63], v[160:163], v[192:195], v[60:63]
	v_mfma_f32_16x16x32_bf16 v[56:59], v[168:171], v[192:195], v[56:59]
	v_mfma_f32_16x16x32_bf16 v[56:59], v[164:167], v[188:191], v[56:59]
	v_mfma_f32_16x16x32_bf16 v[52:55], v[172:175], v[188:191], v[52:55]
	v_mfma_f32_16x16x32_bf16 v[52:55], v[176:179], v[192:195], v[52:55]
	v_mfma_f32_16x16x32_bf16 v[48:51], v[184:187], v[192:195], v[48:51]
	v_mfma_f32_16x16x32_bf16 v[48:51], v[180:183], v[188:191], v[48:51]
	v_mfma_f32_16x16x32_bf16 v[32:35], v[180:183], v[196:199], v[32:35]
	v_mfma_f32_16x16x32_bf16 v[32:35], v[184:187], v[200:203], v[32:35]
	v_mfma_f32_16x16x32_bf16 v[36:39], v[176:179], v[200:203], v[36:39]
	v_mfma_f32_16x16x32_bf16 v[36:39], v[172:175], v[196:199], v[36:39]
	v_mfma_f32_16x16x32_bf16 v[40:43], v[164:167], v[196:199], v[40:43]
	v_mfma_f32_16x16x32_bf16 v[40:43], v[168:171], v[200:203], v[40:43]
	v_mfma_f32_16x16x32_bf16 v[44:47], v[160:163], v[200:203], v[44:47]
	v_mfma_f32_16x16x32_bf16 v[44:47], v[156:159], v[196:199], v[44:47]
	s_setprio 0
	s_setprio 1
	v_mfma_f32_16x16x32_bf16 v[28:31], v[156:159], v[208:211], v[28:31]
	v_mfma_f32_16x16x32_bf16 v[28:31], v[160:163], v[212:215], v[28:31]
	v_mfma_f32_16x16x32_bf16 v[24:27], v[168:171], v[212:215], v[24:27]
	v_mfma_f32_16x16x32_bf16 v[24:27], v[164:167], v[208:211], v[24:27]
	v_mfma_f32_16x16x32_bf16 v[20:23], v[172:175], v[208:211], v[20:23]
	v_mfma_f32_16x16x32_bf16 v[20:23], v[176:179], v[212:215], v[20:23]
	v_mfma_f32_16x16x32_bf16 v[16:19], v[184:187], v[212:215], v[16:19]
	v_mfma_f32_16x16x32_bf16 v[16:19], v[180:183], v[208:211], v[16:19]
	v_mfma_f32_16x16x32_bf16 v[0:3], v[180:183], v[216:219], v[0:3]
	v_mfma_f32_16x16x32_bf16 v[0:3], v[184:187], v[220:223], v[0:3]
	v_mfma_f32_16x16x32_bf16 v[4:7], v[176:179], v[220:223], v[4:7]
	v_mfma_f32_16x16x32_bf16 v[4:7], v[172:175], v[216:219], v[4:7]
	v_mfma_f32_16x16x32_bf16 v[8:11], v[164:167], v[216:219], v[8:11]
	v_mfma_f32_16x16x32_bf16 v[8:11], v[168:171], v[220:223], v[8:11]
	v_mfma_f32_16x16x32_bf16 v[12:15], v[160:163], v[220:223], v[12:15]
	v_mfma_f32_16x16x32_bf16 v[12:15], v[156:159], v[216:219], v[12:15]
	s_setprio 0
	s_barrier
	s_add_i32 s50, 0, 0x18000
	v_add_u32_e32 v136, s50, v149
	s_add_i32 s51, 0, 0x1c000
	ds_read_b128 v[156:159], v136
	ds_read_b128 v[160:163], v136 offset:1024
	ds_read_b128 v[164:167], v136 offset:2048
	ds_read_b128 v[168:171], v136 offset:3072
	v_add_u32_e32 v136, s51, v149
	ds_read_b128 v[172:175], v136
	ds_read_b128 v[176:179], v136 offset:1024
	ds_read_b128 v[180:183], v136 offset:2048
	ds_read_b128 v[184:187], v136 offset:3072
	s_add_u32 s0, s24, 0x18000
	s_addc_u32 s1, s25, 0
	s_mov_b32 m0, s31
	v_lshl_add_u64 v[234:235], s[0:1], 0, v[128:129]
	ds_read_b128 v[188:191], v154 offset:32768
	ds_read_b128 v[192:195], v154 offset:33792
	ds_read_b128 v[196:199], v154 offset:34816
	ds_read_b128 v[200:203], v154 offset:35840
	ds_read_b128 v[208:211], v154 offset:36864
	ds_read_b128 v[212:215], v154 offset:37888
	ds_read_b128 v[216:219], v154 offset:38912
	ds_read_b128 v[220:223], v154 offset:39936
	global_load_lds_dwordx4 v[234:235], off
	v_lshl_add_u64 v[234:235], s[0:1], 0, v[132:133]
	s_mov_b32 m0, s34
	s_nop 0
	global_load_lds_dwordx4 v[234:235], off
	s_waitcnt vmcnt(8)
	s_waitcnt lgkmcnt(0)
	s_setprio 1
	s_barrier
	s_waitcnt lgkmcnt(0)
	v_mfma_f32_16x16x32_bf16 v[124:127], v[156:159], v[188:191], v[124:127]
	v_mfma_f32_16x16x32_bf16 v[124:127], v[160:163], v[192:195], v[124:127]
	v_mfma_f32_16x16x32_bf16 v[120:123], v[168:171], v[192:195], v[120:123]
	v_mfma_f32_16x16x32_bf16 v[120:123], v[164:167], v[188:191], v[120:123]
	v_mfma_f32_16x16x32_bf16 v[116:119], v[172:175], v[188:191], v[116:119]
	v_mfma_f32_16x16x32_bf16 v[116:119], v[176:179], v[192:195], v[116:119]
	v_mfma_f32_16x16x32_bf16 v[112:115], v[184:187], v[192:195], v[112:115]
	v_mfma_f32_16x16x32_bf16 v[112:115], v[180:183], v[188:191], v[112:115]
	v_mfma_f32_16x16x32_bf16 v[96:99], v[180:183], v[196:199], v[96:99]
	v_mfma_f32_16x16x32_bf16 v[96:99], v[184:187], v[200:203], v[96:99]
	v_mfma_f32_16x16x32_bf16 v[100:103], v[176:179], v[200:203], v[100:103]
	v_mfma_f32_16x16x32_bf16 v[100:103], v[172:175], v[196:199], v[100:103]
	v_mfma_f32_16x16x32_bf16 v[104:107], v[164:167], v[196:199], v[104:107]
	v_mfma_f32_16x16x32_bf16 v[104:107], v[168:171], v[200:203], v[104:107]
	v_mfma_f32_16x16x32_bf16 v[108:111], v[160:163], v[200:203], v[108:111]
	v_mfma_f32_16x16x32_bf16 v[108:111], v[156:159], v[196:199], v[108:111]
	s_setprio 0
	s_setprio 1
	v_mfma_f32_16x16x32_bf16 v[92:95], v[156:159], v[208:211], v[92:95]
	v_mfma_f32_16x16x32_bf16 v[92:95], v[160:163], v[212:215], v[92:95]
	v_mfma_f32_16x16x32_bf16 v[88:91], v[168:171], v[212:215], v[88:91]
	v_mfma_f32_16x16x32_bf16 v[88:91], v[164:167], v[208:211], v[88:91]
	v_mfma_f32_16x16x32_bf16 v[84:87], v[172:175], v[208:211], v[84:87]
	v_mfma_f32_16x16x32_bf16 v[84:87], v[176:179], v[212:215], v[84:87]
	v_mfma_f32_16x16x32_bf16 v[80:83], v[184:187], v[212:215], v[80:83]
	v_mfma_f32_16x16x32_bf16 v[80:83], v[180:183], v[208:211], v[80:83]
	v_mfma_f32_16x16x32_bf16 v[64:67], v[180:183], v[216:219], v[64:67]
	v_mfma_f32_16x16x32_bf16 v[64:67], v[184:187], v[220:223], v[64:67]
	v_mfma_f32_16x16x32_bf16 v[68:71], v[176:179], v[220:223], v[68:71]
	v_mfma_f32_16x16x32_bf16 v[68:71], v[172:175], v[216:219], v[68:71]
	v_mfma_f32_16x16x32_bf16 v[72:75], v[164:167], v[216:219], v[72:75]
	v_mfma_f32_16x16x32_bf16 v[72:75], v[168:171], v[220:223], v[72:75]
	v_mfma_f32_16x16x32_bf16 v[76:79], v[160:163], v[220:223], v[76:79]
	v_mfma_f32_16x16x32_bf16 v[76:79], v[156:159], v[216:219], v[76:79]
	s_setprio 0
	s_barrier
; #define PG8_STAGE(bufoff, gbase, voff) do { _Pragma("unroll") for (int _i = 0; _i < 2; ++_i) \
;         __builtin_amdgcn_global_load_lds((const unsigned*)((const char*)(gbase) + (voff)[_i]), (LAS unsigned*)(lds + (bufoff) + ldsw + _i * 8192), 16, 0, 0); } while (0)
; #define PG8_LDA(dst, b, h) do { _Pragma("unroll") for (int m = 0; m < 4; ++m) _Pragma("unroll") for (int k = 0; k < 2; ++k) dst[m][k] = *(const LAS bf16x8*)(lds + PG8_SA(b, h) + aoff + m * 2048 + k * 1024); } while (0)
; #define PG8_MMA(ai, bj, At, Bt) do { __builtin_amdgcn_s_setprio(1); _Pragma("unroll") for (int m = 0; m < 4; ++m) _Pragma("unroll") for (int n = 0; n < 2; ++n) _Pragma("unroll") for (int k = 0; k < 2; ++k) \
;         acc[ai][bj][m][n] = __builtin_amdgcn_mfma_f32_16x16x32_bf16(Bt[n][k], At[m][k], acc[ai][bj][m][n], 0, 0, 0); __builtin_amdgcn_s_setprio(0); } while (0)
; #define PG8_WAIT_V(n) asm volatile("s_waitcnt vmcnt(" #n ")" ::: "memory")
; #define PG8_WAIT_L(n) asm volatile("s_waitcnt lgkmcnt(" #n ")" ::: "memory")
; #define PG8_BAR __builtin_amdgcn_s_barrier()
; #define PG8_SCHED __builtin_amdgcn_sched_barrier(0)
; template <class Epi>
; __device__ __forceinline__ void gemm_phase(LAS unsigned char* lds, const Gemm g, const StaticOrder& S, const Epi& E) {
;     ...
;             PG8_LDA(At, 1, 1); PG8_STAGE(PG8_SB(1, 0), b3, voffB); PG8_STAGE(PG8_SB(1, 1), b3 + hstepB, voffB); PG8_STAGE(PG8_SA(1, 0), a3, voffA);
;             PG8_WAIT_V(8); PG8_WAIT_L(0); PG8_BAR; PG8_MMA(1, 0, At, B0); PG8_MMA(1, 1, At, B1); PG8_BAR; PG8_SCHED;
;         }
	s_add_i32 s0, s50, s28
	v_lshl_add_u64 v[224:225], v[224:225], 0, s[14:15]
	s_mov_b32 m0, s0
	ds_read_b128 v[188:191], v154 offset:49152
	ds_read_b128 v[192:195], v154 offset:50176
	ds_read_b128 v[196:199], v154 offset:51200
	ds_read_b128 v[200:203], v154 offset:52224
	ds_read_b128 v[208:211], v154 offset:53248
	ds_read_b128 v[212:215], v154 offset:54272
	ds_read_b128 v[216:219], v154 offset:55296
	ds_read_b128 v[220:223], v154 offset:56320
	global_load_lds_dwordx4 v[224:225], off
	s_add_i32 m0, s0, 0x2000
	s_add_u32 s0, s22, 0x18080
	v_lshl_add_u64 v[224:225], v[226:227], 0, s[14:15]
	s_addc_u32 s1, s23, 0
	s_add_i32 s22, s51, s28
	global_load_lds_dwordx4 v[224:225], off
	v_lshl_add_u64 v[224:225], s[0:1], 0, v[130:131]
	s_mov_b32 m0, s22
	s_nop 0
	global_load_lds_dwordx4 v[224:225], off
	v_lshl_add_u64 v[224:225], s[0:1], 0, v[134:135]
	s_add_i32 m0, s22, 0x2000
	s_nop 0
	global_load_lds_dwordx4 v[224:225], off
	v_lshl_add_u64 v[224:225], v[230:231], 0, s[14:15]
	s_mov_b32 m0, s38
	s_nop 0
	global_load_lds_dwordx4 v[224:225], off
	v_lshl_add_u64 v[224:225], v[232:233], 0, s[14:15]
	s_mov_b32 m0, s39
	s_nop 0
	global_load_lds_dwordx4 v[224:225], off
	s_waitcnt vmcnt(8)
	s_waitcnt lgkmcnt(0)
	s_setprio 1
	s_barrier
	s_waitcnt lgkmcnt(0)
	v_mfma_f32_16x16x32_bf16 v[60:63], v[156:159], v[188:191], v[60:63]
	v_mfma_f32_16x16x32_bf16 v[60:63], v[160:163], v[192:195], v[60:63]
	v_mfma_f32_16x16x32_bf16 v[56:59], v[168:171], v[192:195], v[56:59]
	v_mfma_f32_16x16x32_bf16 v[56:59], v[164:167], v[188:191], v[56:59]
	v_mfma_f32_16x16x32_bf16 v[52:55], v[172:175], v[188:191], v[52:55]
	v_mfma_f32_16x16x32_bf16 v[52:55], v[176:179], v[192:195], v[52:55]
	v_mfma_f32_16x16x32_bf16 v[48:51], v[184:187], v[192:195], v[48:51]
	v_mfma_f32_16x16x32_bf16 v[48:51], v[180:183], v[188:191], v[48:51]
	v_mfma_f32_16x16x32_bf16 v[32:35], v[180:183], v[196:199], v[32:35]
	v_mfma_f32_16x16x32_bf16 v[32:35], v[184:187], v[200:203], v[32:35]
	v_mfma_f32_16x16x32_bf16 v[36:39], v[176:179], v[200:203], v[36:39]
	v_mfma_f32_16x16x32_bf16 v[36:39], v[172:175], v[196:199], v[36:39]
	v_mfma_f32_16x16x32_bf16 v[40:43], v[164:167], v[196:199], v[40:43]
	v_mfma_f32_16x16x32_bf16 v[40:43], v[168:171], v[200:203], v[40:43]
	v_mfma_f32_16x16x32_bf16 v[44:47], v[160:163], v[200:203], v[44:47]
	v_mfma_f32_16x16x32_bf16 v[44:47], v[156:159], v[196:199], v[44:47]
	s_setprio 0
	s_setprio 1
	v_mfma_f32_16x16x32_bf16 v[28:31], v[156:159], v[208:211], v[28:31]
	v_mfma_f32_16x16x32_bf16 v[28:31], v[160:163], v[212:215], v[28:31]
	v_mfma_f32_16x16x32_bf16 v[24:27], v[168:171], v[212:215], v[24:27]
	v_mfma_f32_16x16x32_bf16 v[24:27], v[164:167], v[208:211], v[24:27]
	v_mfma_f32_16x16x32_bf16 v[20:23], v[172:175], v[208:211], v[20:23]
	v_mfma_f32_16x16x32_bf16 v[20:23], v[176:179], v[212:215], v[20:23]
	v_mfma_f32_16x16x32_bf16 v[16:19], v[184:187], v[212:215], v[16:19]
	v_mfma_f32_16x16x32_bf16 v[16:19], v[180:183], v[208:211], v[16:19]
	v_mfma_f32_16x16x32_bf16 v[0:3], v[180:183], v[216:219], v[0:3]
	v_mfma_f32_16x16x32_bf16 v[0:3], v[184:187], v[220:223], v[0:3]
	v_mfma_f32_16x16x32_bf16 v[4:7], v[176:179], v[220:223], v[4:7]
	v_mfma_f32_16x16x32_bf16 v[4:7], v[172:175], v[216:219], v[4:7]
	v_mfma_f32_16x16x32_bf16 v[8:11], v[164:167], v[216:219], v[8:11]
	v_mfma_f32_16x16x32_bf16 v[8:11], v[168:171], v[220:223], v[8:11]
	v_mfma_f32_16x16x32_bf16 v[12:15], v[160:163], v[220:223], v[12:15]
	v_mfma_f32_16x16x32_bf16 v[12:15], v[156:159], v[216:219], v[12:15]
	s_setprio 0
	s_barrier
	s_add_u32 s47, s47, 0x100
	s_addc_u32 s48, s48, 0
	s_cmp_ge_i32 s49, s36
	s_mov_b64 s[0:1], s[4:5]
	s_mov_b32 s22, s49
	s_cbranch_scc0 .LBB0_834

; #define PG8_STAGE(bufoff, gbase, voff) do { _Pragma("unroll") for (int _i = 0; _i < 2; ++_i) \
;         __builtin_amdgcn_global_load_lds((const unsigned*)((const char*)(gbase) + (voff)[_i]), (LAS unsigned*)(lds + (bufoff) + ldsw + _i * 8192), 16, 0, 0); } while (0)
; #define PG8_LDA(dst, b, h) do { _Pragma("unroll") for (int m = 0; m < 4; ++m) _Pragma("unroll") for (int k = 0; k < 2; ++k) dst[m][k] = *(const LAS bf16x8*)(lds + PG8_SA(b, h) + aoff + m * 2048 + k * 1024); } while (0)
; #define PG8_LDB(dst, b, h) do { _Pragma("unroll") for (int n = 0; n < 2; ++n) _Pragma("unroll") for (int k = 0; k < 2; ++k) dst[n][k] = *(const LAS bf16x8*)(lds + PG8_SB(b, h) + boff + n * 2048 + k * 1024); } while (0)
; #define PG8_MMA(ai, bj, At, Bt) do { __builtin_amdgcn_s_setprio(1); _Pragma("unroll") for (int m = 0; m < 4; ++m) _Pragma("unroll") for (int n = 0; n < 2; ++n) _Pragma("unroll") for (int k = 0; k < 2; ++k) \
;         acc[ai][bj][m][n] = __builtin_amdgcn_mfma_f32_16x16x32_bf16(Bt[n][k], At[m][k], acc[ai][bj][m][n], 0, 0, 0); __builtin_amdgcn_s_setprio(0); } while (0)
; #define PG8_WAIT_V(n) asm volatile("s_waitcnt vmcnt(" #n ")" ::: "memory")
; #define PG8_WAIT_L(n) asm volatile("s_waitcnt lgkmcnt(" #n ")" ::: "memory")
; #define PG8_BAR __builtin_amdgcn_s_barrier()
; #define PG8_SCHED __builtin_amdgcn_sched_barrier(0)
; template <class Epi>
; __device__ __forceinline__ void gemm_phase(LAS unsigned char* lds, const Gemm g, const StaticOrder& S, const Epi& E) {
;     ...
;             const bool last = (t == nt - 2);
;             const char* a1 = cA + (size_t)(t + 1) * kstep;
;             const char* a2 = last ? nA : cA + (size_t)(t + 2) * kstep; const char* b2 = last ? nB : cB + (size_t)(t + 2) * kstep;
;             const char* a3 = a2 + kstep; const char* b3 = b2 + kstep;
;             PG8_LDB(B0, 0, 0); PG8_LDB(B1, 0, 1); PG8_SCHED; PG8_LDA(At, 0, 0); PG8_STAGE(PG8_SA(1, 1), a1 + hstepA, voffA);
;             PG8_WAIT_V(8); PG8_WAIT_L(0); PG8_BAR; PG8_MMA(0, 0, At, B0); PG8_MMA(0, 1, At, B1); PG8_BAR; PG8_SCHED;
;             PG8_LDA(At, 0, 1); PG8_STAGE(PG8_SB(0, 0), b2, voffB); PG8_STAGE(PG8_SB(0, 1), b2 + hstepB, voffB); PG8_STAGE(PG8_SA(0, 0), a2, voffA);
;             PG8_WAIT_V(8); PG8_WAIT_L(0); PG8_BAR; PG8_MMA(1, 0, At, B0); PG8_MMA(1, 1, At, B1); PG8_BAR; PG8_SCHED;
.LBB0_912:
	ds_read_b128 v[96:99], v230
	ds_read_b128 v[100:103], v230 offset:1024
	ds_read_b128 v[104:107], v230 offset:2048
	ds_read_b128 v[116:119], v230 offset:3072
	ds_read_b128 v[120:123], v231
	ds_read_b128 v[124:127], v231 offset:1024
	ds_read_b128 v[136:139], v231 offset:2048
	ds_read_b128 v[148:151], v231 offset:3072
	s_add_i32 s56, s24, 2
	s_add_u32 s25, s4, 0xfffc0080
	s_addc_u32 s26, s5, -1
	s_cmp_eq_u32 s44, s24
	s_cselect_b32 s24, s53, s54
	s_cselect_b32 s27, s17, s26
	s_cselect_b32 s26, s19, s25
	s_cselect_b32 s25, s33, s55
	v_lshl_add_u64 v[192:193], s[4:5], 0, v[220:221]
	s_add_i32 m0, s31, 0xc000
	ds_read_b128 v[160:163], v232
	ds_read_b128 v[164:167], v232 offset:1024
	ds_read_b128 v[168:171], v232 offset:2048
	ds_read_b128 v[172:175], v232 offset:3072
	ds_read_b128 v[176:179], v232 offset:4096
	ds_read_b128 v[180:183], v232 offset:5120
	ds_read_b128 v[184:187], v232 offset:6144
	ds_read_b128 v[188:191], v232 offset:7168
	global_load_lds_dwordx4 v[192:193], off
	v_lshl_add_u64 v[192:193], s[4:5], 0, v[222:223]
	s_add_i32 m0, s31, 0xe000
	s_nop 0
	global_load_lds_dwordx4 v[192:193], off
	s_waitcnt vmcnt(8)
	s_waitcnt lgkmcnt(0)
	s_setprio 1
	s_barrier
	s_waitcnt lgkmcnt(0)
	v_mfma_f32_16x16x32_bf16 v[156:159], v[96:99], v[160:163], v[156:159]
	v_mfma_f32_16x16x32_bf16 v[156:159], v[100:103], v[164:167], v[156:159]
	v_mfma_f32_16x16x32_bf16 v[152:155], v[116:119], v[164:167], v[152:155]
	v_mfma_f32_16x16x32_bf16 v[152:155], v[104:107], v[160:163], v[152:155]
	v_mfma_f32_16x16x32_bf16 v[144:147], v[120:123], v[160:163], v[144:147]
	v_mfma_f32_16x16x32_bf16 v[144:147], v[124:127], v[164:167], v[144:147]
	v_mfma_f32_16x16x32_bf16 v[140:143], v[148:151], v[164:167], v[140:143]
	v_mfma_f32_16x16x32_bf16 v[140:143], v[136:139], v[160:163], v[140:143]
	v_mfma_f32_16x16x32_bf16 v[108:111], v[136:139], v[168:171], v[108:111]
	v_mfma_f32_16x16x32_bf16 v[108:111], v[148:151], v[172:175], v[108:111]
	v_mfma_f32_16x16x32_bf16 v[112:115], v[124:127], v[172:175], v[112:115]
	v_mfma_f32_16x16x32_bf16 v[112:115], v[120:123], v[168:171], v[112:115]
	v_mfma_f32_16x16x32_bf16 v[128:131], v[104:107], v[168:171], v[128:131]
	v_mfma_f32_16x16x32_bf16 v[128:131], v[116:119], v[172:175], v[128:131]
	v_mfma_f32_16x16x32_bf16 v[132:135], v[100:103], v[172:175], v[132:135]
	v_mfma_f32_16x16x32_bf16 v[132:135], v[96:99], v[168:171], v[132:135]
	s_setprio 0
	s_setprio 1
	v_mfma_f32_16x16x32_bf16 v[92:95], v[96:99], v[176:179], v[92:95]
	v_mfma_f32_16x16x32_bf16 v[92:95], v[100:103], v[180:183], v[92:95]
	v_mfma_f32_16x16x32_bf16 v[88:91], v[116:119], v[180:183], v[88:91]
	v_mfma_f32_16x16x32_bf16 v[88:91], v[104:107], v[176:179], v[88:91]
	v_mfma_f32_16x16x32_bf16 v[84:87], v[120:123], v[176:179], v[84:87]
	v_mfma_f32_16x16x32_bf16 v[84:87], v[124:127], v[180:183], v[84:87]
	v_mfma_f32_16x16x32_bf16 v[80:83], v[148:151], v[180:183], v[80:83]
	v_mfma_f32_16x16x32_bf16 v[80:83], v[136:139], v[176:179], v[80:83]
	v_mfma_f32_16x16x32_bf16 v[64:67], v[136:139], v[184:187], v[64:67]
	v_mfma_f32_16x16x32_bf16 v[64:67], v[148:151], v[188:191], v[64:67]
	v_mfma_f32_16x16x32_bf16 v[68:71], v[124:127], v[188:191], v[68:71]
	v_mfma_f32_16x16x32_bf16 v[68:71], v[120:123], v[184:187], v[68:71]
	v_mfma_f32_16x16x32_bf16 v[72:75], v[104:107], v[184:187], v[72:75]
	v_mfma_f32_16x16x32_bf16 v[72:75], v[116:119], v[188:191], v[72:75]
	v_mfma_f32_16x16x32_bf16 v[76:79], v[100:103], v[188:191], v[76:79]
	v_mfma_f32_16x16x32_bf16 v[76:79], v[96:99], v[184:187], v[76:79]
	s_setprio 0
	s_barrier
	s_add_i32 s57, s47, s30
	v_lshl_add_u64 v[192:193], s[24:25], 0, v[210:211]
	s_mov_b32 m0, s57
	ds_read_b128 v[160:163], v232 offset:16384
	ds_read_b128 v[164:167], v232 offset:17408
	ds_read_b128 v[168:171], v232 offset:18432
	ds_read_b128 v[172:175], v232 offset:19456
	ds_read_b128 v[176:179], v232 offset:20480
	ds_read_b128 v[180:183], v232 offset:21504
	ds_read_b128 v[184:187], v232 offset:22528
	ds_read_b128 v[188:191], v232 offset:23552
	global_load_lds_dwordx4 v[192:193], off
	s_add_i32 m0, s57, 0x2000
	s_add_u32 s58, s24, 0x40000
	v_lshl_add_u64 v[194:195], s[24:25], 0, v[214:215]
	s_addc_u32 s59, s25, 0
	s_add_i32 s57, s48, s30
	global_load_lds_dwordx4 v[194:195], off
	v_lshl_add_u64 v[196:197], s[58:59], 0, v[210:211]
	s_mov_b32 m0, s57
	v_lshl_add_u64 v[198:199], s[26:27], 0, v[212:213]
	global_load_lds_dwordx4 v[196:197], off
	v_lshl_add_u64 v[196:197], s[58:59], 0, v[214:215]
	s_add_i32 m0, s57, 0x2000
	s_nop 0
	global_load_lds_dwordx4 v[196:197], off
	v_lshl_add_u64 v[196:197], s[26:27], 0, v[208:209]
	s_mov_b32 m0, s31
	s_nop 0
	global_load_lds_dwordx4 v[196:197], off
	s_mov_b32 m0, s34
	s_nop 0
	global_load_lds_dwordx4 v[198:199], off
	s_waitcnt vmcnt(8)
	s_waitcnt lgkmcnt(0)
	s_setprio 1
	s_barrier
; #define PG8_STAGE(bufoff, gbase, voff) do { _Pragma("unroll") for (int _i = 0; _i < 2; ++_i) \
;         __builtin_amdgcn_global_load_lds((const unsigned*)((const char*)(gbase) + (voff)[_i]), (LAS unsigned*)(lds + (bufoff) + ldsw + _i * 8192), 16, 0, 0); } while (0)
; #define PG8_LDA(dst, b, h) do { _Pragma("unroll") for (int m = 0; m < 4; ++m) _Pragma("unroll") for (int k = 0; k < 2; ++k) dst[m][k] = *(const LAS bf16x8*)(lds + PG8_SA(b, h) + aoff + m * 2048 + k * 1024); } while (0)
; #define PG8_LDB(dst, b, h) do { _Pragma("unroll") for (int n = 0; n < 2; ++n) _Pragma("unroll") for (int k = 0; k < 2; ++k) dst[n][k] = *(const LAS bf16x8*)(lds + PG8_SB(b, h) + boff + n * 2048 + k * 1024); } while (0)
; #define PG8_MMA(ai, bj, At, Bt) do { __builtin_amdgcn_s_setprio(1); _Pragma("unroll") for (int m = 0; m < 4; ++m) _Pragma("unroll") for (int n = 0; n < 2; ++n) _Pragma("unroll") for (int k = 0; k < 2; ++k) \
;         acc[ai][bj][m][n] = __builtin_amdgcn_mfma_f32_16x16x32_bf16(Bt[n][k], At[m][k], acc[ai][bj][m][n], 0, 0, 0); __builtin_amdgcn_s_setprio(0); } while (0)
; #define PG8_WAIT_V(n) asm volatile("s_waitcnt vmcnt(" #n ")" ::: "memory")
; #define PG8_WAIT_L(n) asm volatile("s_waitcnt lgkmcnt(" #n ")" ::: "memory")
; #define PG8_BAR __builtin_amdgcn_s_barrier()
; #define PG8_SCHED __builtin_amdgcn_sched_barrier(0)
; template <class Epi>
; __device__ __forceinline__ void gemm_phase(LAS unsigned char* lds, const Gemm g, const StaticOrder& S, const Epi& E) {
;     ...
;             PG8_WAIT_V(8); PG8_WAIT_L(0); PG8_BAR; PG8_MMA(1, 0, At, B0); PG8_MMA(1, 1, At, B1); PG8_BAR; PG8_SCHED;
;             PG8_LDB(B0, 1, 0); PG8_LDB(B1, 1, 1); PG8_SCHED; PG8_LDA(At, 1, 0); PG8_STAGE(PG8_SA(0, 1), a2 + hstepA, voffA);
;             PG8_WAIT_V(8); PG8_WAIT_L(0); PG8_BAR; PG8_MMA(0, 0, At, B0); PG8_MMA(0, 1, At, B1); PG8_BAR; PG8_SCHED;
	s_waitcnt lgkmcnt(0)
	v_mfma_f32_16x16x32_bf16 v[60:63], v[96:99], v[160:163], v[60:63]
	v_mfma_f32_16x16x32_bf16 v[60:63], v[100:103], v[164:167], v[60:63]
	v_mfma_f32_16x16x32_bf16 v[56:59], v[116:119], v[164:167], v[56:59]
	v_mfma_f32_16x16x32_bf16 v[56:59], v[104:107], v[160:163], v[56:59]
	v_mfma_f32_16x16x32_bf16 v[52:55], v[120:123], v[160:163], v[52:55]
	v_mfma_f32_16x16x32_bf16 v[52:55], v[124:127], v[164:167], v[52:55]
	v_mfma_f32_16x16x32_bf16 v[48:51], v[148:151], v[164:167], v[48:51]
	v_mfma_f32_16x16x32_bf16 v[48:51], v[136:139], v[160:163], v[48:51]
	v_mfma_f32_16x16x32_bf16 v[32:35], v[136:139], v[168:171], v[32:35]
	v_mfma_f32_16x16x32_bf16 v[32:35], v[148:151], v[172:175], v[32:35]
	v_mfma_f32_16x16x32_bf16 v[36:39], v[124:127], v[172:175], v[36:39]
	v_mfma_f32_16x16x32_bf16 v[36:39], v[120:123], v[168:171], v[36:39]
	v_mfma_f32_16x16x32_bf16 v[40:43], v[104:107], v[168:171], v[40:43]
	v_mfma_f32_16x16x32_bf16 v[40:43], v[116:119], v[172:175], v[40:43]
	v_mfma_f32_16x16x32_bf16 v[44:47], v[100:103], v[172:175], v[44:47]
	v_mfma_f32_16x16x32_bf16 v[44:47], v[96:99], v[168:171], v[44:47]
	s_setprio 0
	s_setprio 1
	v_mfma_f32_16x16x32_bf16 v[28:31], v[96:99], v[176:179], v[28:31]
	v_mfma_f32_16x16x32_bf16 v[28:31], v[100:103], v[180:183], v[28:31]
	v_mfma_f32_16x16x32_bf16 v[24:27], v[116:119], v[180:183], v[24:27]
	v_mfma_f32_16x16x32_bf16 v[24:27], v[104:107], v[176:179], v[24:27]
	v_mfma_f32_16x16x32_bf16 v[20:23], v[120:123], v[176:179], v[20:23]
	v_mfma_f32_16x16x32_bf16 v[20:23], v[124:127], v[180:183], v[20:23]
	v_mfma_f32_16x16x32_bf16 v[16:19], v[148:151], v[180:183], v[16:19]
	v_mfma_f32_16x16x32_bf16 v[16:19], v[136:139], v[176:179], v[16:19]
	v_mfma_f32_16x16x32_bf16 v[0:3], v[136:139], v[184:187], v[0:3]
	v_mfma_f32_16x16x32_bf16 v[0:3], v[148:151], v[188:191], v[0:3]
	v_mfma_f32_16x16x32_bf16 v[4:7], v[124:127], v[188:191], v[4:7]
	v_mfma_f32_16x16x32_bf16 v[4:7], v[120:123], v[184:187], v[4:7]
	v_mfma_f32_16x16x32_bf16 v[8:11], v[104:107], v[184:187], v[8:11]
	v_mfma_f32_16x16x32_bf16 v[8:11], v[116:119], v[188:191], v[8:11]
	v_mfma_f32_16x16x32_bf16 v[12:15], v[100:103], v[188:191], v[12:15]
	v_mfma_f32_16x16x32_bf16 v[12:15], v[96:99], v[184:187], v[12:15]
	s_setprio 0
	s_barrier
	s_add_i32 s57, 0, 0x18000
	s_add_i32 s58, 0, 0x1c000
	v_add_u32_e32 v116, s57, v229
	v_add_u32_e32 v148, s58, v229
	ds_read_b128 v[96:99], v116
	ds_read_b128 v[100:103], v116 offset:1024
	ds_read_b128 v[104:107], v116 offset:2048
	ds_read_b128 v[116:119], v116 offset:3072
	ds_read_b128 v[120:123], v148
	ds_read_b128 v[124:127], v148 offset:1024
	ds_read_b128 v[136:139], v148 offset:2048
	ds_read_b128 v[148:151], v148 offset:3072
	s_add_u32 s26, s26, 0x40000
	s_addc_u32 s27, s27, 0
	s_mov_b32 m0, s35
	v_lshl_add_u64 v[200:201], s[26:27], 0, v[208:209]
	ds_read_b128 v[160:163], v232 offset:32768
	ds_read_b128 v[164:167], v232 offset:33792
	ds_read_b128 v[168:171], v232 offset:34816
	ds_read_b128 v[172:175], v232 offset:35840
	ds_read_b128 v[176:179], v232 offset:36864
	ds_read_b128 v[180:183], v232 offset:37888
	ds_read_b128 v[184:187], v232 offset:38912
	ds_read_b128 v[188:191], v232 offset:39936
	global_load_lds_dwordx4 v[200:201], off
	v_lshl_add_u64 v[200:201], s[26:27], 0, v[212:213]
	s_mov_b32 m0, s36
	s_nop 0
	global_load_lds_dwordx4 v[200:201], off
	s_waitcnt vmcnt(8)
	s_waitcnt lgkmcnt(0)
	s_setprio 1
	s_barrier
	s_waitcnt lgkmcnt(0)
	v_mfma_f32_16x16x32_bf16 v[156:159], v[96:99], v[160:163], v[156:159]
	v_mfma_f32_16x16x32_bf16 v[156:159], v[100:103], v[164:167], v[156:159]
	v_mfma_f32_16x16x32_bf16 v[152:155], v[116:119], v[164:167], v[152:155]
	v_mfma_f32_16x16x32_bf16 v[152:155], v[104:107], v[160:163], v[152:155]
	v_mfma_f32_16x16x32_bf16 v[144:147], v[120:123], v[160:163], v[144:147]
	v_mfma_f32_16x16x32_bf16 v[144:147], v[124:127], v[164:167], v[144:147]
	v_mfma_f32_16x16x32_bf16 v[140:143], v[148:151], v[164:167], v[140:143]
	v_mfma_f32_16x16x32_bf16 v[140:143], v[136:139], v[160:163], v[140:143]
	v_mfma_f32_16x16x32_bf16 v[108:111], v[136:139], v[168:171], v[108:111]
	v_mfma_f32_16x16x32_bf16 v[108:111], v[148:151], v[172:175], v[108:111]
	v_mfma_f32_16x16x32_bf16 v[112:115], v[124:127], v[172:175], v[112:115]
	v_mfma_f32_16x16x32_bf16 v[112:115], v[120:123], v[168:171], v[112:115]
	v_mfma_f32_16x16x32_bf16 v[128:131], v[104:107], v[168:171], v[128:131]
	v_mfma_f32_16x16x32_bf16 v[128:131], v[116:119], v[172:175], v[128:131]
	v_mfma_f32_16x16x32_bf16 v[132:135], v[100:103], v[172:175], v[132:135]
	v_mfma_f32_16x16x32_bf16 v[132:135], v[96:99], v[168:171], v[132:135]
	s_setprio 0
	s_setprio 1
	v_mfma_f32_16x16x32_bf16 v[92:95], v[96:99], v[176:179], v[92:95]
	v_mfma_f32_16x16x32_bf16 v[92:95], v[100:103], v[180:183], v[92:95]
	v_mfma_f32_16x16x32_bf16 v[88:91], v[116:119], v[180:183], v[88:91]
	v_mfma_f32_16x16x32_bf16 v[88:91], v[104:107], v[176:179], v[88:91]
	v_mfma_f32_16x16x32_bf16 v[84:87], v[120:123], v[176:179], v[84:87]
	v_mfma_f32_16x16x32_bf16 v[84:87], v[124:127], v[180:183], v[84:87]
	v_mfma_f32_16x16x32_bf16 v[80:83], v[148:151], v[180:183], v[80:83]
	v_mfma_f32_16x16x32_bf16 v[80:83], v[136:139], v[176:179], v[80:83]
	v_mfma_f32_16x16x32_bf16 v[64:67], v[136:139], v[184:187], v[64:67]
	v_mfma_f32_16x16x32_bf16 v[64:67], v[148:151], v[188:191], v[64:67]
	v_mfma_f32_16x16x32_bf16 v[68:71], v[124:127], v[188:191], v[68:71]
	v_mfma_f32_16x16x32_bf16 v[68:71], v[120:123], v[184:187], v[68:71]
	v_mfma_f32_16x16x32_bf16 v[72:75], v[104:107], v[184:187], v[72:75]
	v_mfma_f32_16x16x32_bf16 v[72:75], v[116:119], v[188:191], v[72:75]
	v_mfma_f32_16x16x32_bf16 v[76:79], v[100:103], v[188:191], v[76:79]
	v_mfma_f32_16x16x32_bf16 v[76:79], v[96:99], v[184:187], v[76:79]
	s_setprio 0
	s_barrier
; #define PG8_STAGE(bufoff, gbase, voff) do { _Pragma("unroll") for (int _i = 0; _i < 2; ++_i) \
;         __builtin_amdgcn_global_load_lds((const unsigned*)((const char*)(gbase) + (voff)[_i]), (LAS unsigned*)(lds + (bufoff) + ldsw + _i * 8192), 16, 0, 0); } while (0)
; #define PG8_LDA(dst, b, h) do { _Pragma("unroll") for (int m = 0; m < 4; ++m) _Pragma("unroll") for (int k = 0; k < 2; ++k) dst[m][k] = *(const LAS bf16x8*)(lds + PG8_SA(b, h) + aoff + m * 2048 + k * 1024); } while (0)
; #define PG8_MMA(ai, bj, At, Bt) do { __builtin_amdgcn_s_setprio(1); _Pragma("unroll") for (int m = 0; m < 4; ++m) _Pragma("unroll") for (int n = 0; n < 2; ++n) _Pragma("unroll") for (int k = 0; k < 2; ++k) \
;         acc[ai][bj][m][n] = __builtin_amdgcn_mfma_f32_16x16x32_bf16(Bt[n][k], At[m][k], acc[ai][bj][m][n], 0, 0, 0); __builtin_amdgcn_s_setprio(0); } while (0)
; #define PG8_WAIT_V(n) asm volatile("s_waitcnt vmcnt(" #n ")" ::: "memory")
; #define PG8_WAIT_L(n) asm volatile("s_waitcnt lgkmcnt(" #n ")" ::: "memory")
; #define PG8_BAR __builtin_amdgcn_s_barrier()
; #define PG8_SCHED __builtin_amdgcn_sched_barrier(0)
; template <class Epi>
; __device__ __forceinline__ void gemm_phase(LAS unsigned char* lds, const Gemm g, const StaticOrder& S, const Epi& E) {
;     ...
;             PG8_LDA(At, 1, 1); PG8_STAGE(PG8_SB(1, 0), b3, voffB); PG8_STAGE(PG8_SB(1, 1), b3 + hstepB, voffB); PG8_STAGE(PG8_SA(1, 0), a3, voffA);
;             PG8_WAIT_V(8); PG8_WAIT_L(0); PG8_BAR; PG8_MMA(1, 0, At, B0); PG8_MMA(1, 1, At, B1); PG8_BAR; PG8_SCHED;
;         }
	s_add_i32 s26, s57, s30
	v_lshl_add_u64 v[192:193], v[192:193], 0, s[10:11]
	s_mov_b32 m0, s26
	ds_read_b128 v[160:163], v232 offset:49152
	ds_read_b128 v[164:167], v232 offset:50176
	ds_read_b128 v[168:171], v232 offset:51200
	ds_read_b128 v[172:175], v232 offset:52224
	ds_read_b128 v[176:179], v232 offset:53248
	ds_read_b128 v[180:183], v232 offset:54272
	ds_read_b128 v[184:187], v232 offset:55296
	ds_read_b128 v[188:191], v232 offset:56320
	global_load_lds_dwordx4 v[192:193], off
	s_add_i32 m0, s26, 0x2000
	s_add_u32 s24, s24, 0x40080
	v_lshl_add_u64 v[192:193], v[194:195], 0, s[10:11]
	s_addc_u32 s25, s25, 0
	s_add_i32 s26, s58, s30
	global_load_lds_dwordx4 v[192:193], off
	v_lshl_add_u64 v[192:193], s[24:25], 0, v[210:211]
	s_mov_b32 m0, s26
	s_nop 0
	global_load_lds_dwordx4 v[192:193], off
	v_lshl_add_u64 v[192:193], s[24:25], 0, v[214:215]
	s_add_i32 m0, s26, 0x2000
	s_nop 0
	global_load_lds_dwordx4 v[192:193], off
	v_lshl_add_u64 v[192:193], v[196:197], 0, s[10:11]
	s_mov_b32 m0, s40
	s_nop 0
	global_load_lds_dwordx4 v[192:193], off
	v_lshl_add_u64 v[192:193], v[198:199], 0, s[10:11]
	s_mov_b32 m0, s41
	s_nop 0
	global_load_lds_dwordx4 v[192:193], off
	s_waitcnt vmcnt(8)
	s_waitcnt lgkmcnt(0)
	s_setprio 1
	s_barrier
	s_waitcnt lgkmcnt(0)
	v_mfma_f32_16x16x32_bf16 v[60:63], v[96:99], v[160:163], v[60:63]
	v_mfma_f32_16x16x32_bf16 v[60:63], v[100:103], v[164:167], v[60:63]
	v_mfma_f32_16x16x32_bf16 v[56:59], v[116:119], v[164:167], v[56:59]
	v_mfma_f32_16x16x32_bf16 v[56:59], v[104:107], v[160:163], v[56:59]
	v_mfma_f32_16x16x32_bf16 v[52:55], v[120:123], v[160:163], v[52:55]
	v_mfma_f32_16x16x32_bf16 v[52:55], v[124:127], v[164:167], v[52:55]
	v_mfma_f32_16x16x32_bf16 v[48:51], v[148:151], v[164:167], v[48:51]
	v_mfma_f32_16x16x32_bf16 v[48:51], v[136:139], v[160:163], v[48:51]
	v_mfma_f32_16x16x32_bf16 v[32:35], v[136:139], v[168:171], v[32:35]
	v_mfma_f32_16x16x32_bf16 v[32:35], v[148:151], v[172:175], v[32:35]
	v_mfma_f32_16x16x32_bf16 v[36:39], v[124:127], v[172:175], v[36:39]
	v_mfma_f32_16x16x32_bf16 v[36:39], v[120:123], v[168:171], v[36:39]
	v_mfma_f32_16x16x32_bf16 v[40:43], v[104:107], v[168:171], v[40:43]
	v_mfma_f32_16x16x32_bf16 v[40:43], v[116:119], v[172:175], v[40:43]
	v_mfma_f32_16x16x32_bf16 v[44:47], v[100:103], v[172:175], v[44:47]
	v_mfma_f32_16x16x32_bf16 v[44:47], v[96:99], v[168:171], v[44:47]
	s_setprio 0
	s_setprio 1
	v_mfma_f32_16x16x32_bf16 v[28:31], v[96:99], v[176:179], v[28:31]
	v_mfma_f32_16x16x32_bf16 v[28:31], v[100:103], v[180:183], v[28:31]
	v_mfma_f32_16x16x32_bf16 v[24:27], v[116:119], v[180:183], v[24:27]
	v_mfma_f32_16x16x32_bf16 v[24:27], v[104:107], v[176:179], v[24:27]
	v_mfma_f32_16x16x32_bf16 v[20:23], v[120:123], v[176:179], v[20:23]
	v_mfma_f32_16x16x32_bf16 v[20:23], v[124:127], v[180:183], v[20:23]
	v_mfma_f32_16x16x32_bf16 v[16:19], v[148:151], v[180:183], v[16:19]
	v_mfma_f32_16x16x32_bf16 v[16:19], v[136:139], v[176:179], v[16:19]
	v_mfma_f32_16x16x32_bf16 v[0:3], v[136:139], v[184:187], v[0:3]
	v_mfma_f32_16x16x32_bf16 v[0:3], v[148:151], v[188:191], v[0:3]
	v_mfma_f32_16x16x32_bf16 v[4:7], v[124:127], v[188:191], v[4:7]
	v_mfma_f32_16x16x32_bf16 v[4:7], v[120:123], v[184:187], v[4:7]
	v_mfma_f32_16x16x32_bf16 v[8:11], v[104:107], v[184:187], v[8:11]
	v_mfma_f32_16x16x32_bf16 v[8:11], v[116:119], v[188:191], v[8:11]
	v_mfma_f32_16x16x32_bf16 v[12:15], v[100:103], v[188:191], v[12:15]
	v_mfma_f32_16x16x32_bf16 v[12:15], v[96:99], v[184:187], v[12:15]
	s_setprio 0
	s_barrier
	s_add_u32 s4, s4, 0x100
	s_addc_u32 s5, s5, 0
	s_add_u32 s54, s54, 0x100
	s_addc_u32 s55, s55, 0
	s_cmp_ge_i32 s56, s39
	s_mov_b32 s24, s56
	s_cbranch_scc0 .LBB0_912

; #define PG8_STAGE(bufoff, gbase, voff) do { _Pragma("unroll") for (int _i = 0; _i < 2; ++_i) \
;         __builtin_amdgcn_global_load_lds((const unsigned*)((const char*)(gbase) + (voff)[_i]), (LAS unsigned*)(lds + (bufoff) + ldsw + _i * 8192), 16, 0, 0); } while (0)
; #define PG8_LDA(dst, b, h) do { _Pragma("unroll") for (int m = 0; m < 4; ++m) _Pragma("unroll") for (int k = 0; k < 2; ++k) dst[m][k] = *(const LAS bf16x8*)(lds + PG8_SA(b, h) + aoff + m * 2048 + k * 1024); } while (0)
; #define PG8_LDB(dst, b, h) do { _Pragma("unroll") for (int n = 0; n < 2; ++n) _Pragma("unroll") for (int k = 0; k < 2; ++k) dst[n][k] = *(const LAS bf16x8*)(lds + PG8_SB(b, h) + boff + n * 2048 + k * 1024); } while (0)
; #define PG8_MMA(ai, bj, At, Bt) do { __builtin_amdgcn_s_setprio(1); _Pragma("unroll") for (int m = 0; m < 4; ++m) _Pragma("unroll") for (int n = 0; n < 2; ++n) _Pragma("unroll") for (int k = 0; k < 2; ++k) \
;         acc[ai][bj][m][n] = __builtin_amdgcn_mfma_f32_16x16x32_bf16(Bt[n][k], At[m][k], acc[ai][bj][m][n], 0, 0, 0); __builtin_amdgcn_s_setprio(0); } while (0)
; #define PG8_WAIT_V(n) asm volatile("s_waitcnt vmcnt(" #n ")" ::: "memory")
; #define PG8_WAIT_L(n) asm volatile("s_waitcnt lgkmcnt(" #n ")" ::: "memory")
; #define PG8_BAR __builtin_amdgcn_s_barrier()
; #define PG8_SCHED __builtin_amdgcn_sched_barrier(0)
; template <class Epi>
; __device__ __forceinline__ void gemm_phase(LAS unsigned char* lds, const Gemm g, const StaticOrder& S, const Epi& E) {
;     ...
;             const bool last = (t == nt - 2);
;             const char* a1 = cA + (size_t)(t + 1) * kstep;
;             const char* a2 = last ? nA : cA + (size_t)(t + 2) * kstep; const char* b2 = last ? nB : cB + (size_t)(t + 2) * kstep;
;             const char* a3 = a2 + kstep; const char* b3 = b2 + kstep;
;             PG8_LDB(B0, 0, 0); PG8_LDB(B1, 0, 1); PG8_SCHED; PG8_LDA(At, 0, 0); PG8_STAGE(PG8_SA(1, 1), a1 + hstepA, voffA);
;             PG8_WAIT_V(8); PG8_WAIT_L(0); PG8_BAR; PG8_MMA(0, 0, At, B0); PG8_MMA(0, 1, At, B1); PG8_BAR; PG8_SCHED;
;             PG8_LDA(At, 0, 1); PG8_STAGE(PG8_SB(0, 0), b2, voffB); PG8_STAGE(PG8_SB(0, 1), b2 + hstepB, voffB); PG8_STAGE(PG8_SA(0, 0), a2, voffA);
;             PG8_WAIT_V(8); PG8_WAIT_L(0); PG8_BAR; PG8_MMA(1, 0, At, B0); PG8_MMA(1, 1, At, B1); PG8_BAR; PG8_SCHED;
.LBB0_1046:
	ds_read_b128 v[128:131], v185
	ds_read_b128 v[132:135], v185 offset:1024
	ds_read_b128 v[136:139], v185 offset:2048
	ds_read_b128 v[140:143], v185 offset:3072
	ds_read_b128 v[144:147], v186
	ds_read_b128 v[148:151], v186 offset:1024
	ds_read_b128 v[152:155], v186 offset:2048
	ds_read_b128 v[156:159], v186 offset:3072
	s_add_i32 s73, s46, 2
	s_add_u32 s47, s12, 0xfff80080
	s_addc_u32 s48, s13, -1
	s_cmp_eq_u32 s62, s46
	s_cselect_b32 s46, s41, s71
	s_cselect_b32 s49, s1, s48
	s_cselect_b32 s48, s33, s47
	s_cselect_b32 s47, s39, s72
	v_lshl_add_u64 v[182:183], s[12:13], 0, v[174:175]
	s_add_i32 m0, s5, 0xc000
	ds_read_b128 v[190:193], v187
	ds_read_b128 v[194:197], v187 offset:1024
	ds_read_b128 v[198:201], v187 offset:2048
	ds_read_b128 v[208:211], v187 offset:3072
	ds_read_b128 v[212:215], v187 offset:4096
	ds_read_b128 v[216:219], v187 offset:5120
	ds_read_b128 v[220:223], v187 offset:6144
	ds_read_b128 v[224:227], v187 offset:7168
	global_load_lds_dwordx4 v[182:183], off
	v_lshl_add_u64 v[182:183], s[12:13], 0, v[176:177]
	s_add_i32 m0, s5, 0xe000
	s_nop 0
	global_load_lds_dwordx4 v[182:183], off
	s_waitcnt vmcnt(8)
	s_waitcnt lgkmcnt(0)
	s_setprio 1
	s_barrier
	s_waitcnt lgkmcnt(0)
	v_mfma_f32_16x16x32_bf16 v[120:123], v[128:131], v[190:193], v[120:123]
	v_mfma_f32_16x16x32_bf16 v[120:123], v[132:135], v[194:197], v[120:123]
	v_mfma_f32_16x16x32_bf16 v[124:127], v[140:143], v[194:197], v[124:127]
	v_mfma_f32_16x16x32_bf16 v[124:127], v[136:139], v[190:193], v[124:127]
	v_mfma_f32_16x16x32_bf16 v[116:119], v[144:147], v[190:193], v[116:119]
	v_mfma_f32_16x16x32_bf16 v[116:119], v[148:151], v[194:197], v[116:119]
	v_mfma_f32_16x16x32_bf16 v[112:115], v[156:159], v[194:197], v[112:115]
	v_mfma_f32_16x16x32_bf16 v[112:115], v[152:155], v[190:193], v[112:115]
	v_mfma_f32_16x16x32_bf16 v[96:99], v[152:155], v[198:201], v[96:99]
	v_mfma_f32_16x16x32_bf16 v[96:99], v[156:159], v[208:211], v[96:99]
	v_mfma_f32_16x16x32_bf16 v[100:103], v[148:151], v[208:211], v[100:103]
	v_mfma_f32_16x16x32_bf16 v[100:103], v[144:147], v[198:201], v[100:103]
	v_mfma_f32_16x16x32_bf16 v[104:107], v[136:139], v[198:201], v[104:107]
	v_mfma_f32_16x16x32_bf16 v[104:107], v[140:143], v[208:211], v[104:107]
	v_mfma_f32_16x16x32_bf16 v[108:111], v[132:135], v[208:211], v[108:111]
	v_mfma_f32_16x16x32_bf16 v[108:111], v[128:131], v[198:201], v[108:111]
	s_setprio 0
	s_setprio 1
	v_mfma_f32_16x16x32_bf16 v[92:95], v[128:131], v[212:215], v[92:95]
	v_mfma_f32_16x16x32_bf16 v[92:95], v[132:135], v[216:219], v[92:95]
	v_mfma_f32_16x16x32_bf16 v[88:91], v[140:143], v[216:219], v[88:91]
	v_mfma_f32_16x16x32_bf16 v[88:91], v[136:139], v[212:215], v[88:91]
	v_mfma_f32_16x16x32_bf16 v[84:87], v[144:147], v[212:215], v[84:87]
	v_mfma_f32_16x16x32_bf16 v[84:87], v[148:151], v[216:219], v[84:87]
	v_mfma_f32_16x16x32_bf16 v[80:83], v[156:159], v[216:219], v[80:83]
	v_mfma_f32_16x16x32_bf16 v[80:83], v[152:155], v[212:215], v[80:83]
	v_mfma_f32_16x16x32_bf16 v[64:67], v[152:155], v[220:223], v[64:67]
	v_mfma_f32_16x16x32_bf16 v[64:67], v[156:159], v[224:227], v[64:67]
	v_mfma_f32_16x16x32_bf16 v[68:71], v[148:151], v[224:227], v[68:71]
	v_mfma_f32_16x16x32_bf16 v[68:71], v[144:147], v[220:223], v[68:71]
	v_mfma_f32_16x16x32_bf16 v[72:75], v[136:139], v[220:223], v[72:75]
	v_mfma_f32_16x16x32_bf16 v[72:75], v[140:143], v[224:227], v[72:75]
	v_mfma_f32_16x16x32_bf16 v[76:79], v[132:135], v[224:227], v[76:79]
	v_mfma_f32_16x16x32_bf16 v[76:79], v[128:131], v[220:223], v[76:79]
	s_setprio 0
	s_barrier
	s_add_i32 s76, s65, s54
	v_lshl_add_u64 v[182:183], s[46:47], 0, v[162:163]
	s_mov_b32 m0, s76
	ds_read_b128 v[190:193], v187 offset:16384
	ds_read_b128 v[194:197], v187 offset:17408
	ds_read_b128 v[198:201], v187 offset:18432
	ds_read_b128 v[208:211], v187 offset:19456
	ds_read_b128 v[212:215], v187 offset:20480
	ds_read_b128 v[216:219], v187 offset:21504
	ds_read_b128 v[220:223], v187 offset:22528
	ds_read_b128 v[224:227], v187 offset:23552
	global_load_lds_dwordx4 v[182:183], off
	s_add_i32 m0, s76, 0x2000
	s_add_u32 s76, s46, 0x80000
	v_lshl_add_u64 v[202:203], s[46:47], 0, v[166:167]
	s_addc_u32 s77, s47, 0
	s_add_i32 s78, s66, s54
	global_load_lds_dwordx4 v[202:203], off
	v_lshl_add_u64 v[230:231], s[76:77], 0, v[162:163]
	s_mov_b32 m0, s78
	v_lshl_add_u64 v[232:233], s[48:49], 0, v[164:165]
	global_load_lds_dwordx4 v[230:231], off
	v_lshl_add_u64 v[230:231], s[76:77], 0, v[166:167]
	s_add_i32 m0, s78, 0x2000
	s_nop 0
	global_load_lds_dwordx4 v[230:231], off
	v_lshl_add_u64 v[230:231], s[48:49], 0, v[160:161]
	s_mov_b32 m0, s5
	s_nop 0
	global_load_lds_dwordx4 v[230:231], off
	s_mov_b32 m0, s55
	s_nop 0
	global_load_lds_dwordx4 v[232:233], off
	s_waitcnt vmcnt(8)
	s_waitcnt lgkmcnt(0)
	s_setprio 1
	s_barrier
; #define PG8_STAGE(bufoff, gbase, voff) do { _Pragma("unroll") for (int _i = 0; _i < 2; ++_i) \
;         __builtin_amdgcn_global_load_lds((const unsigned*)((const char*)(gbase) + (voff)[_i]), (LAS unsigned*)(lds + (bufoff) + ldsw + _i * 8192), 16, 0, 0); } while (0)
; #define PG8_LDA(dst, b, h) do { _Pragma("unroll") for (int m = 0; m < 4; ++m) _Pragma("unroll") for (int k = 0; k < 2; ++k) dst[m][k] = *(const LAS bf16x8*)(lds + PG8_SA(b, h) + aoff + m * 2048 + k * 1024); } while (0)
; #define PG8_LDB(dst, b, h) do { _Pragma("unroll") for (int n = 0; n < 2; ++n) _Pragma("unroll") for (int k = 0; k < 2; ++k) dst[n][k] = *(const LAS bf16x8*)(lds + PG8_SB(b, h) + boff + n * 2048 + k * 1024); } while (0)
; #define PG8_MMA(ai, bj, At, Bt) do { __builtin_amdgcn_s_setprio(1); _Pragma("unroll") for (int m = 0; m < 4; ++m) _Pragma("unroll") for (int n = 0; n < 2; ++n) _Pragma("unroll") for (int k = 0; k < 2; ++k) \
;         acc[ai][bj][m][n] = __builtin_amdgcn_mfma_f32_16x16x32_bf16(Bt[n][k], At[m][k], acc[ai][bj][m][n], 0, 0, 0); __builtin_amdgcn_s_setprio(0); } while (0)
; #define PG8_WAIT_V(n) asm volatile("s_waitcnt vmcnt(" #n ")" ::: "memory")
; #define PG8_WAIT_L(n) asm volatile("s_waitcnt lgkmcnt(" #n ")" ::: "memory")
; #define PG8_BAR __builtin_amdgcn_s_barrier()
; #define PG8_SCHED __builtin_amdgcn_sched_barrier(0)
; template <class Epi>
; __device__ __forceinline__ void gemm_phase(LAS unsigned char* lds, const Gemm g, const StaticOrder& S, const Epi& E) {
;     ...
;             PG8_WAIT_V(8); PG8_WAIT_L(0); PG8_BAR; PG8_MMA(1, 0, At, B0); PG8_MMA(1, 1, At, B1); PG8_BAR; PG8_SCHED;
;             PG8_LDB(B0, 1, 0); PG8_LDB(B1, 1, 1); PG8_SCHED; PG8_LDA(At, 1, 0); PG8_STAGE(PG8_SA(0, 1), a2 + hstepA, voffA);
;             PG8_WAIT_V(8); PG8_WAIT_L(0); PG8_BAR; PG8_MMA(0, 0, At, B0); PG8_MMA(0, 1, At, B1); PG8_BAR; PG8_SCHED;
	s_waitcnt lgkmcnt(0)
	v_mfma_f32_16x16x32_bf16 v[60:63], v[128:131], v[190:193], v[60:63]
	v_mfma_f32_16x16x32_bf16 v[60:63], v[132:135], v[194:197], v[60:63]
	v_mfma_f32_16x16x32_bf16 v[56:59], v[140:143], v[194:197], v[56:59]
	v_mfma_f32_16x16x32_bf16 v[56:59], v[136:139], v[190:193], v[56:59]
	v_mfma_f32_16x16x32_bf16 v[52:55], v[144:147], v[190:193], v[52:55]
	v_mfma_f32_16x16x32_bf16 v[52:55], v[148:151], v[194:197], v[52:55]
	v_mfma_f32_16x16x32_bf16 v[48:51], v[156:159], v[194:197], v[48:51]
	v_mfma_f32_16x16x32_bf16 v[48:51], v[152:155], v[190:193], v[48:51]
	v_mfma_f32_16x16x32_bf16 v[32:35], v[152:155], v[198:201], v[32:35]
	v_mfma_f32_16x16x32_bf16 v[32:35], v[156:159], v[208:211], v[32:35]
	v_mfma_f32_16x16x32_bf16 v[36:39], v[148:151], v[208:211], v[36:39]
	v_mfma_f32_16x16x32_bf16 v[36:39], v[144:147], v[198:201], v[36:39]
	v_mfma_f32_16x16x32_bf16 v[40:43], v[136:139], v[198:201], v[40:43]
	v_mfma_f32_16x16x32_bf16 v[40:43], v[140:143], v[208:211], v[40:43]
	v_mfma_f32_16x16x32_bf16 v[44:47], v[132:135], v[208:211], v[44:47]
	v_mfma_f32_16x16x32_bf16 v[44:47], v[128:131], v[198:201], v[44:47]
	s_setprio 0
	s_setprio 1
	v_mfma_f32_16x16x32_bf16 v[28:31], v[128:131], v[212:215], v[28:31]
	v_mfma_f32_16x16x32_bf16 v[28:31], v[132:135], v[216:219], v[28:31]
	v_mfma_f32_16x16x32_bf16 v[24:27], v[140:143], v[216:219], v[24:27]
	v_mfma_f32_16x16x32_bf16 v[24:27], v[136:139], v[212:215], v[24:27]
	v_mfma_f32_16x16x32_bf16 v[20:23], v[144:147], v[212:215], v[20:23]
	v_mfma_f32_16x16x32_bf16 v[20:23], v[148:151], v[216:219], v[20:23]
	v_mfma_f32_16x16x32_bf16 v[16:19], v[156:159], v[216:219], v[16:19]
	v_mfma_f32_16x16x32_bf16 v[16:19], v[152:155], v[212:215], v[16:19]
	v_mfma_f32_16x16x32_bf16 v[0:3], v[152:155], v[220:223], v[0:3]
	v_mfma_f32_16x16x32_bf16 v[0:3], v[156:159], v[224:227], v[0:3]
	v_mfma_f32_16x16x32_bf16 v[4:7], v[148:151], v[224:227], v[4:7]
	v_mfma_f32_16x16x32_bf16 v[4:7], v[144:147], v[220:223], v[4:7]
	v_mfma_f32_16x16x32_bf16 v[8:11], v[136:139], v[220:223], v[8:11]
	v_mfma_f32_16x16x32_bf16 v[8:11], v[140:143], v[224:227], v[8:11]
	v_mfma_f32_16x16x32_bf16 v[12:15], v[132:135], v[224:227], v[12:15]
	v_mfma_f32_16x16x32_bf16 v[12:15], v[128:131], v[220:223], v[12:15]
	s_setprio 0
	s_barrier
	s_add_i32 s76, 0, 0x18000
	s_add_i32 s77, 0, 0x1c000
	v_add_u32_e32 v140, s76, v184
	v_add_u32_e32 v156, s77, v184
	ds_read_b128 v[128:131], v140
	ds_read_b128 v[132:135], v140 offset:1024
	ds_read_b128 v[136:139], v140 offset:2048
	ds_read_b128 v[140:143], v140 offset:3072
	ds_read_b128 v[144:147], v156
	ds_read_b128 v[148:151], v156 offset:1024
	ds_read_b128 v[152:155], v156 offset:2048
	ds_read_b128 v[156:159], v156 offset:3072
	s_add_u32 s48, s48, 0x80000
	s_addc_u32 s49, s49, 0
	s_mov_b32 m0, s56
	v_lshl_add_u64 v[234:235], s[48:49], 0, v[160:161]
	ds_read_b128 v[190:193], v187 offset:32768
	ds_read_b128 v[194:197], v187 offset:33792
	ds_read_b128 v[198:201], v187 offset:34816
	ds_read_b128 v[208:211], v187 offset:35840
	ds_read_b128 v[212:215], v187 offset:36864
	ds_read_b128 v[216:219], v187 offset:37888
	ds_read_b128 v[220:223], v187 offset:38912
	ds_read_b128 v[224:227], v187 offset:39936
	global_load_lds_dwordx4 v[234:235], off
	v_lshl_add_u64 v[234:235], s[48:49], 0, v[164:165]
	s_mov_b32 m0, s57
	s_nop 0
	global_load_lds_dwordx4 v[234:235], off
	s_waitcnt vmcnt(8)
	s_waitcnt lgkmcnt(0)
	s_setprio 1
	s_barrier
	s_waitcnt lgkmcnt(0)
	v_mfma_f32_16x16x32_bf16 v[120:123], v[128:131], v[190:193], v[120:123]
	v_mfma_f32_16x16x32_bf16 v[120:123], v[132:135], v[194:197], v[120:123]
	v_mfma_f32_16x16x32_bf16 v[124:127], v[140:143], v[194:197], v[124:127]
	v_mfma_f32_16x16x32_bf16 v[124:127], v[136:139], v[190:193], v[124:127]
	v_mfma_f32_16x16x32_bf16 v[116:119], v[144:147], v[190:193], v[116:119]
	v_mfma_f32_16x16x32_bf16 v[116:119], v[148:151], v[194:197], v[116:119]
	v_mfma_f32_16x16x32_bf16 v[112:115], v[156:159], v[194:197], v[112:115]
	v_mfma_f32_16x16x32_bf16 v[112:115], v[152:155], v[190:193], v[112:115]
	v_mfma_f32_16x16x32_bf16 v[96:99], v[152:155], v[198:201], v[96:99]
	v_mfma_f32_16x16x32_bf16 v[96:99], v[156:159], v[208:211], v[96:99]
	v_mfma_f32_16x16x32_bf16 v[100:103], v[148:151], v[208:211], v[100:103]
	v_mfma_f32_16x16x32_bf16 v[100:103], v[144:147], v[198:201], v[100:103]
	v_mfma_f32_16x16x32_bf16 v[104:107], v[136:139], v[198:201], v[104:107]
	v_mfma_f32_16x16x32_bf16 v[104:107], v[140:143], v[208:211], v[104:107]
	v_mfma_f32_16x16x32_bf16 v[108:111], v[132:135], v[208:211], v[108:111]
	v_mfma_f32_16x16x32_bf16 v[108:111], v[128:131], v[198:201], v[108:111]
	s_setprio 0
	s_setprio 1
	v_mfma_f32_16x16x32_bf16 v[92:95], v[128:131], v[212:215], v[92:95]
	v_mfma_f32_16x16x32_bf16 v[92:95], v[132:135], v[216:219], v[92:95]
	v_mfma_f32_16x16x32_bf16 v[88:91], v[140:143], v[216:219], v[88:91]
	v_mfma_f32_16x16x32_bf16 v[88:91], v[136:139], v[212:215], v[88:91]
	v_mfma_f32_16x16x32_bf16 v[84:87], v[144:147], v[212:215], v[84:87]
	v_mfma_f32_16x16x32_bf16 v[84:87], v[148:151], v[216:219], v[84:87]
	v_mfma_f32_16x16x32_bf16 v[80:83], v[156:159], v[216:219], v[80:83]
	v_mfma_f32_16x16x32_bf16 v[80:83], v[152:155], v[212:215], v[80:83]
	v_mfma_f32_16x16x32_bf16 v[64:67], v[152:155], v[220:223], v[64:67]
	v_mfma_f32_16x16x32_bf16 v[64:67], v[156:159], v[224:227], v[64:67]
	v_mfma_f32_16x16x32_bf16 v[68:71], v[148:151], v[224:227], v[68:71]
	v_mfma_f32_16x16x32_bf16 v[68:71], v[144:147], v[220:223], v[68:71]
	v_mfma_f32_16x16x32_bf16 v[72:75], v[136:139], v[220:223], v[72:75]
	v_mfma_f32_16x16x32_bf16 v[72:75], v[140:143], v[224:227], v[72:75]
	v_mfma_f32_16x16x32_bf16 v[76:79], v[132:135], v[224:227], v[76:79]
	v_mfma_f32_16x16x32_bf16 v[76:79], v[128:131], v[220:223], v[76:79]
	s_setprio 0
	s_barrier
; #define PG8_STAGE(bufoff, gbase, voff) do { _Pragma("unroll") for (int _i = 0; _i < 2; ++_i) \
;         __builtin_amdgcn_global_load_lds((const unsigned*)((const char*)(gbase) + (voff)[_i]), (LAS unsigned*)(lds + (bufoff) + ldsw + _i * 8192), 16, 0, 0); } while (0)
; #define PG8_LDA(dst, b, h) do { _Pragma("unroll") for (int m = 0; m < 4; ++m) _Pragma("unroll") for (int k = 0; k < 2; ++k) dst[m][k] = *(const LAS bf16x8*)(lds + PG8_SA(b, h) + aoff + m * 2048 + k * 1024); } while (0)
; #define PG8_MMA(ai, bj, At, Bt) do { __builtin_amdgcn_s_setprio(1); _Pragma("unroll") for (int m = 0; m < 4; ++m) _Pragma("unroll") for (int n = 0; n < 2; ++n) _Pragma("unroll") for (int k = 0; k < 2; ++k) \
;         acc[ai][bj][m][n] = __builtin_amdgcn_mfma_f32_16x16x32_bf16(Bt[n][k], At[m][k], acc[ai][bj][m][n], 0, 0, 0); __builtin_amdgcn_s_setprio(0); } while (0)
; #define PG8_WAIT_V(n) asm volatile("s_waitcnt vmcnt(" #n ")" ::: "memory")
; #define PG8_WAIT_L(n) asm volatile("s_waitcnt lgkmcnt(" #n ")" ::: "memory")
; #define PG8_BAR __builtin_amdgcn_s_barrier()
; #define PG8_SCHED __builtin_amdgcn_sched_barrier(0)
; template <class Epi>
; __device__ __forceinline__ void gemm_phase(LAS unsigned char* lds, const Gemm g, const StaticOrder& S, const Epi& E) {
;     ...
;             PG8_LDA(At, 1, 1); PG8_STAGE(PG8_SB(1, 0), b3, voffB); PG8_STAGE(PG8_SB(1, 1), b3 + hstepB, voffB); PG8_STAGE(PG8_SA(1, 0), a3, voffA);
;             PG8_WAIT_V(8); PG8_WAIT_L(0); PG8_BAR; PG8_MMA(1, 0, At, B0); PG8_MMA(1, 1, At, B1); PG8_BAR; PG8_SCHED;
;         }
	s_add_i32 s48, s76, s54
	v_lshl_add_u64 v[182:183], v[182:183], 0, s[16:17]
	s_mov_b32 m0, s48
	ds_read_b128 v[190:193], v187 offset:49152
	ds_read_b128 v[194:197], v187 offset:50176
	ds_read_b128 v[198:201], v187 offset:51200
	ds_read_b128 v[208:211], v187 offset:52224
	ds_read_b128 v[212:215], v187 offset:53248
	ds_read_b128 v[216:219], v187 offset:54272
	ds_read_b128 v[220:223], v187 offset:55296
	ds_read_b128 v[224:227], v187 offset:56320
	global_load_lds_dwordx4 v[182:183], off
	s_add_i32 m0, s48, 0x2000
	s_add_u32 s46, s46, 0x80080
	v_lshl_add_u64 v[182:183], v[202:203], 0, s[16:17]
	s_addc_u32 s47, s47, 0
	s_add_i32 s48, s77, s54
	global_load_lds_dwordx4 v[182:183], off
	v_lshl_add_u64 v[182:183], s[46:47], 0, v[162:163]
	s_mov_b32 m0, s48
	s_nop 0
	global_load_lds_dwordx4 v[182:183], off
	v_lshl_add_u64 v[182:183], s[46:47], 0, v[166:167]
	s_add_i32 m0, s48, 0x2000
	s_nop 0
	global_load_lds_dwordx4 v[182:183], off
	v_lshl_add_u64 v[182:183], v[230:231], 0, s[16:17]
	s_mov_b32 m0, s60
	s_nop 0
	global_load_lds_dwordx4 v[182:183], off
	v_lshl_add_u64 v[182:183], v[232:233], 0, s[16:17]
	s_mov_b32 m0, s61
	s_nop 0
	global_load_lds_dwordx4 v[182:183], off
	s_waitcnt vmcnt(8)
	s_waitcnt lgkmcnt(0)
	s_setprio 1
	s_barrier
	s_waitcnt lgkmcnt(0)
	v_mfma_f32_16x16x32_bf16 v[60:63], v[128:131], v[190:193], v[60:63]
	v_mfma_f32_16x16x32_bf16 v[60:63], v[132:135], v[194:197], v[60:63]
	v_mfma_f32_16x16x32_bf16 v[56:59], v[140:143], v[194:197], v[56:59]
	v_mfma_f32_16x16x32_bf16 v[56:59], v[136:139], v[190:193], v[56:59]
	v_mfma_f32_16x16x32_bf16 v[52:55], v[144:147], v[190:193], v[52:55]
	v_mfma_f32_16x16x32_bf16 v[52:55], v[148:151], v[194:197], v[52:55]
	v_mfma_f32_16x16x32_bf16 v[48:51], v[156:159], v[194:197], v[48:51]
	v_mfma_f32_16x16x32_bf16 v[48:51], v[152:155], v[190:193], v[48:51]
	v_mfma_f32_16x16x32_bf16 v[32:35], v[152:155], v[198:201], v[32:35]
	v_mfma_f32_16x16x32_bf16 v[32:35], v[156:159], v[208:211], v[32:35]
	v_mfma_f32_16x16x32_bf16 v[36:39], v[148:151], v[208:211], v[36:39]
	v_mfma_f32_16x16x32_bf16 v[36:39], v[144:147], v[198:201], v[36:39]
	v_mfma_f32_16x16x32_bf16 v[40:43], v[136:139], v[198:201], v[40:43]
	v_mfma_f32_16x16x32_bf16 v[40:43], v[140:143], v[208:211], v[40:43]
	v_mfma_f32_16x16x32_bf16 v[44:47], v[132:135], v[208:211], v[44:47]
	v_mfma_f32_16x16x32_bf16 v[44:47], v[128:131], v[198:201], v[44:47]
	s_setprio 0
	s_setprio 1
	v_mfma_f32_16x16x32_bf16 v[28:31], v[128:131], v[212:215], v[28:31]
	v_mfma_f32_16x16x32_bf16 v[28:31], v[132:135], v[216:219], v[28:31]
	v_mfma_f32_16x16x32_bf16 v[24:27], v[140:143], v[216:219], v[24:27]
	v_mfma_f32_16x16x32_bf16 v[24:27], v[136:139], v[212:215], v[24:27]
	v_mfma_f32_16x16x32_bf16 v[20:23], v[144:147], v[212:215], v[20:23]
	v_mfma_f32_16x16x32_bf16 v[20:23], v[148:151], v[216:219], v[20:23]
	v_mfma_f32_16x16x32_bf16 v[16:19], v[156:159], v[216:219], v[16:19]
	v_mfma_f32_16x16x32_bf16 v[16:19], v[152:155], v[212:215], v[16:19]
	v_mfma_f32_16x16x32_bf16 v[0:3], v[152:155], v[220:223], v[0:3]
	v_mfma_f32_16x16x32_bf16 v[0:3], v[156:159], v[224:227], v[0:3]
	v_mfma_f32_16x16x32_bf16 v[4:7], v[148:151], v[224:227], v[4:7]
	v_mfma_f32_16x16x32_bf16 v[4:7], v[144:147], v[220:223], v[4:7]
	v_mfma_f32_16x16x32_bf16 v[8:11], v[136:139], v[220:223], v[8:11]
	v_mfma_f32_16x16x32_bf16 v[8:11], v[140:143], v[224:227], v[8:11]
	v_mfma_f32_16x16x32_bf16 v[12:15], v[132:135], v[224:227], v[12:15]
	v_mfma_f32_16x16x32_bf16 v[12:15], v[128:131], v[220:223], v[12:15]
	s_setprio 0
	s_barrier
	s_add_u32 s12, s12, 0x100
	s_addc_u32 s13, s13, 0
	s_add_u32 s71, s71, 0x100
	s_addc_u32 s72, s72, 0
	s_cmp_ge_i32 s73, s59
	s_mov_b32 s46, s73
	s_cbranch_scc0 .LBB0_1046

; #define PG8_STAGE(bufoff, gbase, voff) do { _Pragma("unroll") for (int _i = 0; _i < 2; ++_i) \
;         __builtin_amdgcn_global_load_lds((const unsigned*)((const char*)(gbase) + (voff)[_i]), (LAS unsigned*)(lds + (bufoff) + ldsw + _i * 8192), 16, 0, 0); } while (0)
; #define PG8_LDA(dst, b, h) do { _Pragma("unroll") for (int m = 0; m < 4; ++m) _Pragma("unroll") for (int k = 0; k < 2; ++k) dst[m][k] = *(const LAS bf16x8*)(lds + PG8_SA(b, h) + aoff + m * 2048 + k * 1024); } while (0)
; #define PG8_LDB(dst, b, h) do { _Pragma("unroll") for (int n = 0; n < 2; ++n) _Pragma("unroll") for (int k = 0; k < 2; ++k) dst[n][k] = *(const LAS bf16x8*)(lds + PG8_SB(b, h) + boff + n * 2048 + k * 1024); } while (0)
; #define PG8_MMA(ai, bj, At, Bt) do { __builtin_amdgcn_s_setprio(1); _Pragma("unroll") for (int m = 0; m < 4; ++m) _Pragma("unroll") for (int n = 0; n < 2; ++n) _Pragma("unroll") for (int k = 0; k < 2; ++k) \
;         acc[ai][bj][m][n] = __builtin_amdgcn_mfma_f32_16x16x32_bf16(Bt[n][k], At[m][k], acc[ai][bj][m][n], 0, 0, 0); __builtin_amdgcn_s_setprio(0); } while (0)
; #define PG8_WAIT_V(n) asm volatile("s_waitcnt vmcnt(" #n ")" ::: "memory")
; #define PG8_WAIT_L(n) asm volatile("s_waitcnt lgkmcnt(" #n ")" ::: "memory")
; #define PG8_BAR __builtin_amdgcn_s_barrier()
; #define PG8_SCHED __builtin_amdgcn_sched_barrier(0)
; template <class Epi>
; __device__ __forceinline__ void gemm_phase(LAS unsigned char* lds, const Gemm g, const StaticOrder& S, const Epi& E) {
;     ...
;             const bool last = (t == nt - 2);
;             const char* a1 = cA + (size_t)(t + 1) * kstep;
;             const char* a2 = last ? nA : cA + (size_t)(t + 2) * kstep; const char* b2 = last ? nB : cB + (size_t)(t + 2) * kstep;
;             const char* a3 = a2 + kstep; const char* b3 = b2 + kstep;
;             PG8_LDB(B0, 0, 0); PG8_LDB(B1, 0, 1); PG8_SCHED; PG8_LDA(At, 0, 0); PG8_STAGE(PG8_SA(1, 1), a1 + hstepA, voffA);
;             PG8_WAIT_V(8); PG8_WAIT_L(0); PG8_BAR; PG8_MMA(0, 0, At, B0); PG8_MMA(0, 1, At, B1); PG8_BAR; PG8_SCHED;
;             PG8_LDA(At, 0, 1); PG8_STAGE(PG8_SB(0, 0), b2, voffB); PG8_STAGE(PG8_SB(0, 1), b2 + hstepB, voffB); PG8_STAGE(PG8_SA(0, 0), a2, voffA);
;             PG8_WAIT_V(8); PG8_WAIT_L(0); PG8_BAR; PG8_MMA(1, 0, At, B0); PG8_MMA(1, 1, At, B1); PG8_BAR; PG8_SCHED;
.LBB0_1131:
	ds_read_b128 v[164:167], v182
	ds_read_b128 v[168:171], v182 offset:1024
	ds_read_b128 v[172:175], v182 offset:2048
	ds_read_b128 v[176:179], v182 offset:3072
	ds_read_b128 v[186:189], v183
	ds_read_b128 v[190:193], v183 offset:1024
	ds_read_b128 v[194:197], v183 offset:2048
	ds_read_b128 v[198:201], v183 offset:3072
	s_add_i32 s22, s12, 2
	s_add_u32 s13, s10, 0xfff80080
	s_addc_u32 s14, s11, -1
	s_cmp_eq_u32 s58, s12
	s_cselect_b32 s12, s19, s20
	s_cselect_b32 s15, s16, s14
	s_cselect_b32 s14, s17, s13
	s_cselect_b32 s13, s18, s21
	v_lshl_add_u64 v[202:203], s[10:11], 0, v[140:141]
	s_add_i32 m0, s33, 0xc000
	ds_read_b128 v[208:211], v184
	ds_read_b128 v[212:215], v184 offset:1024
	ds_read_b128 v[216:219], v184 offset:2048
	ds_read_b128 v[220:223], v184 offset:3072
	ds_read_b128 v[224:227], v184 offset:4096
	ds_read_b128 v[230:233], v184 offset:5120
	ds_read_b128 v[234:237], v184 offset:6144
	ds_read_b128 v[238:241], v184 offset:7168
	global_load_lds_dwordx4 v[202:203], off
	v_lshl_add_u64 v[202:203], s[10:11], 0, v[142:143]
	s_add_i32 m0, s33, 0xe000
	s_nop 0
	global_load_lds_dwordx4 v[202:203], off
	s_waitcnt vmcnt(8)
	s_waitcnt lgkmcnt(0)
	s_setprio 1
	s_barrier
	s_waitcnt lgkmcnt(0)
	v_mfma_f32_16x16x32_bf16 v[120:123], v[164:167], v[208:211], v[120:123]
	v_mfma_f32_16x16x32_bf16 v[120:123], v[168:171], v[212:215], v[120:123]
	v_mfma_f32_16x16x32_bf16 v[116:119], v[176:179], v[212:215], v[116:119]
	v_mfma_f32_16x16x32_bf16 v[116:119], v[172:175], v[208:211], v[116:119]
	v_mfma_f32_16x16x32_bf16 v[124:127], v[186:189], v[208:211], v[124:127]
	v_mfma_f32_16x16x32_bf16 v[124:127], v[190:193], v[212:215], v[124:127]
	v_mfma_f32_16x16x32_bf16 v[112:115], v[198:201], v[212:215], v[112:115]
	v_mfma_f32_16x16x32_bf16 v[112:115], v[194:197], v[208:211], v[112:115]
	v_mfma_f32_16x16x32_bf16 v[96:99], v[194:197], v[216:219], v[96:99]
	v_mfma_f32_16x16x32_bf16 v[96:99], v[198:201], v[220:223], v[96:99]
	v_mfma_f32_16x16x32_bf16 v[104:107], v[190:193], v[220:223], v[104:107]
	v_mfma_f32_16x16x32_bf16 v[104:107], v[186:189], v[216:219], v[104:107]
	v_mfma_f32_16x16x32_bf16 v[100:103], v[172:175], v[216:219], v[100:103]
	v_mfma_f32_16x16x32_bf16 v[100:103], v[176:179], v[220:223], v[100:103]
	v_mfma_f32_16x16x32_bf16 v[108:111], v[168:171], v[220:223], v[108:111]
	v_mfma_f32_16x16x32_bf16 v[108:111], v[164:167], v[216:219], v[108:111]
	s_setprio 0
	s_setprio 1
	v_mfma_f32_16x16x32_bf16 v[92:95], v[164:167], v[224:227], v[92:95]
	v_mfma_f32_16x16x32_bf16 v[92:95], v[168:171], v[230:233], v[92:95]
	v_mfma_f32_16x16x32_bf16 v[84:87], v[176:179], v[230:233], v[84:87]
	v_mfma_f32_16x16x32_bf16 v[84:87], v[172:175], v[224:227], v[84:87]
	v_mfma_f32_16x16x32_bf16 v[88:91], v[186:189], v[224:227], v[88:91]
	v_mfma_f32_16x16x32_bf16 v[88:91], v[190:193], v[230:233], v[88:91]
	v_mfma_f32_16x16x32_bf16 v[80:83], v[198:201], v[230:233], v[80:83]
	v_mfma_f32_16x16x32_bf16 v[80:83], v[194:197], v[224:227], v[80:83]
	v_mfma_f32_16x16x32_bf16 v[64:67], v[194:197], v[234:237], v[64:67]
	v_mfma_f32_16x16x32_bf16 v[64:67], v[198:201], v[238:241], v[64:67]
	v_mfma_f32_16x16x32_bf16 v[72:75], v[190:193], v[238:241], v[72:75]
	v_mfma_f32_16x16x32_bf16 v[72:75], v[186:189], v[234:237], v[72:75]
	v_mfma_f32_16x16x32_bf16 v[68:71], v[172:175], v[234:237], v[68:71]
	v_mfma_f32_16x16x32_bf16 v[68:71], v[176:179], v[238:241], v[68:71]
	v_mfma_f32_16x16x32_bf16 v[76:79], v[168:171], v[238:241], v[76:79]
	v_mfma_f32_16x16x32_bf16 v[76:79], v[164:167], v[234:237], v[76:79]
	s_setprio 0
	s_barrier
	s_add_i32 s23, s62, s37
	v_lshl_add_u64 v[202:203], s[12:13], 0, v[132:133]
	s_mov_b32 m0, s23
	ds_read_b128 v[208:211], v184 offset:16384
	ds_read_b128 v[212:215], v184 offset:17408
	ds_read_b128 v[216:219], v184 offset:18432
	ds_read_b128 v[220:223], v184 offset:19456
	ds_read_b128 v[224:227], v184 offset:20480
	ds_read_b128 v[230:233], v184 offset:21504
	ds_read_b128 v[234:237], v184 offset:22528
	ds_read_b128 v[238:241], v184 offset:23552
	global_load_lds_dwordx4 v[202:203], off
	s_add_i32 m0, s23, 0x2000
	s_add_u32 s50, s12, 0x80000
	v_lshl_add_u64 v[242:243], s[12:13], 0, v[128:129]
	s_addc_u32 s51, s13, 0
	s_add_i32 s23, s63, s37
	global_load_lds_dwordx4 v[242:243], off
	v_lshl_add_u64 v[244:245], s[50:51], 0, v[132:133]
	s_mov_b32 m0, s23
	v_lshl_add_u64 v[246:247], s[14:15], 0, v[130:131]
	global_load_lds_dwordx4 v[244:245], off
	v_lshl_add_u64 v[244:245], s[50:51], 0, v[128:129]
	s_add_i32 m0, s23, 0x2000
	s_nop 0
	global_load_lds_dwordx4 v[244:245], off
	v_lshl_add_u64 v[244:245], s[14:15], 0, v[134:135]
	s_mov_b32 m0, s33
	s_nop 0
	global_load_lds_dwordx4 v[244:245], off
	s_mov_b32 m0, s52
	s_nop 0
	global_load_lds_dwordx4 v[246:247], off
	s_waitcnt vmcnt(8)
	s_waitcnt lgkmcnt(0)
	s_setprio 1
	s_barrier
; #define PG8_STAGE(bufoff, gbase, voff) do { _Pragma("unroll") for (int _i = 0; _i < 2; ++_i) \
;         __builtin_amdgcn_global_load_lds((const unsigned*)((const char*)(gbase) + (voff)[_i]), (LAS unsigned*)(lds + (bufoff) + ldsw + _i * 8192), 16, 0, 0); } while (0)
; #define PG8_LDA(dst, b, h) do { _Pragma("unroll") for (int m = 0; m < 4; ++m) _Pragma("unroll") for (int k = 0; k < 2; ++k) dst[m][k] = *(const LAS bf16x8*)(lds + PG8_SA(b, h) + aoff + m * 2048 + k * 1024); } while (0)
; #define PG8_LDB(dst, b, h) do { _Pragma("unroll") for (int n = 0; n < 2; ++n) _Pragma("unroll") for (int k = 0; k < 2; ++k) dst[n][k] = *(const LAS bf16x8*)(lds + PG8_SB(b, h) + boff + n * 2048 + k * 1024); } while (0)
; #define PG8_MMA(ai, bj, At, Bt) do { __builtin_amdgcn_s_setprio(1); _Pragma("unroll") for (int m = 0; m < 4; ++m) _Pragma("unroll") for (int n = 0; n < 2; ++n) _Pragma("unroll") for (int k = 0; k < 2; ++k) \
;         acc[ai][bj][m][n] = __builtin_amdgcn_mfma_f32_16x16x32_bf16(Bt[n][k], At[m][k], acc[ai][bj][m][n], 0, 0, 0); __builtin_amdgcn_s_setprio(0); } while (0)
; #define PG8_WAIT_V(n) asm volatile("s_waitcnt vmcnt(" #n ")" ::: "memory")
; #define PG8_WAIT_L(n) asm volatile("s_waitcnt lgkmcnt(" #n ")" ::: "memory")
; #define PG8_BAR __builtin_amdgcn_s_barrier()
; #define PG8_SCHED __builtin_amdgcn_sched_barrier(0)
; template <class Epi>
; __device__ __forceinline__ void gemm_phase(LAS unsigned char* lds, const Gemm g, const StaticOrder& S, const Epi& E) {
;     ...
;             PG8_WAIT_V(8); PG8_WAIT_L(0); PG8_BAR; PG8_MMA(1, 0, At, B0); PG8_MMA(1, 1, At, B1); PG8_BAR; PG8_SCHED;
;             PG8_LDB(B0, 1, 0); PG8_LDB(B1, 1, 1); PG8_SCHED; PG8_LDA(At, 1, 0); PG8_STAGE(PG8_SA(0, 1), a2 + hstepA, voffA);
;             PG8_WAIT_V(8); PG8_WAIT_L(0); PG8_BAR; PG8_MMA(0, 0, At, B0); PG8_MMA(0, 1, At, B1); PG8_BAR; PG8_SCHED;
	s_waitcnt lgkmcnt(0)
	v_mfma_f32_16x16x32_bf16 v[60:63], v[164:167], v[208:211], v[60:63]
	v_mfma_f32_16x16x32_bf16 v[60:63], v[168:171], v[212:215], v[60:63]
	v_mfma_f32_16x16x32_bf16 v[52:55], v[176:179], v[212:215], v[52:55]
	v_mfma_f32_16x16x32_bf16 v[52:55], v[172:175], v[208:211], v[52:55]
	v_mfma_f32_16x16x32_bf16 v[56:59], v[186:189], v[208:211], v[56:59]
	v_mfma_f32_16x16x32_bf16 v[56:59], v[190:193], v[212:215], v[56:59]
	v_mfma_f32_16x16x32_bf16 v[48:51], v[198:201], v[212:215], v[48:51]
	v_mfma_f32_16x16x32_bf16 v[48:51], v[194:197], v[208:211], v[48:51]
	v_mfma_f32_16x16x32_bf16 v[32:35], v[194:197], v[216:219], v[32:35]
	v_mfma_f32_16x16x32_bf16 v[32:35], v[198:201], v[220:223], v[32:35]
	v_mfma_f32_16x16x32_bf16 v[40:43], v[190:193], v[220:223], v[40:43]
	v_mfma_f32_16x16x32_bf16 v[40:43], v[186:189], v[216:219], v[40:43]
	v_mfma_f32_16x16x32_bf16 v[36:39], v[172:175], v[216:219], v[36:39]
	v_mfma_f32_16x16x32_bf16 v[36:39], v[176:179], v[220:223], v[36:39]
	v_mfma_f32_16x16x32_bf16 v[44:47], v[168:171], v[220:223], v[44:47]
	v_mfma_f32_16x16x32_bf16 v[44:47], v[164:167], v[216:219], v[44:47]
	s_setprio 0
	s_setprio 1
	v_mfma_f32_16x16x32_bf16 v[28:31], v[164:167], v[224:227], v[28:31]
	v_mfma_f32_16x16x32_bf16 v[28:31], v[168:171], v[230:233], v[28:31]
	v_mfma_f32_16x16x32_bf16 v[20:23], v[176:179], v[230:233], v[20:23]
	v_mfma_f32_16x16x32_bf16 v[20:23], v[172:175], v[224:227], v[20:23]
	v_mfma_f32_16x16x32_bf16 v[24:27], v[186:189], v[224:227], v[24:27]
	v_mfma_f32_16x16x32_bf16 v[24:27], v[190:193], v[230:233], v[24:27]
	v_mfma_f32_16x16x32_bf16 v[16:19], v[198:201], v[230:233], v[16:19]
	v_mfma_f32_16x16x32_bf16 v[16:19], v[194:197], v[224:227], v[16:19]
	v_mfma_f32_16x16x32_bf16 v[0:3], v[194:197], v[234:237], v[0:3]
	v_mfma_f32_16x16x32_bf16 v[0:3], v[198:201], v[238:241], v[0:3]
	v_mfma_f32_16x16x32_bf16 v[8:11], v[190:193], v[238:241], v[8:11]
	v_mfma_f32_16x16x32_bf16 v[8:11], v[186:189], v[234:237], v[8:11]
	v_mfma_f32_16x16x32_bf16 v[4:7], v[172:175], v[234:237], v[4:7]
	v_mfma_f32_16x16x32_bf16 v[4:7], v[176:179], v[238:241], v[4:7]
	v_mfma_f32_16x16x32_bf16 v[12:15], v[168:171], v[238:241], v[12:15]
	v_mfma_f32_16x16x32_bf16 v[12:15], v[164:167], v[234:237], v[12:15]
	s_setprio 0
	s_barrier
	s_add_i32 s23, 0, 0x18000
	s_add_i32 s25, 0, 0x1c000
	v_add_u32_e32 v176, s23, v180
	v_add_u32_e32 v185, s25, v180
	ds_read_b128 v[164:167], v176
	ds_read_b128 v[168:171], v176 offset:1024
	ds_read_b128 v[172:175], v176 offset:2048
	ds_read_b128 v[176:179], v176 offset:3072
	ds_read_b128 v[186:189], v185
	ds_read_b128 v[190:193], v185 offset:1024
	ds_read_b128 v[194:197], v185 offset:2048
	ds_read_b128 v[198:201], v185 offset:3072
	s_add_u32 s14, s14, 0x80000
	s_addc_u32 s15, s15, 0
	s_mov_b32 m0, s53
	v_lshl_add_u64 v[248:249], s[14:15], 0, v[134:135]
	ds_read_b128 v[208:211], v184 offset:32768
	ds_read_b128 v[212:215], v184 offset:33792
	ds_read_b128 v[216:219], v184 offset:34816
	ds_read_b128 v[220:223], v184 offset:35840
	ds_read_b128 v[224:227], v184 offset:36864
	ds_read_b128 v[230:233], v184 offset:37888
	ds_read_b128 v[234:237], v184 offset:38912
	ds_read_b128 v[238:241], v184 offset:39936
	global_load_lds_dwordx4 v[248:249], off
	v_lshl_add_u64 v[248:249], s[14:15], 0, v[130:131]
	s_mov_b32 m0, s54
	s_nop 0
	global_load_lds_dwordx4 v[248:249], off
	s_waitcnt vmcnt(8)
	s_waitcnt lgkmcnt(0)
	s_setprio 1
	s_barrier
	s_waitcnt lgkmcnt(0)
	v_mfma_f32_16x16x32_bf16 v[120:123], v[164:167], v[208:211], v[120:123]
	v_mfma_f32_16x16x32_bf16 v[120:123], v[168:171], v[212:215], v[120:123]
	v_mfma_f32_16x16x32_bf16 v[116:119], v[176:179], v[212:215], v[116:119]
	v_mfma_f32_16x16x32_bf16 v[116:119], v[172:175], v[208:211], v[116:119]
	v_mfma_f32_16x16x32_bf16 v[124:127], v[186:189], v[208:211], v[124:127]
	v_mfma_f32_16x16x32_bf16 v[124:127], v[190:193], v[212:215], v[124:127]
	v_mfma_f32_16x16x32_bf16 v[112:115], v[198:201], v[212:215], v[112:115]
	v_mfma_f32_16x16x32_bf16 v[112:115], v[194:197], v[208:211], v[112:115]
	v_mfma_f32_16x16x32_bf16 v[96:99], v[194:197], v[216:219], v[96:99]
	v_mfma_f32_16x16x32_bf16 v[96:99], v[198:201], v[220:223], v[96:99]
	v_mfma_f32_16x16x32_bf16 v[104:107], v[190:193], v[220:223], v[104:107]
	v_mfma_f32_16x16x32_bf16 v[104:107], v[186:189], v[216:219], v[104:107]
	v_mfma_f32_16x16x32_bf16 v[100:103], v[172:175], v[216:219], v[100:103]
	v_mfma_f32_16x16x32_bf16 v[100:103], v[176:179], v[220:223], v[100:103]
	v_mfma_f32_16x16x32_bf16 v[108:111], v[168:171], v[220:223], v[108:111]
	v_mfma_f32_16x16x32_bf16 v[108:111], v[164:167], v[216:219], v[108:111]
	s_setprio 0
	s_setprio 1
	v_mfma_f32_16x16x32_bf16 v[92:95], v[164:167], v[224:227], v[92:95]
	v_mfma_f32_16x16x32_bf16 v[92:95], v[168:171], v[230:233], v[92:95]
	v_mfma_f32_16x16x32_bf16 v[84:87], v[176:179], v[230:233], v[84:87]
	v_mfma_f32_16x16x32_bf16 v[84:87], v[172:175], v[224:227], v[84:87]
	v_mfma_f32_16x16x32_bf16 v[88:91], v[186:189], v[224:227], v[88:91]
	v_mfma_f32_16x16x32_bf16 v[88:91], v[190:193], v[230:233], v[88:91]
	v_mfma_f32_16x16x32_bf16 v[80:83], v[198:201], v[230:233], v[80:83]
	v_mfma_f32_16x16x32_bf16 v[80:83], v[194:197], v[224:227], v[80:83]
	v_mfma_f32_16x16x32_bf16 v[64:67], v[194:197], v[234:237], v[64:67]
	v_mfma_f32_16x16x32_bf16 v[64:67], v[198:201], v[238:241], v[64:67]
	v_mfma_f32_16x16x32_bf16 v[72:75], v[190:193], v[238:241], v[72:75]
	v_mfma_f32_16x16x32_bf16 v[72:75], v[186:189], v[234:237], v[72:75]
	v_mfma_f32_16x16x32_bf16 v[68:71], v[172:175], v[234:237], v[68:71]
	v_mfma_f32_16x16x32_bf16 v[68:71], v[176:179], v[238:241], v[68:71]
	v_mfma_f32_16x16x32_bf16 v[76:79], v[168:171], v[238:241], v[76:79]
	v_mfma_f32_16x16x32_bf16 v[76:79], v[164:167], v[234:237], v[76:79]
	s_setprio 0
	s_barrier
; #define PG8_STAGE(bufoff, gbase, voff) do { _Pragma("unroll") for (int _i = 0; _i < 2; ++_i) \
;         __builtin_amdgcn_global_load_lds((const unsigned*)((const char*)(gbase) + (voff)[_i]), (LAS unsigned*)(lds + (bufoff) + ldsw + _i * 8192), 16, 0, 0); } while (0)
; #define PG8_LDA(dst, b, h) do { _Pragma("unroll") for (int m = 0; m < 4; ++m) _Pragma("unroll") for (int k = 0; k < 2; ++k) dst[m][k] = *(const LAS bf16x8*)(lds + PG8_SA(b, h) + aoff + m * 2048 + k * 1024); } while (0)
; #define PG8_MMA(ai, bj, At, Bt) do { __builtin_amdgcn_s_setprio(1); _Pragma("unroll") for (int m = 0; m < 4; ++m) _Pragma("unroll") for (int n = 0; n < 2; ++n) _Pragma("unroll") for (int k = 0; k < 2; ++k) \
;         acc[ai][bj][m][n] = __builtin_amdgcn_mfma_f32_16x16x32_bf16(Bt[n][k], At[m][k], acc[ai][bj][m][n], 0, 0, 0); __builtin_amdgcn_s_setprio(0); } while (0)
; #define PG8_WAIT_V(n) asm volatile("s_waitcnt vmcnt(" #n ")" ::: "memory")
; #define PG8_WAIT_L(n) asm volatile("s_waitcnt lgkmcnt(" #n ")" ::: "memory")
; #define PG8_BAR __builtin_amdgcn_s_barrier()
; #define PG8_SCHED __builtin_amdgcn_sched_barrier(0)
; template <class Epi>
; __device__ __forceinline__ void gemm_phase(LAS unsigned char* lds, const Gemm g, const StaticOrder& S, const Epi& E) {
;     ...
;             PG8_LDA(At, 1, 1); PG8_STAGE(PG8_SB(1, 0), b3, voffB); PG8_STAGE(PG8_SB(1, 1), b3 + hstepB, voffB); PG8_STAGE(PG8_SA(1, 0), a3, voffA);
;             PG8_WAIT_V(8); PG8_WAIT_L(0); PG8_BAR; PG8_MMA(1, 0, At, B0); PG8_MMA(1, 1, At, B1); PG8_BAR; PG8_SCHED;
;         }
	s_add_i32 s14, s23, s37
	v_lshl_add_u64 v[202:203], v[202:203], 0, s[4:5]
	s_mov_b32 m0, s14
	ds_read_b128 v[208:211], v184 offset:49152
	ds_read_b128 v[212:215], v184 offset:50176
	ds_read_b128 v[216:219], v184 offset:51200
	ds_read_b128 v[220:223], v184 offset:52224
	ds_read_b128 v[224:227], v184 offset:53248
	ds_read_b128 v[230:233], v184 offset:54272
	ds_read_b128 v[234:237], v184 offset:55296
	ds_read_b128 v[238:241], v184 offset:56320
	global_load_lds_dwordx4 v[202:203], off
	s_add_i32 m0, s14, 0x2000
	s_add_u32 s12, s12, 0x80080
	v_lshl_add_u64 v[202:203], v[242:243], 0, s[4:5]
	s_addc_u32 s13, s13, 0
	s_add_i32 s14, s25, s37
	global_load_lds_dwordx4 v[202:203], off
	v_lshl_add_u64 v[202:203], s[12:13], 0, v[132:133]
	s_mov_b32 m0, s14
	s_nop 0
	global_load_lds_dwordx4 v[202:203], off
	v_lshl_add_u64 v[202:203], s[12:13], 0, v[128:129]
	s_add_i32 m0, s14, 0x2000
	s_nop 0
	global_load_lds_dwordx4 v[202:203], off
	v_lshl_add_u64 v[202:203], v[244:245], 0, s[4:5]
	s_mov_b32 m0, s56
	s_nop 0
	global_load_lds_dwordx4 v[202:203], off
	v_lshl_add_u64 v[202:203], v[246:247], 0, s[4:5]
	s_mov_b32 m0, s57
	s_nop 0
	global_load_lds_dwordx4 v[202:203], off
	s_waitcnt vmcnt(8)
	s_waitcnt lgkmcnt(0)
	s_setprio 1
	s_barrier
	s_waitcnt lgkmcnt(0)
	v_mfma_f32_16x16x32_bf16 v[60:63], v[164:167], v[208:211], v[60:63]
	v_mfma_f32_16x16x32_bf16 v[60:63], v[168:171], v[212:215], v[60:63]
	v_mfma_f32_16x16x32_bf16 v[52:55], v[176:179], v[212:215], v[52:55]
	v_mfma_f32_16x16x32_bf16 v[52:55], v[172:175], v[208:211], v[52:55]
	v_mfma_f32_16x16x32_bf16 v[56:59], v[186:189], v[208:211], v[56:59]
	v_mfma_f32_16x16x32_bf16 v[56:59], v[190:193], v[212:215], v[56:59]
	v_mfma_f32_16x16x32_bf16 v[48:51], v[198:201], v[212:215], v[48:51]
	v_mfma_f32_16x16x32_bf16 v[48:51], v[194:197], v[208:211], v[48:51]
	v_mfma_f32_16x16x32_bf16 v[32:35], v[194:197], v[216:219], v[32:35]
	v_mfma_f32_16x16x32_bf16 v[32:35], v[198:201], v[220:223], v[32:35]
	v_mfma_f32_16x16x32_bf16 v[40:43], v[190:193], v[220:223], v[40:43]
	v_mfma_f32_16x16x32_bf16 v[40:43], v[186:189], v[216:219], v[40:43]
	v_mfma_f32_16x16x32_bf16 v[36:39], v[172:175], v[216:219], v[36:39]
	v_mfma_f32_16x16x32_bf16 v[36:39], v[176:179], v[220:223], v[36:39]
	v_mfma_f32_16x16x32_bf16 v[44:47], v[168:171], v[220:223], v[44:47]
	v_mfma_f32_16x16x32_bf16 v[44:47], v[164:167], v[216:219], v[44:47]
	s_setprio 0
	s_setprio 1
	v_mfma_f32_16x16x32_bf16 v[28:31], v[164:167], v[224:227], v[28:31]
	v_mfma_f32_16x16x32_bf16 v[28:31], v[168:171], v[230:233], v[28:31]
	v_mfma_f32_16x16x32_bf16 v[20:23], v[176:179], v[230:233], v[20:23]
	v_mfma_f32_16x16x32_bf16 v[20:23], v[172:175], v[224:227], v[20:23]
	v_mfma_f32_16x16x32_bf16 v[24:27], v[186:189], v[224:227], v[24:27]
	v_mfma_f32_16x16x32_bf16 v[24:27], v[190:193], v[230:233], v[24:27]
	v_mfma_f32_16x16x32_bf16 v[16:19], v[198:201], v[230:233], v[16:19]
	v_mfma_f32_16x16x32_bf16 v[16:19], v[194:197], v[224:227], v[16:19]
	v_mfma_f32_16x16x32_bf16 v[0:3], v[194:197], v[234:237], v[0:3]
	v_mfma_f32_16x16x32_bf16 v[0:3], v[198:201], v[238:241], v[0:3]
	v_mfma_f32_16x16x32_bf16 v[8:11], v[190:193], v[238:241], v[8:11]
	v_mfma_f32_16x16x32_bf16 v[8:11], v[186:189], v[234:237], v[8:11]
	v_mfma_f32_16x16x32_bf16 v[4:7], v[172:175], v[234:237], v[4:7]
	v_mfma_f32_16x16x32_bf16 v[4:7], v[176:179], v[238:241], v[4:7]
	v_mfma_f32_16x16x32_bf16 v[12:15], v[168:171], v[238:241], v[12:15]
	v_mfma_f32_16x16x32_bf16 v[12:15], v[164:167], v[234:237], v[12:15]
	s_setprio 0
	s_barrier
	s_add_u32 s10, s10, 0x100
	s_addc_u32 s11, s11, 0
	s_add_u32 s20, s20, 0x100
	s_addc_u32 s21, s21, 0
	s_cmp_ge_i32 s22, s55
	s_mov_b32 s12, s22
	s_cbranch_scc0 .LBB0_1131

; #define PG8_STAGE(bufoff, gbase, voff) do { _Pragma("unroll") for (int _i = 0; _i < 2; ++_i) \
;         __builtin_amdgcn_global_load_lds((const unsigned*)((const char*)(gbase) + (voff)[_i]), (LAS unsigned*)(lds + (bufoff) + ldsw + _i * 8192), 16, 0, 0); } while (0)
; #define PG8_LDA(dst, b, h) do { _Pragma("unroll") for (int m = 0; m < 4; ++m) _Pragma("unroll") for (int k = 0; k < 2; ++k) dst[m][k] = *(const LAS bf16x8*)(lds + PG8_SA(b, h) + aoff + m * 2048 + k * 1024); } while (0)
; #define PG8_LDB(dst, b, h) do { _Pragma("unroll") for (int n = 0; n < 2; ++n) _Pragma("unroll") for (int k = 0; k < 2; ++k) dst[n][k] = *(const LAS bf16x8*)(lds + PG8_SB(b, h) + boff + n * 2048 + k * 1024); } while (0)
; #define PG8_MMA(ai, bj, At, Bt) do { __builtin_amdgcn_s_setprio(1); _Pragma("unroll") for (int m = 0; m < 4; ++m) _Pragma("unroll") for (int n = 0; n < 2; ++n) _Pragma("unroll") for (int k = 0; k < 2; ++k) \
;         acc[ai][bj][m][n] = __builtin_amdgcn_mfma_f32_16x16x32_bf16(Bt[n][k], At[m][k], acc[ai][bj][m][n], 0, 0, 0); __builtin_amdgcn_s_setprio(0); } while (0)
; #define PG8_WAIT_V(n) asm volatile("s_waitcnt vmcnt(" #n ")" ::: "memory")
; #define PG8_WAIT_L(n) asm volatile("s_waitcnt lgkmcnt(" #n ")" ::: "memory")
; #define PG8_BAR __builtin_amdgcn_s_barrier()
; #define PG8_SCHED __builtin_amdgcn_sched_barrier(0)
; template <class Epi>
; __device__ __forceinline__ void gemm_phase(LAS unsigned char* lds, const Gemm g, const StaticOrder& S, const Epi& E) {
;     ...
;             const bool last = (t == nt - 2);
;             const char* a1 = cA + (size_t)(t + 1) * kstep;
;             const char* a2 = last ? nA : cA + (size_t)(t + 2) * kstep; const char* b2 = last ? nB : cB + (size_t)(t + 2) * kstep;
;             const char* a3 = a2 + kstep; const char* b3 = b2 + kstep;
;             PG8_LDB(B0, 0, 0); PG8_LDB(B1, 0, 1); PG8_SCHED; PG8_LDA(At, 0, 0); PG8_STAGE(PG8_SA(1, 1), a1 + hstepA, voffA);
;             PG8_WAIT_V(8); PG8_WAIT_L(0); PG8_BAR; PG8_MMA(0, 0, At, B0); PG8_MMA(0, 1, At, B1); PG8_BAR; PG8_SCHED;
;             PG8_LDA(At, 0, 1); PG8_STAGE(PG8_SB(0, 0), b2, voffB); PG8_STAGE(PG8_SB(0, 1), b2 + hstepB, voffB); PG8_STAGE(PG8_SA(0, 0), a2, voffA);
;             PG8_WAIT_V(8); PG8_WAIT_L(0); PG8_BAR; PG8_MMA(1, 0, At, B0); PG8_MMA(1, 1, At, B1); PG8_BAR; PG8_SCHED;
.LBB0_1161:
	ds_read_b128 v[152:155], v149
	ds_read_b128 v[156:159], v149 offset:1024
	ds_read_b128 v[160:163], v149 offset:2048
	ds_read_b128 v[164:167], v149 offset:3072
	ds_read_b128 v[168:171], v150
	ds_read_b128 v[172:175], v150 offset:1024
	ds_read_b128 v[176:179], v150 offset:2048
	ds_read_b128 v[180:183], v150 offset:3072
	s_add_i32 s83, s46, 2
	s_add_u32 s47, s44, 0xffff0080
	s_addc_u32 s48, s45, -1
	s_cmp_eq_u32 s65, s46
	s_cselect_b32 s46, s78, s79
	s_cselect_b32 s49, s35, s48
	s_cselect_b32 s48, s37, s47
	s_cselect_b32 s47, s39, s82
	v_lshl_add_u64 v[220:221], s[44:45], 0, v[140:141]
	s_add_i32 m0, s56, 0xc000
	ds_read_b128 v[184:187], v151
	ds_read_b128 v[188:191], v151 offset:1024
	ds_read_b128 v[192:195], v151 offset:2048
	ds_read_b128 v[196:199], v151 offset:3072
	ds_read_b128 v[200:203], v151 offset:4096
	ds_read_b128 v[208:211], v151 offset:5120
	ds_read_b128 v[212:215], v151 offset:6144
	ds_read_b128 v[216:219], v151 offset:7168
	global_load_lds_dwordx4 v[220:221], off
	v_lshl_add_u64 v[220:221], s[44:45], 0, v[142:143]
	s_add_i32 m0, s56, 0xe000
	s_nop 0
	global_load_lds_dwordx4 v[220:221], off
	s_waitcnt vmcnt(8)
	s_waitcnt lgkmcnt(0)
	s_setprio 1
	s_barrier
	s_waitcnt lgkmcnt(0)
	v_mfma_f32_16x16x32_bf16 v[120:123], v[152:155], v[184:187], v[120:123]
	v_mfma_f32_16x16x32_bf16 v[120:123], v[156:159], v[188:191], v[120:123]
	v_mfma_f32_16x16x32_bf16 v[124:127], v[164:167], v[188:191], v[124:127]
	v_mfma_f32_16x16x32_bf16 v[124:127], v[160:163], v[184:187], v[124:127]
	v_mfma_f32_16x16x32_bf16 v[116:119], v[168:171], v[184:187], v[116:119]
	v_mfma_f32_16x16x32_bf16 v[116:119], v[172:175], v[188:191], v[116:119]
	v_mfma_f32_16x16x32_bf16 v[112:115], v[180:183], v[188:191], v[112:115]
	v_mfma_f32_16x16x32_bf16 v[112:115], v[176:179], v[184:187], v[112:115]
	v_mfma_f32_16x16x32_bf16 v[96:99], v[176:179], v[192:195], v[96:99]
	v_mfma_f32_16x16x32_bf16 v[96:99], v[180:183], v[196:199], v[96:99]
	v_mfma_f32_16x16x32_bf16 v[100:103], v[172:175], v[196:199], v[100:103]
	v_mfma_f32_16x16x32_bf16 v[100:103], v[168:171], v[192:195], v[100:103]
	v_mfma_f32_16x16x32_bf16 v[104:107], v[160:163], v[192:195], v[104:107]
	v_mfma_f32_16x16x32_bf16 v[104:107], v[164:167], v[196:199], v[104:107]
	v_mfma_f32_16x16x32_bf16 v[108:111], v[156:159], v[196:199], v[108:111]
	v_mfma_f32_16x16x32_bf16 v[108:111], v[152:155], v[192:195], v[108:111]
	s_setprio 0
	s_setprio 1
	v_mfma_f32_16x16x32_bf16 v[92:95], v[152:155], v[200:203], v[92:95]
	v_mfma_f32_16x16x32_bf16 v[92:95], v[156:159], v[208:211], v[92:95]
	v_mfma_f32_16x16x32_bf16 v[88:91], v[164:167], v[208:211], v[88:91]
	v_mfma_f32_16x16x32_bf16 v[88:91], v[160:163], v[200:203], v[88:91]
	v_mfma_f32_16x16x32_bf16 v[84:87], v[168:171], v[200:203], v[84:87]
	v_mfma_f32_16x16x32_bf16 v[84:87], v[172:175], v[208:211], v[84:87]
	v_mfma_f32_16x16x32_bf16 v[80:83], v[180:183], v[208:211], v[80:83]
	v_mfma_f32_16x16x32_bf16 v[80:83], v[176:179], v[200:203], v[80:83]
	v_mfma_f32_16x16x32_bf16 v[64:67], v[176:179], v[212:215], v[64:67]
	v_mfma_f32_16x16x32_bf16 v[64:67], v[180:183], v[216:219], v[64:67]
	v_mfma_f32_16x16x32_bf16 v[68:71], v[172:175], v[216:219], v[68:71]
	v_mfma_f32_16x16x32_bf16 v[68:71], v[168:171], v[212:215], v[68:71]
	v_mfma_f32_16x16x32_bf16 v[72:75], v[160:163], v[212:215], v[72:75]
	v_mfma_f32_16x16x32_bf16 v[72:75], v[164:167], v[216:219], v[72:75]
	v_mfma_f32_16x16x32_bf16 v[76:79], v[156:159], v[216:219], v[76:79]
	v_mfma_f32_16x16x32_bf16 v[76:79], v[152:155], v[212:215], v[76:79]
	s_setprio 0
	s_barrier
	s_add_i32 s84, s67, s51
	v_lshl_add_u64 v[220:221], s[46:47], 0, v[130:131]
	s_mov_b32 m0, s84
	ds_read_b128 v[184:187], v151 offset:16384
	ds_read_b128 v[188:191], v151 offset:17408
	ds_read_b128 v[192:195], v151 offset:18432
	ds_read_b128 v[196:199], v151 offset:19456
	ds_read_b128 v[200:203], v151 offset:20480
	ds_read_b128 v[208:211], v151 offset:21504
	ds_read_b128 v[212:215], v151 offset:22528
	ds_read_b128 v[216:219], v151 offset:23552
	global_load_lds_dwordx4 v[220:221], off
	s_add_i32 m0, s84, 0x2000
	s_add_u32 s84, s46, 0x10000
	v_lshl_add_u64 v[222:223], s[46:47], 0, v[134:135]
	s_addc_u32 s85, s47, 0
	s_add_i32 s86, s68, s51
	global_load_lds_dwordx4 v[222:223], off
	v_lshl_add_u64 v[224:225], s[84:85], 0, v[130:131]
	s_mov_b32 m0, s86
	v_lshl_add_u64 v[226:227], s[48:49], 0, v[132:133]
	global_load_lds_dwordx4 v[224:225], off
	v_lshl_add_u64 v[224:225], s[84:85], 0, v[134:135]
	s_add_i32 m0, s86, 0x2000
	s_nop 0
	global_load_lds_dwordx4 v[224:225], off
	v_lshl_add_u64 v[224:225], s[48:49], 0, v[128:129]
	s_mov_b32 m0, s56
	s_nop 0
	global_load_lds_dwordx4 v[224:225], off
	s_mov_b32 m0, s57
	s_nop 0
	global_load_lds_dwordx4 v[226:227], off
	s_waitcnt vmcnt(8)
	s_waitcnt lgkmcnt(0)
	s_setprio 1
	s_barrier
; #define PG8_STAGE(bufoff, gbase, voff) do { _Pragma("unroll") for (int _i = 0; _i < 2; ++_i) \
;         __builtin_amdgcn_global_load_lds((const unsigned*)((const char*)(gbase) + (voff)[_i]), (LAS unsigned*)(lds + (bufoff) + ldsw + _i * 8192), 16, 0, 0); } while (0)
; #define PG8_LDA(dst, b, h) do { _Pragma("unroll") for (int m = 0; m < 4; ++m) _Pragma("unroll") for (int k = 0; k < 2; ++k) dst[m][k] = *(const LAS bf16x8*)(lds + PG8_SA(b, h) + aoff + m * 2048 + k * 1024); } while (0)
; #define PG8_LDB(dst, b, h) do { _Pragma("unroll") for (int n = 0; n < 2; ++n) _Pragma("unroll") for (int k = 0; k < 2; ++k) dst[n][k] = *(const LAS bf16x8*)(lds + PG8_SB(b, h) + boff + n * 2048 + k * 1024); } while (0)
; #define PG8_MMA(ai, bj, At, Bt) do { __builtin_amdgcn_s_setprio(1); _Pragma("unroll") for (int m = 0; m < 4; ++m) _Pragma("unroll") for (int n = 0; n < 2; ++n) _Pragma("unroll") for (int k = 0; k < 2; ++k) \
;         acc[ai][bj][m][n] = __builtin_amdgcn_mfma_f32_16x16x32_bf16(Bt[n][k], At[m][k], acc[ai][bj][m][n], 0, 0, 0); __builtin_amdgcn_s_setprio(0); } while (0)
; #define PG8_WAIT_V(n) asm volatile("s_waitcnt vmcnt(" #n ")" ::: "memory")
; #define PG8_WAIT_L(n) asm volatile("s_waitcnt lgkmcnt(" #n ")" ::: "memory")
; #define PG8_BAR __builtin_amdgcn_s_barrier()
; #define PG8_SCHED __builtin_amdgcn_sched_barrier(0)
; template <class Epi>
; __device__ __forceinline__ void gemm_phase(LAS unsigned char* lds, const Gemm g, const StaticOrder& S, const Epi& E) {
;     ...
;             PG8_WAIT_V(8); PG8_WAIT_L(0); PG8_BAR; PG8_MMA(1, 0, At, B0); PG8_MMA(1, 1, At, B1); PG8_BAR; PG8_SCHED;
;             PG8_LDB(B0, 1, 0); PG8_LDB(B1, 1, 1); PG8_SCHED; PG8_LDA(At, 1, 0); PG8_STAGE(PG8_SA(0, 1), a2 + hstepA, voffA);
;             PG8_WAIT_V(8); PG8_WAIT_L(0); PG8_BAR; PG8_MMA(0, 0, At, B0); PG8_MMA(0, 1, At, B1); PG8_BAR; PG8_SCHED;
	s_waitcnt lgkmcnt(0)
	v_mfma_f32_16x16x32_bf16 v[60:63], v[152:155], v[184:187], v[60:63]
	v_mfma_f32_16x16x32_bf16 v[60:63], v[156:159], v[188:191], v[60:63]
	v_mfma_f32_16x16x32_bf16 v[56:59], v[164:167], v[188:191], v[56:59]
	v_mfma_f32_16x16x32_bf16 v[56:59], v[160:163], v[184:187], v[56:59]
	v_mfma_f32_16x16x32_bf16 v[52:55], v[168:171], v[184:187], v[52:55]
	v_mfma_f32_16x16x32_bf16 v[52:55], v[172:175], v[188:191], v[52:55]
	v_mfma_f32_16x16x32_bf16 v[48:51], v[180:183], v[188:191], v[48:51]
	v_mfma_f32_16x16x32_bf16 v[48:51], v[176:179], v[184:187], v[48:51]
	v_mfma_f32_16x16x32_bf16 v[32:35], v[176:179], v[192:195], v[32:35]
	v_mfma_f32_16x16x32_bf16 v[32:35], v[180:183], v[196:199], v[32:35]
	v_mfma_f32_16x16x32_bf16 v[36:39], v[172:175], v[196:199], v[36:39]
	v_mfma_f32_16x16x32_bf16 v[36:39], v[168:171], v[192:195], v[36:39]
	v_mfma_f32_16x16x32_bf16 v[40:43], v[160:163], v[192:195], v[40:43]
	v_mfma_f32_16x16x32_bf16 v[40:43], v[164:167], v[196:199], v[40:43]
	v_mfma_f32_16x16x32_bf16 v[44:47], v[156:159], v[196:199], v[44:47]
	v_mfma_f32_16x16x32_bf16 v[44:47], v[152:155], v[192:195], v[44:47]
	s_setprio 0
	s_setprio 1
	v_mfma_f32_16x16x32_bf16 v[28:31], v[152:155], v[200:203], v[28:31]
	v_mfma_f32_16x16x32_bf16 v[28:31], v[156:159], v[208:211], v[28:31]
	v_mfma_f32_16x16x32_bf16 v[24:27], v[164:167], v[208:211], v[24:27]
	v_mfma_f32_16x16x32_bf16 v[24:27], v[160:163], v[200:203], v[24:27]
	v_mfma_f32_16x16x32_bf16 v[20:23], v[168:171], v[200:203], v[20:23]
	v_mfma_f32_16x16x32_bf16 v[20:23], v[172:175], v[208:211], v[20:23]
	v_mfma_f32_16x16x32_bf16 v[16:19], v[180:183], v[208:211], v[16:19]
	v_mfma_f32_16x16x32_bf16 v[16:19], v[176:179], v[200:203], v[16:19]
	v_mfma_f32_16x16x32_bf16 v[0:3], v[176:179], v[212:215], v[0:3]
	v_mfma_f32_16x16x32_bf16 v[0:3], v[180:183], v[216:219], v[0:3]
	v_mfma_f32_16x16x32_bf16 v[4:7], v[172:175], v[216:219], v[4:7]
	v_mfma_f32_16x16x32_bf16 v[4:7], v[168:171], v[212:215], v[4:7]
	v_mfma_f32_16x16x32_bf16 v[8:11], v[160:163], v[212:215], v[8:11]
	v_mfma_f32_16x16x32_bf16 v[8:11], v[164:167], v[216:219], v[8:11]
	v_mfma_f32_16x16x32_bf16 v[12:15], v[156:159], v[216:219], v[12:15]
	v_mfma_f32_16x16x32_bf16 v[12:15], v[152:155], v[212:215], v[12:15]
	s_setprio 0
	s_barrier
	s_add_i32 s84, 0, 0x18000
	s_add_i32 s85, 0, 0x1c000
	v_add_u32_e32 v164, s84, v148
	v_add_u32_e32 v180, s85, v148
	ds_read_b128 v[152:155], v164
	ds_read_b128 v[156:159], v164 offset:1024
	ds_read_b128 v[160:163], v164 offset:2048
	ds_read_b128 v[164:167], v164 offset:3072
	ds_read_b128 v[168:171], v180
	ds_read_b128 v[172:175], v180 offset:1024
	ds_read_b128 v[176:179], v180 offset:2048
	ds_read_b128 v[180:183], v180 offset:3072
	s_add_u32 s48, s48, 0x10000
	s_addc_u32 s49, s49, 0
	s_mov_b32 m0, s58
	v_lshl_add_u64 v[230:231], s[48:49], 0, v[128:129]
	ds_read_b128 v[184:187], v151 offset:32768
	ds_read_b128 v[188:191], v151 offset:33792
	ds_read_b128 v[192:195], v151 offset:34816
	ds_read_b128 v[196:199], v151 offset:35840
	ds_read_b128 v[200:203], v151 offset:36864
	ds_read_b128 v[208:211], v151 offset:37888
	ds_read_b128 v[212:215], v151 offset:38912
	ds_read_b128 v[216:219], v151 offset:39936
	global_load_lds_dwordx4 v[230:231], off
	v_lshl_add_u64 v[230:231], s[48:49], 0, v[132:133]
	s_mov_b32 m0, s59
	s_nop 0
	global_load_lds_dwordx4 v[230:231], off
	s_waitcnt vmcnt(8)
	s_waitcnt lgkmcnt(0)
	s_setprio 1
	s_barrier
	s_waitcnt lgkmcnt(0)
	v_mfma_f32_16x16x32_bf16 v[120:123], v[152:155], v[184:187], v[120:123]
	v_mfma_f32_16x16x32_bf16 v[120:123], v[156:159], v[188:191], v[120:123]
	v_mfma_f32_16x16x32_bf16 v[124:127], v[164:167], v[188:191], v[124:127]
	v_mfma_f32_16x16x32_bf16 v[124:127], v[160:163], v[184:187], v[124:127]
	v_mfma_f32_16x16x32_bf16 v[116:119], v[168:171], v[184:187], v[116:119]
	v_mfma_f32_16x16x32_bf16 v[116:119], v[172:175], v[188:191], v[116:119]
	v_mfma_f32_16x16x32_bf16 v[112:115], v[180:183], v[188:191], v[112:115]
	v_mfma_f32_16x16x32_bf16 v[112:115], v[176:179], v[184:187], v[112:115]
	v_mfma_f32_16x16x32_bf16 v[96:99], v[176:179], v[192:195], v[96:99]
	v_mfma_f32_16x16x32_bf16 v[96:99], v[180:183], v[196:199], v[96:99]
	v_mfma_f32_16x16x32_bf16 v[100:103], v[172:175], v[196:199], v[100:103]
	v_mfma_f32_16x16x32_bf16 v[100:103], v[168:171], v[192:195], v[100:103]
	v_mfma_f32_16x16x32_bf16 v[104:107], v[160:163], v[192:195], v[104:107]
	v_mfma_f32_16x16x32_bf16 v[104:107], v[164:167], v[196:199], v[104:107]
	v_mfma_f32_16x16x32_bf16 v[108:111], v[156:159], v[196:199], v[108:111]
	v_mfma_f32_16x16x32_bf16 v[108:111], v[152:155], v[192:195], v[108:111]
	s_setprio 0
	s_setprio 1
	v_mfma_f32_16x16x32_bf16 v[92:95], v[152:155], v[200:203], v[92:95]
	v_mfma_f32_16x16x32_bf16 v[92:95], v[156:159], v[208:211], v[92:95]
	v_mfma_f32_16x16x32_bf16 v[88:91], v[164:167], v[208:211], v[88:91]
	v_mfma_f32_16x16x32_bf16 v[88:91], v[160:163], v[200:203], v[88:91]
	v_mfma_f32_16x16x32_bf16 v[84:87], v[168:171], v[200:203], v[84:87]
	v_mfma_f32_16x16x32_bf16 v[84:87], v[172:175], v[208:211], v[84:87]
	v_mfma_f32_16x16x32_bf16 v[80:83], v[180:183], v[208:211], v[80:83]
	v_mfma_f32_16x16x32_bf16 v[80:83], v[176:179], v[200:203], v[80:83]
	v_mfma_f32_16x16x32_bf16 v[64:67], v[176:179], v[212:215], v[64:67]
	v_mfma_f32_16x16x32_bf16 v[64:67], v[180:183], v[216:219], v[64:67]
	v_mfma_f32_16x16x32_bf16 v[68:71], v[172:175], v[216:219], v[68:71]
	v_mfma_f32_16x16x32_bf16 v[68:71], v[168:171], v[212:215], v[68:71]
	v_mfma_f32_16x16x32_bf16 v[72:75], v[160:163], v[212:215], v[72:75]
	v_mfma_f32_16x16x32_bf16 v[72:75], v[164:167], v[216:219], v[72:75]
	v_mfma_f32_16x16x32_bf16 v[76:79], v[156:159], v[216:219], v[76:79]
	v_mfma_f32_16x16x32_bf16 v[76:79], v[152:155], v[212:215], v[76:79]
	s_setprio 0
	s_barrier
; #define PG8_STAGE(bufoff, gbase, voff) do { _Pragma("unroll") for (int _i = 0; _i < 2; ++_i) \
;         __builtin_amdgcn_global_load_lds((const unsigned*)((const char*)(gbase) + (voff)[_i]), (LAS unsigned*)(lds + (bufoff) + ldsw + _i * 8192), 16, 0, 0); } while (0)
; #define PG8_LDA(dst, b, h) do { _Pragma("unroll") for (int m = 0; m < 4; ++m) _Pragma("unroll") for (int k = 0; k < 2; ++k) dst[m][k] = *(const LAS bf16x8*)(lds + PG8_SA(b, h) + aoff + m * 2048 + k * 1024); } while (0)
; #define PG8_MMA(ai, bj, At, Bt) do { __builtin_amdgcn_s_setprio(1); _Pragma("unroll") for (int m = 0; m < 4; ++m) _Pragma("unroll") for (int n = 0; n < 2; ++n) _Pragma("unroll") for (int k = 0; k < 2; ++k) \
;         acc[ai][bj][m][n] = __builtin_amdgcn_mfma_f32_16x16x32_bf16(Bt[n][k], At[m][k], acc[ai][bj][m][n], 0, 0, 0); __builtin_amdgcn_s_setprio(0); } while (0)
; #define PG8_WAIT_V(n) asm volatile("s_waitcnt vmcnt(" #n ")" ::: "memory")
; #define PG8_WAIT_L(n) asm volatile("s_waitcnt lgkmcnt(" #n ")" ::: "memory")
; #define PG8_BAR __builtin_amdgcn_s_barrier()
; #define PG8_SCHED __builtin_amdgcn_sched_barrier(0)
; template <class Epi>
; __device__ __forceinline__ void gemm_phase(LAS unsigned char* lds, const Gemm g, const StaticOrder& S, const Epi& E) {
;     ...
;             PG8_LDA(At, 1, 1); PG8_STAGE(PG8_SB(1, 0), b3, voffB); PG8_STAGE(PG8_SB(1, 1), b3 + hstepB, voffB); PG8_STAGE(PG8_SA(1, 0), a3, voffA);
;             PG8_WAIT_V(8); PG8_WAIT_L(0); PG8_BAR; PG8_MMA(1, 0, At, B0); PG8_MMA(1, 1, At, B1); PG8_BAR; PG8_SCHED;
;         }
	s_add_i32 s48, s84, s51
	v_lshl_add_u64 v[220:221], v[220:221], 0, s[12:13]
	s_mov_b32 m0, s48
	ds_read_b128 v[184:187], v151 offset:49152
	ds_read_b128 v[188:191], v151 offset:50176
	ds_read_b128 v[192:195], v151 offset:51200
	ds_read_b128 v[196:199], v151 offset:52224
	ds_read_b128 v[200:203], v151 offset:53248
	ds_read_b128 v[208:211], v151 offset:54272
	ds_read_b128 v[212:215], v151 offset:55296
	ds_read_b128 v[216:219], v151 offset:56320
	global_load_lds_dwordx4 v[220:221], off
	s_add_i32 m0, s48, 0x2000
	s_add_u32 s46, s46, 0x10080
	v_lshl_add_u64 v[220:221], v[222:223], 0, s[12:13]
	s_addc_u32 s47, s47, 0
	s_add_i32 s48, s85, s51
	global_load_lds_dwordx4 v[220:221], off
	v_lshl_add_u64 v[220:221], s[46:47], 0, v[130:131]
	s_mov_b32 m0, s48
	s_nop 0
	global_load_lds_dwordx4 v[220:221], off
	v_lshl_add_u64 v[220:221], s[46:47], 0, v[134:135]
	s_add_i32 m0, s48, 0x2000
	s_nop 0
	global_load_lds_dwordx4 v[220:221], off
	v_lshl_add_u64 v[220:221], v[224:225], 0, s[12:13]
	s_mov_b32 m0, s63
	s_nop 0
	global_load_lds_dwordx4 v[220:221], off
	v_lshl_add_u64 v[220:221], v[226:227], 0, s[12:13]
	s_mov_b32 m0, s64
	s_nop 0
	global_load_lds_dwordx4 v[220:221], off
	s_waitcnt vmcnt(8)
	s_waitcnt lgkmcnt(0)
	s_setprio 1
	s_barrier
	s_waitcnt lgkmcnt(0)
	v_mfma_f32_16x16x32_bf16 v[60:63], v[152:155], v[184:187], v[60:63]
	v_mfma_f32_16x16x32_bf16 v[60:63], v[156:159], v[188:191], v[60:63]
	v_mfma_f32_16x16x32_bf16 v[56:59], v[164:167], v[188:191], v[56:59]
	v_mfma_f32_16x16x32_bf16 v[56:59], v[160:163], v[184:187], v[56:59]
	v_mfma_f32_16x16x32_bf16 v[52:55], v[168:171], v[184:187], v[52:55]
	v_mfma_f32_16x16x32_bf16 v[52:55], v[172:175], v[188:191], v[52:55]
	v_mfma_f32_16x16x32_bf16 v[48:51], v[180:183], v[188:191], v[48:51]
	v_mfma_f32_16x16x32_bf16 v[48:51], v[176:179], v[184:187], v[48:51]
	v_mfma_f32_16x16x32_bf16 v[32:35], v[176:179], v[192:195], v[32:35]
	v_mfma_f32_16x16x32_bf16 v[32:35], v[180:183], v[196:199], v[32:35]
	v_mfma_f32_16x16x32_bf16 v[36:39], v[172:175], v[196:199], v[36:39]
	v_mfma_f32_16x16x32_bf16 v[36:39], v[168:171], v[192:195], v[36:39]
	v_mfma_f32_16x16x32_bf16 v[40:43], v[160:163], v[192:195], v[40:43]
	v_mfma_f32_16x16x32_bf16 v[40:43], v[164:167], v[196:199], v[40:43]
	v_mfma_f32_16x16x32_bf16 v[44:47], v[156:159], v[196:199], v[44:47]
	v_mfma_f32_16x16x32_bf16 v[44:47], v[152:155], v[192:195], v[44:47]
	s_setprio 0
	s_setprio 1
	v_mfma_f32_16x16x32_bf16 v[28:31], v[152:155], v[200:203], v[28:31]
	v_mfma_f32_16x16x32_bf16 v[28:31], v[156:159], v[208:211], v[28:31]
	v_mfma_f32_16x16x32_bf16 v[24:27], v[164:167], v[208:211], v[24:27]
	v_mfma_f32_16x16x32_bf16 v[24:27], v[160:163], v[200:203], v[24:27]
	v_mfma_f32_16x16x32_bf16 v[20:23], v[168:171], v[200:203], v[20:23]
	v_mfma_f32_16x16x32_bf16 v[20:23], v[172:175], v[208:211], v[20:23]
	v_mfma_f32_16x16x32_bf16 v[16:19], v[180:183], v[208:211], v[16:19]
	v_mfma_f32_16x16x32_bf16 v[16:19], v[176:179], v[200:203], v[16:19]
	v_mfma_f32_16x16x32_bf16 v[0:3], v[176:179], v[212:215], v[0:3]
	v_mfma_f32_16x16x32_bf16 v[0:3], v[180:183], v[216:219], v[0:3]
	v_mfma_f32_16x16x32_bf16 v[4:7], v[172:175], v[216:219], v[4:7]
	v_mfma_f32_16x16x32_bf16 v[4:7], v[168:171], v[212:215], v[4:7]
	v_mfma_f32_16x16x32_bf16 v[8:11], v[160:163], v[212:215], v[8:11]
	v_mfma_f32_16x16x32_bf16 v[8:11], v[164:167], v[216:219], v[8:11]
	v_mfma_f32_16x16x32_bf16 v[12:15], v[156:159], v[216:219], v[12:15]
	v_mfma_f32_16x16x32_bf16 v[12:15], v[152:155], v[212:215], v[12:15]
	s_setprio 0
	s_barrier
	s_add_u32 s44, s44, 0x100
	s_addc_u32 s45, s45, 0
	s_add_u32 s79, s79, 0x100
	s_addc_u32 s82, s82, 0
	s_cmp_ge_i32 s83, s61
	s_mov_b32 s46, s83
	s_cbranch_scc0 .LBB0_1161

; #define PG8_STAGE(bufoff, gbase, voff) do { _Pragma("unroll") for (int _i = 0; _i < 2; ++_i) \
;         __builtin_amdgcn_global_load_lds((const unsigned*)((const char*)(gbase) + (voff)[_i]), (LAS unsigned*)(lds + (bufoff) + ldsw + _i * 8192), 16, 0, 0); } while (0)
; #define PG8_LDA(dst, b, h) do { _Pragma("unroll") for (int m = 0; m < 4; ++m) _Pragma("unroll") for (int k = 0; k < 2; ++k) dst[m][k] = *(const LAS bf16x8*)(lds + PG8_SA(b, h) + aoff + m * 2048 + k * 1024); } while (0)
; #define PG8_LDB(dst, b, h) do { _Pragma("unroll") for (int n = 0; n < 2; ++n) _Pragma("unroll") for (int k = 0; k < 2; ++k) dst[n][k] = *(const LAS bf16x8*)(lds + PG8_SB(b, h) + boff + n * 2048 + k * 1024); } while (0)
; #define PG8_MMA(ai, bj, At, Bt) do { __builtin_amdgcn_s_setprio(1); _Pragma("unroll") for (int m = 0; m < 4; ++m) _Pragma("unroll") for (int n = 0; n < 2; ++n) _Pragma("unroll") for (int k = 0; k < 2; ++k) \
;         acc[ai][bj][m][n] = __builtin_amdgcn_mfma_f32_16x16x32_bf16(Bt[n][k], At[m][k], acc[ai][bj][m][n], 0, 0, 0); __builtin_amdgcn_s_setprio(0); } while (0)
; #define PG8_WAIT_V(n) asm volatile("s_waitcnt vmcnt(" #n ")" ::: "memory")
; #define PG8_WAIT_L(n) asm volatile("s_waitcnt lgkmcnt(" #n ")" ::: "memory")
; #define PG8_BAR __builtin_amdgcn_s_barrier()
; #define PG8_SCHED __builtin_amdgcn_sched_barrier(0)
; template <class Epi>
; __device__ __forceinline__ void gemm_phase(LAS unsigned char* lds, const Gemm g, const StaticOrder& S, const Epi& E) {
;     ...
;             const bool last = (t == nt - 2);
;             const char* a1 = cA + (size_t)(t + 1) * kstep;
;             const char* a2 = last ? nA : cA + (size_t)(t + 2) * kstep; const char* b2 = last ? nB : cB + (size_t)(t + 2) * kstep;
;             const char* a3 = a2 + kstep; const char* b3 = b2 + kstep;
;             PG8_LDB(B0, 0, 0); PG8_LDB(B1, 0, 1); PG8_SCHED; PG8_LDA(At, 0, 0); PG8_STAGE(PG8_SA(1, 1), a1 + hstepA, voffA);
;             PG8_WAIT_V(8); PG8_WAIT_L(0); PG8_BAR; PG8_MMA(0, 0, At, B0); PG8_MMA(0, 1, At, B1); PG8_BAR; PG8_SCHED;
;             PG8_LDA(At, 0, 1); PG8_STAGE(PG8_SB(0, 0), b2, voffB); PG8_STAGE(PG8_SB(0, 1), b2 + hstepB, voffB); PG8_STAGE(PG8_SA(0, 0), a2, voffA);
;             PG8_WAIT_V(8); PG8_WAIT_L(0); PG8_BAR; PG8_MMA(1, 0, At, B0); PG8_MMA(1, 1, At, B1); PG8_BAR; PG8_SCHED;
.LBB0_1244:
	ds_read_b128 v[150:153], v187
	ds_read_b128 v[154:157], v187 offset:1024
	ds_read_b128 v[158:161], v187 offset:2048
	ds_read_b128 v[162:165], v187 offset:3072
	ds_read_b128 v[166:169], v188
	ds_read_b128 v[170:173], v188 offset:1024
	ds_read_b128 v[174:177], v188 offset:2048
	ds_read_b128 v[178:181], v188 offset:3072
	s_add_i32 s84, s52, 2
	s_add_u32 s12, s4, 0x100
	s_addc_u32 s13, s5, 0
	s_cmp_eq_u32 s67, s52
	s_cselect_b32 s52, s50, s1
	s_cselect_b32 s55, s49, s13
	s_cselect_b32 s54, s48, s12
	s_cselect_b32 s53, s51, s77
	v_lshl_add_u64 v[224:225], s[4:5], 0, v[142:143]
	s_add_i32 m0, s59, 0xc000
	ds_read_b128 v[182:185], v189
	ds_read_b128 v[192:195], v189 offset:1024
	ds_read_b128 v[196:199], v189 offset:2048
	ds_read_b128 v[200:203], v189 offset:3072
	ds_read_b128 v[208:211], v189 offset:4096
	ds_read_b128 v[212:215], v189 offset:5120
	ds_read_b128 v[216:219], v189 offset:6144
	ds_read_b128 v[220:223], v189 offset:7168
	global_load_lds_dwordx4 v[224:225], off
	v_lshl_add_u64 v[224:225], s[4:5], 0, v[144:145]
	s_add_i32 m0, s59, 0xe000
	s_nop 0
	global_load_lds_dwordx4 v[224:225], off
	s_waitcnt vmcnt(8)
	s_waitcnt lgkmcnt(0)
	s_setprio 1
	s_barrier
	s_waitcnt lgkmcnt(0)
	v_mfma_f32_16x16x32_bf16 v[124:127], v[150:153], v[182:185], v[124:127]
	v_mfma_f32_16x16x32_bf16 v[124:127], v[154:157], v[192:195], v[124:127]
	v_mfma_f32_16x16x32_bf16 v[120:123], v[162:165], v[192:195], v[120:123]
	v_mfma_f32_16x16x32_bf16 v[120:123], v[158:161], v[182:185], v[120:123]
	v_mfma_f32_16x16x32_bf16 v[108:111], v[166:169], v[182:185], v[108:111]
	v_mfma_f32_16x16x32_bf16 v[108:111], v[170:173], v[192:195], v[108:111]
	v_mfma_f32_16x16x32_bf16 v[100:103], v[178:181], v[192:195], v[100:103]
	v_mfma_f32_16x16x32_bf16 v[100:103], v[174:177], v[182:185], v[100:103]
	v_mfma_f32_16x16x32_bf16 v[84:87], v[174:177], v[196:199], v[84:87]
	v_mfma_f32_16x16x32_bf16 v[84:87], v[178:181], v[200:203], v[84:87]
	v_mfma_f32_16x16x32_bf16 v[92:95], v[170:173], v[200:203], v[92:95]
	v_mfma_f32_16x16x32_bf16 v[92:95], v[166:169], v[196:199], v[92:95]
	v_mfma_f32_16x16x32_bf16 v[112:115], v[158:161], v[196:199], v[112:115]
	v_mfma_f32_16x16x32_bf16 v[112:115], v[162:165], v[200:203], v[112:115]
	v_mfma_f32_16x16x32_bf16 v[116:119], v[154:157], v[200:203], v[116:119]
	v_mfma_f32_16x16x32_bf16 v[116:119], v[150:153], v[196:199], v[116:119]
	s_setprio 0
	s_setprio 1
	v_mfma_f32_16x16x32_bf16 v[104:107], v[150:153], v[208:211], v[104:107]
	v_mfma_f32_16x16x32_bf16 v[104:107], v[154:157], v[212:215], v[104:107]
	v_mfma_f32_16x16x32_bf16 v[96:99], v[162:165], v[212:215], v[96:99]
	v_mfma_f32_16x16x32_bf16 v[96:99], v[158:161], v[208:211], v[96:99]
	v_mfma_f32_16x16x32_bf16 v[76:79], v[166:169], v[208:211], v[76:79]
	v_mfma_f32_16x16x32_bf16 v[76:79], v[170:173], v[212:215], v[76:79]
	v_mfma_f32_16x16x32_bf16 v[72:75], v[178:181], v[212:215], v[72:75]
	v_mfma_f32_16x16x32_bf16 v[72:75], v[174:177], v[208:211], v[72:75]
	v_mfma_f32_16x16x32_bf16 v[64:67], v[174:177], v[216:219], v[64:67]
	v_mfma_f32_16x16x32_bf16 v[64:67], v[178:181], v[220:223], v[64:67]
	v_mfma_f32_16x16x32_bf16 v[68:71], v[170:173], v[220:223], v[68:71]
	v_mfma_f32_16x16x32_bf16 v[68:71], v[166:169], v[216:219], v[68:71]
	v_mfma_f32_16x16x32_bf16 v[80:83], v[158:161], v[216:219], v[80:83]
	v_mfma_f32_16x16x32_bf16 v[80:83], v[162:165], v[220:223], v[80:83]
	v_mfma_f32_16x16x32_bf16 v[88:91], v[154:157], v[220:223], v[88:91]
	v_mfma_f32_16x16x32_bf16 v[88:91], v[150:153], v[216:219], v[88:91]
	s_setprio 0
	s_barrier
	s_add_i32 s4, s70, s58
	v_lshl_add_u64 v[224:225], s[52:53], 0, v[130:131]
	s_mov_b32 m0, s4
	ds_read_b128 v[182:185], v189 offset:16384
	ds_read_b128 v[192:195], v189 offset:17408
	ds_read_b128 v[196:199], v189 offset:18432
	ds_read_b128 v[200:203], v189 offset:19456
	ds_read_b128 v[208:211], v189 offset:20480
	ds_read_b128 v[212:215], v189 offset:21504
	ds_read_b128 v[216:219], v189 offset:22528
	ds_read_b128 v[220:223], v189 offset:23552
	global_load_lds_dwordx4 v[224:225], off
	s_add_i32 m0, s4, 0x2000
	s_add_u32 s4, s52, 0x158000
	v_lshl_add_u64 v[226:227], s[52:53], 0, v[134:135]
	s_addc_u32 s5, s53, 0
	s_add_i32 s85, s71, s58
	global_load_lds_dwordx4 v[226:227], off
	v_lshl_add_u64 v[230:231], s[4:5], 0, v[130:131]
	s_mov_b32 m0, s85
	v_lshl_add_u64 v[232:233], s[54:55], 0, v[132:133]
	global_load_lds_dwordx4 v[230:231], off
	v_lshl_add_u64 v[230:231], s[4:5], 0, v[134:135]
	s_add_i32 m0, s85, 0x2000
	s_nop 0
	global_load_lds_dwordx4 v[230:231], off
	v_lshl_add_u64 v[230:231], s[54:55], 0, v[128:129]
	s_mov_b32 m0, s59
	s_nop 0
	global_load_lds_dwordx4 v[230:231], off
	s_mov_b32 m0, s60
	s_nop 0
	global_load_lds_dwordx4 v[232:233], off
	s_waitcnt vmcnt(8)
	s_waitcnt lgkmcnt(0)
	s_setprio 1
	s_barrier
; #define PG8_STAGE(bufoff, gbase, voff) do { _Pragma("unroll") for (int _i = 0; _i < 2; ++_i) \
;         __builtin_amdgcn_global_load_lds((const unsigned*)((const char*)(gbase) + (voff)[_i]), (LAS unsigned*)(lds + (bufoff) + ldsw + _i * 8192), 16, 0, 0); } while (0)
; #define PG8_LDA(dst, b, h) do { _Pragma("unroll") for (int m = 0; m < 4; ++m) _Pragma("unroll") for (int k = 0; k < 2; ++k) dst[m][k] = *(const LAS bf16x8*)(lds + PG8_SA(b, h) + aoff + m * 2048 + k * 1024); } while (0)
; #define PG8_LDB(dst, b, h) do { _Pragma("unroll") for (int n = 0; n < 2; ++n) _Pragma("unroll") for (int k = 0; k < 2; ++k) dst[n][k] = *(const LAS bf16x8*)(lds + PG8_SB(b, h) + boff + n * 2048 + k * 1024); } while (0)
; #define PG8_MMA(ai, bj, At, Bt) do { __builtin_amdgcn_s_setprio(1); _Pragma("unroll") for (int m = 0; m < 4; ++m) _Pragma("unroll") for (int n = 0; n < 2; ++n) _Pragma("unroll") for (int k = 0; k < 2; ++k) \
;         acc[ai][bj][m][n] = __builtin_amdgcn_mfma_f32_16x16x32_bf16(Bt[n][k], At[m][k], acc[ai][bj][m][n], 0, 0, 0); __builtin_amdgcn_s_setprio(0); } while (0)
; #define PG8_WAIT_V(n) asm volatile("s_waitcnt vmcnt(" #n ")" ::: "memory")
; #define PG8_WAIT_L(n) asm volatile("s_waitcnt lgkmcnt(" #n ")" ::: "memory")
; #define PG8_BAR __builtin_amdgcn_s_barrier()
; #define PG8_SCHED __builtin_amdgcn_sched_barrier(0)
; template <class Epi>
; __device__ __forceinline__ void gemm_phase(LAS unsigned char* lds, const Gemm g, const StaticOrder& S, const Epi& E) {
;     ...
;             PG8_WAIT_V(8); PG8_WAIT_L(0); PG8_BAR; PG8_MMA(1, 0, At, B0); PG8_MMA(1, 1, At, B1); PG8_BAR; PG8_SCHED;
;             PG8_LDB(B0, 1, 0); PG8_LDB(B1, 1, 1); PG8_SCHED; PG8_LDA(At, 1, 0); PG8_STAGE(PG8_SA(0, 1), a2 + hstepA, voffA);
;             PG8_WAIT_V(8); PG8_WAIT_L(0); PG8_BAR; PG8_MMA(0, 0, At, B0); PG8_MMA(0, 1, At, B1); PG8_BAR; PG8_SCHED;
	s_waitcnt lgkmcnt(0)
	v_mfma_f32_16x16x32_bf16 v[60:63], v[150:153], v[182:185], v[60:63]
	v_mfma_f32_16x16x32_bf16 v[60:63], v[154:157], v[192:195], v[60:63]
	v_mfma_f32_16x16x32_bf16 v[56:59], v[162:165], v[192:195], v[56:59]
	v_mfma_f32_16x16x32_bf16 v[56:59], v[158:161], v[182:185], v[56:59]
	v_mfma_f32_16x16x32_bf16 v[44:47], v[166:169], v[182:185], v[44:47]
	v_mfma_f32_16x16x32_bf16 v[44:47], v[170:173], v[192:195], v[44:47]
	v_mfma_f32_16x16x32_bf16 v[36:39], v[178:181], v[192:195], v[36:39]
	v_mfma_f32_16x16x32_bf16 v[36:39], v[174:177], v[182:185], v[36:39]
	v_mfma_f32_16x16x32_bf16 v[20:23], v[174:177], v[196:199], v[20:23]
	v_mfma_f32_16x16x32_bf16 v[20:23], v[178:181], v[200:203], v[20:23]
	v_mfma_f32_16x16x32_bf16 v[28:31], v[170:173], v[200:203], v[28:31]
	v_mfma_f32_16x16x32_bf16 v[28:31], v[166:169], v[196:199], v[28:31]
	v_mfma_f32_16x16x32_bf16 v[48:51], v[158:161], v[196:199], v[48:51]
	v_mfma_f32_16x16x32_bf16 v[48:51], v[162:165], v[200:203], v[48:51]
	v_mfma_f32_16x16x32_bf16 v[52:55], v[154:157], v[200:203], v[52:55]
	v_mfma_f32_16x16x32_bf16 v[52:55], v[150:153], v[196:199], v[52:55]
	s_setprio 0
	s_setprio 1
	v_mfma_f32_16x16x32_bf16 v[40:43], v[150:153], v[208:211], v[40:43]
	v_mfma_f32_16x16x32_bf16 v[40:43], v[154:157], v[212:215], v[40:43]
	v_mfma_f32_16x16x32_bf16 v[32:35], v[162:165], v[212:215], v[32:35]
	v_mfma_f32_16x16x32_bf16 v[32:35], v[158:161], v[208:211], v[32:35]
	v_mfma_f32_16x16x32_bf16 v[12:15], v[166:169], v[208:211], v[12:15]
	v_mfma_f32_16x16x32_bf16 v[12:15], v[170:173], v[212:215], v[12:15]
	v_mfma_f32_16x16x32_bf16 v[8:11], v[178:181], v[212:215], v[8:11]
	v_mfma_f32_16x16x32_bf16 v[8:11], v[174:177], v[208:211], v[8:11]
	v_mfma_f32_16x16x32_bf16 v[0:3], v[174:177], v[216:219], v[0:3]
	v_mfma_f32_16x16x32_bf16 v[0:3], v[178:181], v[220:223], v[0:3]
	v_mfma_f32_16x16x32_bf16 v[4:7], v[170:173], v[220:223], v[4:7]
	v_mfma_f32_16x16x32_bf16 v[4:7], v[166:169], v[216:219], v[4:7]
	v_mfma_f32_16x16x32_bf16 v[16:19], v[158:161], v[216:219], v[16:19]
	v_mfma_f32_16x16x32_bf16 v[16:19], v[162:165], v[220:223], v[16:19]
	v_mfma_f32_16x16x32_bf16 v[24:27], v[154:157], v[220:223], v[24:27]
	v_mfma_f32_16x16x32_bf16 v[24:27], v[150:153], v[216:219], v[24:27]
	s_setprio 0
	s_barrier
	s_add_i32 s85, 0, 0x18000
	s_add_i32 s86, 0, 0x1c000
	v_add_u32_e32 v162, s85, v186
	v_add_u32_e32 v178, s86, v186
	ds_read_b128 v[150:153], v162
	ds_read_b128 v[154:157], v162 offset:1024
	ds_read_b128 v[158:161], v162 offset:2048
	ds_read_b128 v[162:165], v162 offset:3072
	ds_read_b128 v[166:169], v178
	ds_read_b128 v[170:173], v178 offset:1024
	ds_read_b128 v[174:177], v178 offset:2048
	ds_read_b128 v[178:181], v178 offset:3072
	s_add_u32 s4, s54, 0x158000
	s_addc_u32 s5, s55, 0
	s_mov_b32 m0, s61
	v_lshl_add_u64 v[234:235], s[4:5], 0, v[128:129]
	ds_read_b128 v[182:185], v189 offset:32768
	ds_read_b128 v[192:195], v189 offset:33792
	ds_read_b128 v[196:199], v189 offset:34816
	ds_read_b128 v[200:203], v189 offset:35840
	ds_read_b128 v[208:211], v189 offset:36864
	ds_read_b128 v[212:215], v189 offset:37888
	ds_read_b128 v[216:219], v189 offset:38912
	ds_read_b128 v[220:223], v189 offset:39936
	global_load_lds_dwordx4 v[234:235], off
	v_lshl_add_u64 v[234:235], s[4:5], 0, v[132:133]
	s_mov_b32 m0, s62
	s_nop 0
	global_load_lds_dwordx4 v[234:235], off
	s_waitcnt vmcnt(8)
	s_waitcnt lgkmcnt(0)
	s_setprio 1
	s_barrier
	s_waitcnt lgkmcnt(0)
	v_mfma_f32_16x16x32_bf16 v[124:127], v[150:153], v[182:185], v[124:127]
	v_mfma_f32_16x16x32_bf16 v[124:127], v[154:157], v[192:195], v[124:127]
	v_mfma_f32_16x16x32_bf16 v[120:123], v[162:165], v[192:195], v[120:123]
	v_mfma_f32_16x16x32_bf16 v[120:123], v[158:161], v[182:185], v[120:123]
	v_mfma_f32_16x16x32_bf16 v[108:111], v[166:169], v[182:185], v[108:111]
	v_mfma_f32_16x16x32_bf16 v[108:111], v[170:173], v[192:195], v[108:111]
	v_mfma_f32_16x16x32_bf16 v[100:103], v[178:181], v[192:195], v[100:103]
	v_mfma_f32_16x16x32_bf16 v[100:103], v[174:177], v[182:185], v[100:103]
	v_mfma_f32_16x16x32_bf16 v[84:87], v[174:177], v[196:199], v[84:87]
	v_mfma_f32_16x16x32_bf16 v[84:87], v[178:181], v[200:203], v[84:87]
	v_mfma_f32_16x16x32_bf16 v[92:95], v[170:173], v[200:203], v[92:95]
	v_mfma_f32_16x16x32_bf16 v[92:95], v[166:169], v[196:199], v[92:95]
	v_mfma_f32_16x16x32_bf16 v[112:115], v[158:161], v[196:199], v[112:115]
	v_mfma_f32_16x16x32_bf16 v[112:115], v[162:165], v[200:203], v[112:115]
	v_mfma_f32_16x16x32_bf16 v[116:119], v[154:157], v[200:203], v[116:119]
	v_mfma_f32_16x16x32_bf16 v[116:119], v[150:153], v[196:199], v[116:119]
	s_setprio 0
	s_setprio 1
	v_mfma_f32_16x16x32_bf16 v[104:107], v[150:153], v[208:211], v[104:107]
	v_mfma_f32_16x16x32_bf16 v[104:107], v[154:157], v[212:215], v[104:107]
	v_mfma_f32_16x16x32_bf16 v[96:99], v[162:165], v[212:215], v[96:99]
	v_mfma_f32_16x16x32_bf16 v[96:99], v[158:161], v[208:211], v[96:99]
	v_mfma_f32_16x16x32_bf16 v[76:79], v[166:169], v[208:211], v[76:79]
	v_mfma_f32_16x16x32_bf16 v[76:79], v[170:173], v[212:215], v[76:79]
	v_mfma_f32_16x16x32_bf16 v[72:75], v[178:181], v[212:215], v[72:75]
	v_mfma_f32_16x16x32_bf16 v[72:75], v[174:177], v[208:211], v[72:75]
	v_mfma_f32_16x16x32_bf16 v[64:67], v[174:177], v[216:219], v[64:67]
	v_mfma_f32_16x16x32_bf16 v[64:67], v[178:181], v[220:223], v[64:67]
	v_mfma_f32_16x16x32_bf16 v[68:71], v[170:173], v[220:223], v[68:71]
	v_mfma_f32_16x16x32_bf16 v[68:71], v[166:169], v[216:219], v[68:71]
	v_mfma_f32_16x16x32_bf16 v[80:83], v[158:161], v[216:219], v[80:83]
	v_mfma_f32_16x16x32_bf16 v[80:83], v[162:165], v[220:223], v[80:83]
	v_mfma_f32_16x16x32_bf16 v[88:91], v[154:157], v[220:223], v[88:91]
	v_mfma_f32_16x16x32_bf16 v[88:91], v[150:153], v[216:219], v[88:91]
	s_setprio 0
	s_barrier
; #define PG8_STAGE(bufoff, gbase, voff) do { _Pragma("unroll") for (int _i = 0; _i < 2; ++_i) \
;         __builtin_amdgcn_global_load_lds((const unsigned*)((const char*)(gbase) + (voff)[_i]), (LAS unsigned*)(lds + (bufoff) + ldsw + _i * 8192), 16, 0, 0); } while (0)
; #define PG8_LDA(dst, b, h) do { _Pragma("unroll") for (int m = 0; m < 4; ++m) _Pragma("unroll") for (int k = 0; k < 2; ++k) dst[m][k] = *(const LAS bf16x8*)(lds + PG8_SA(b, h) + aoff + m * 2048 + k * 1024); } while (0)
; #define PG8_MMA(ai, bj, At, Bt) do { __builtin_amdgcn_s_setprio(1); _Pragma("unroll") for (int m = 0; m < 4; ++m) _Pragma("unroll") for (int n = 0; n < 2; ++n) _Pragma("unroll") for (int k = 0; k < 2; ++k) \
;         acc[ai][bj][m][n] = __builtin_amdgcn_mfma_f32_16x16x32_bf16(Bt[n][k], At[m][k], acc[ai][bj][m][n], 0, 0, 0); __builtin_amdgcn_s_setprio(0); } while (0)
; #define PG8_WAIT_V(n) asm volatile("s_waitcnt vmcnt(" #n ")" ::: "memory")
; #define PG8_WAIT_L(n) asm volatile("s_waitcnt lgkmcnt(" #n ")" ::: "memory")
; #define PG8_BAR __builtin_amdgcn_s_barrier()
; #define PG8_SCHED __builtin_amdgcn_sched_barrier(0)
; template <class Epi>
; __device__ __forceinline__ void gemm_phase(LAS unsigned char* lds, const Gemm g, const StaticOrder& S, const Epi& E) {
;     ...
;             PG8_LDA(At, 1, 1); PG8_STAGE(PG8_SB(1, 0), b3, voffB); PG8_STAGE(PG8_SB(1, 1), b3 + hstepB, voffB); PG8_STAGE(PG8_SA(1, 0), a3, voffA);
;             PG8_WAIT_V(8); PG8_WAIT_L(0); PG8_BAR; PG8_MMA(1, 0, At, B0); PG8_MMA(1, 1, At, B1); PG8_BAR; PG8_SCHED;
	s_add_i32 s4, s85, s58
	v_lshl_add_u64 v[224:225], v[224:225], 0, s[16:17]
	s_mov_b32 m0, s4
	ds_read_b128 v[182:185], v189 offset:49152
	ds_read_b128 v[192:195], v189 offset:50176
	ds_read_b128 v[196:199], v189 offset:51200
	ds_read_b128 v[200:203], v189 offset:52224
	ds_read_b128 v[208:211], v189 offset:53248
	ds_read_b128 v[212:215], v189 offset:54272
	ds_read_b128 v[216:219], v189 offset:55296
	ds_read_b128 v[220:223], v189 offset:56320
	global_load_lds_dwordx4 v[224:225], off
	s_add_i32 m0, s4, 0x2000
	s_add_u32 s4, s52, 0x158080
	v_lshl_add_u64 v[224:225], v[226:227], 0, s[16:17]
	s_addc_u32 s5, s53, 0
	s_add_i32 s52, s86, s58
	global_load_lds_dwordx4 v[224:225], off
	v_lshl_add_u64 v[224:225], s[4:5], 0, v[130:131]
	s_mov_b32 m0, s52
	s_nop 0
	global_load_lds_dwordx4 v[224:225], off
	v_lshl_add_u64 v[224:225], s[4:5], 0, v[134:135]
	s_add_i32 m0, s52, 0x2000
	s_nop 0
	global_load_lds_dwordx4 v[224:225], off
	v_lshl_add_u64 v[224:225], v[230:231], 0, s[16:17]
	s_mov_b32 m0, s65
	s_nop 0
	global_load_lds_dwordx4 v[224:225], off
	v_lshl_add_u64 v[224:225], v[232:233], 0, s[16:17]
	s_mov_b32 m0, s66
	s_nop 0
	global_load_lds_dwordx4 v[224:225], off
	s_waitcnt vmcnt(8)
	s_waitcnt lgkmcnt(0)
	s_setprio 1
	s_barrier
	s_waitcnt lgkmcnt(0)
	v_mfma_f32_16x16x32_bf16 v[60:63], v[150:153], v[182:185], v[60:63]
	v_mfma_f32_16x16x32_bf16 v[60:63], v[154:157], v[192:195], v[60:63]
	v_mfma_f32_16x16x32_bf16 v[56:59], v[162:165], v[192:195], v[56:59]
	v_mfma_f32_16x16x32_bf16 v[56:59], v[158:161], v[182:185], v[56:59]
	v_mfma_f32_16x16x32_bf16 v[44:47], v[166:169], v[182:185], v[44:47]
	v_mfma_f32_16x16x32_bf16 v[44:47], v[170:173], v[192:195], v[44:47]
	v_mfma_f32_16x16x32_bf16 v[36:39], v[178:181], v[192:195], v[36:39]
	v_mfma_f32_16x16x32_bf16 v[36:39], v[174:177], v[182:185], v[36:39]
	v_mfma_f32_16x16x32_bf16 v[20:23], v[174:177], v[196:199], v[20:23]
	v_mfma_f32_16x16x32_bf16 v[20:23], v[178:181], v[200:203], v[20:23]
	v_mfma_f32_16x16x32_bf16 v[28:31], v[170:173], v[200:203], v[28:31]
	v_mfma_f32_16x16x32_bf16 v[28:31], v[166:169], v[196:199], v[28:31]
	v_mfma_f32_16x16x32_bf16 v[48:51], v[158:161], v[196:199], v[48:51]
	v_mfma_f32_16x16x32_bf16 v[48:51], v[162:165], v[200:203], v[48:51]
	v_mfma_f32_16x16x32_bf16 v[52:55], v[154:157], v[200:203], v[52:55]
	v_mfma_f32_16x16x32_bf16 v[52:55], v[150:153], v[196:199], v[52:55]
	s_setprio 0
	s_setprio 1
	v_mfma_f32_16x16x32_bf16 v[40:43], v[150:153], v[208:211], v[40:43]
	v_mfma_f32_16x16x32_bf16 v[40:43], v[154:157], v[212:215], v[40:43]
	v_mfma_f32_16x16x32_bf16 v[32:35], v[162:165], v[212:215], v[32:35]
	v_mfma_f32_16x16x32_bf16 v[32:35], v[158:161], v[208:211], v[32:35]
	v_mfma_f32_16x16x32_bf16 v[12:15], v[166:169], v[208:211], v[12:15]
	v_mfma_f32_16x16x32_bf16 v[12:15], v[170:173], v[212:215], v[12:15]
	v_mfma_f32_16x16x32_bf16 v[8:11], v[178:181], v[212:215], v[8:11]
	v_mfma_f32_16x16x32_bf16 v[8:11], v[174:177], v[208:211], v[8:11]
	v_mfma_f32_16x16x32_bf16 v[0:3], v[174:177], v[216:219], v[0:3]
	v_mfma_f32_16x16x32_bf16 v[0:3], v[178:181], v[220:223], v[0:3]
	v_mfma_f32_16x16x32_bf16 v[4:7], v[170:173], v[220:223], v[4:7]
	v_mfma_f32_16x16x32_bf16 v[4:7], v[166:169], v[216:219], v[4:7]
	v_mfma_f32_16x16x32_bf16 v[16:19], v[158:161], v[216:219], v[16:19]
	v_mfma_f32_16x16x32_bf16 v[16:19], v[162:165], v[220:223], v[16:19]
	v_mfma_f32_16x16x32_bf16 v[24:27], v[154:157], v[220:223], v[24:27]
	v_mfma_f32_16x16x32_bf16 v[24:27], v[150:153], v[216:219], v[24:27]
	s_setprio 0
	s_barrier
	s_add_u32 s1, s1, 0x100
	s_addc_u32 s77, s77, 0
	s_cmp_ge_i32 s84, s64
	s_mov_b64 s[4:5], s[12:13]
	s_mov_b32 s52, s84
	s_cbranch_scc0 .LBB0_1244
	v_pk_mul_f32 v[170:171], v[126:127], 0.5 op_sel_hi:[1,0]
	v_pk_mul_f32 v[172:173], v[124:125], 0.5 op_sel_hi:[1,0]
	v_pk_mul_f32 v[174:175], v[122:123], 0.5 op_sel_hi:[1,0]
	v_pk_mul_f32 v[176:177], v[120:121], 0.5 op_sel_hi:[1,0]
	v_pk_mul_f32 v[178:179], v[110:111], 0.5 op_sel_hi:[1,0]
	v_pk_mul_f32 v[180:181], v[108:109], 0.5 op_sel_hi:[1,0]
	v_pk_mul_f32 v[182:183], v[102:103], 0.5 op_sel_hi:[1,0]
	v_pk_mul_f32 v[184:185], v[100:101], 0.5 op_sel_hi:[1,0]
	v_pk_mul_f32 v[160:161], v[118:119], 0.5 op_sel_hi:[1,0]
	v_pk_mul_f32 v[158:159], v[116:117], 0.5 op_sel_hi:[1,0]
	v_pk_mul_f32 v[156:157], v[114:115], 0.5 op_sel_hi:[1,0]
	v_pk_mul_f32 v[154:155], v[112:113], 0.5 op_sel_hi:[1,0]
	v_pk_mul_f32 v[168:169], v[94:95], 0.5 op_sel_hi:[1,0]
	v_pk_mul_f32 v[166:167], v[92:93], 0.5 op_sel_hi:[1,0]
	v_pk_mul_f32 v[164:165], v[86:87], 0.5 op_sel_hi:[1,0]
	v_pk_mul_f32 v[162:163], v[84:85], 0.5 op_sel_hi:[1,0]
	v_pk_mul_f32 v[116:117], v[106:107], 0.5 op_sel_hi:[1,0]
	v_pk_mul_f32 v[118:119], v[104:105], 0.5 op_sel_hi:[1,0]
	v_pk_mul_f32 v[120:121], v[98:99], 0.5 op_sel_hi:[1,0]
	v_pk_mul_f32 v[122:123], v[96:97], 0.5 op_sel_hi:[1,0]
	v_pk_mul_f32 v[124:125], v[78:79], 0.5 op_sel_hi:[1,0]
	v_pk_mul_f32 v[126:127], v[76:77], 0.5 op_sel_hi:[1,0]
	v_pk_mul_f32 v[150:151], v[74:75], 0.5 op_sel_hi:[1,0]
	v_pk_mul_f32 v[152:153], v[72:73], 0.5 op_sel_hi:[1,0]
	v_pk_mul_f32 v[104:105], v[90:91], 0.5 op_sel_hi:[1,0]
	v_pk_mul_f32 v[102:103], v[88:89], 0.5 op_sel_hi:[1,0]
	v_pk_mul_f32 v[100:101], v[82:83], 0.5 op_sel_hi:[1,0]
	v_pk_mul_f32 v[98:99], v[80:81], 0.5 op_sel_hi:[1,0]
	v_pk_mul_f32 v[112:113], v[70:71], 0.5 op_sel_hi:[1,0]
	v_pk_mul_f32 v[110:111], v[68:69], 0.5 op_sel_hi:[1,0]
	v_pk_mul_f32 v[108:109], v[66:67], 0.5 op_sel_hi:[1,0]
	v_pk_mul_f32 v[106:107], v[64:65], 0.5 op_sel_hi:[1,0]
	v_pk_mul_f32 v[80:81], v[62:63], 0.5 op_sel_hi:[1,0]
	v_pk_mul_f32 v[82:83], v[60:61], 0.5 op_sel_hi:[1,0]
	v_pk_mul_f32 v[84:85], v[58:59], 0.5 op_sel_hi:[1,0]
	v_pk_mul_f32 v[86:87], v[56:57], 0.5 op_sel_hi:[1,0]
	v_pk_mul_f32 v[88:89], v[46:47], 0.5 op_sel_hi:[1,0]
	v_pk_mul_f32 v[90:91], v[44:45], 0.5 op_sel_hi:[1,0]
	v_pk_mul_f32 v[92:93], v[38:39], 0.5 op_sel_hi:[1,0]
	v_pk_mul_f32 v[94:95], v[36:37], 0.5 op_sel_hi:[1,0]
	v_pk_mul_f32 v[70:71], v[54:55], 0.5 op_sel_hi:[1,0]
	v_pk_mul_f32 v[68:69], v[52:53], 0.5 op_sel_hi:[1,0]
	v_pk_mul_f32 v[66:67], v[50:51], 0.5 op_sel_hi:[1,0]
	v_pk_mul_f32 v[64:65], v[48:49], 0.5 op_sel_hi:[1,0]
	v_pk_mul_f32 v[78:79], v[30:31], 0.5 op_sel_hi:[1,0]
	v_pk_mul_f32 v[76:77], v[28:29], 0.5 op_sel_hi:[1,0]
	v_pk_mul_f32 v[74:75], v[22:23], 0.5 op_sel_hi:[1,0]
	v_pk_mul_f32 v[72:73], v[20:21], 0.5 op_sel_hi:[1,0]
	v_pk_mul_f32 v[54:55], v[42:43], 0.5 op_sel_hi:[1,0]
	v_pk_mul_f32 v[52:53], v[40:41], 0.5 op_sel_hi:[1,0]
	v_pk_mul_f32 v[50:51], v[34:35], 0.5 op_sel_hi:[1,0]
	v_pk_mul_f32 v[48:49], v[32:33], 0.5 op_sel_hi:[1,0]
	v_pk_mul_f32 v[62:63], v[14:15], 0.5 op_sel_hi:[1,0]
	v_pk_mul_f32 v[60:61], v[12:13], 0.5 op_sel_hi:[1,0]
	v_pk_mul_f32 v[58:59], v[10:11], 0.5 op_sel_hi:[1,0]
	v_pk_mul_f32 v[56:57], v[8:9], 0.5 op_sel_hi:[1,0]
	v_pk_mul_f32 v[38:39], v[26:27], 0.5 op_sel_hi:[1,0]
	v_pk_mul_f32 v[36:37], v[24:25], 0.5 op_sel_hi:[1,0]
	v_pk_mul_f32 v[34:35], v[18:19], 0.5 op_sel_hi:[1,0]
	v_pk_mul_f32 v[32:33], v[16:17], 0.5 op_sel_hi:[1,0]
	v_pk_mul_f32 v[46:47], v[6:7], 0.5 op_sel_hi:[1,0]
	v_pk_mul_f32 v[44:45], v[4:5], 0.5 op_sel_hi:[1,0]
	v_pk_mul_f32 v[42:43], v[2:3], 0.5 op_sel_hi:[1,0]
	v_pk_mul_f32 v[40:41], v[0:1], 0.5 op_sel_hi:[1,0]

; #define PG8_STAGE(bufoff, gbase, voff) do { _Pragma("unroll") for (int _i = 0; _i < 2; ++_i) \
;         __builtin_amdgcn_global_load_lds((const unsigned*)((const char*)(gbase) + (voff)[_i]), (LAS unsigned*)(lds + (bufoff) + ldsw + _i * 8192), 16, 0, 0); } while (0)
; #define PG8_LDA(dst, b, h) do { _Pragma("unroll") for (int m = 0; m < 4; ++m) _Pragma("unroll") for (int k = 0; k < 2; ++k) dst[m][k] = *(const LAS bf16x8*)(lds + PG8_SA(b, h) + aoff + m * 2048 + k * 1024); } while (0)
; #define PG8_LDB(dst, b, h) do { _Pragma("unroll") for (int n = 0; n < 2; ++n) _Pragma("unroll") for (int k = 0; k < 2; ++k) dst[n][k] = *(const LAS bf16x8*)(lds + PG8_SB(b, h) + boff + n * 2048 + k * 1024); } while (0)
; #define PG8_MMA(ai, bj, At, Bt) do { __builtin_amdgcn_s_setprio(1); _Pragma("unroll") for (int m = 0; m < 4; ++m) _Pragma("unroll") for (int n = 0; n < 2; ++n) _Pragma("unroll") for (int k = 0; k < 2; ++k) \
;         acc[ai][bj][m][n] = __builtin_amdgcn_mfma_f32_16x16x32_bf16(Bt[n][k], At[m][k], acc[ai][bj][m][n], 0, 0, 0); __builtin_amdgcn_s_setprio(0); } while (0)
; #define PG8_WAIT_V(n) asm volatile("s_waitcnt vmcnt(" #n ")" ::: "memory")
; #define PG8_WAIT_L(n) asm volatile("s_waitcnt lgkmcnt(" #n ")" ::: "memory")
; #define PG8_BAR __builtin_amdgcn_s_barrier()
; #define PG8_SCHED __builtin_amdgcn_sched_barrier(0)
; template <class Epi>
; __device__ __forceinline__ void gemm_phase(LAS unsigned char* lds, const Gemm g, const StaticOrder& S, const Epi& E) {
;     ...
;             PG8_LDB(B0, 0, 0); PG8_LDB(B1, 0, 1); PG8_SCHED; PG8_LDA(At, 0, 0); PG8_STAGE(PG8_SA(1, 1), a1 + hstepA, voffA);
;             PG8_WAIT_V(8); PG8_WAIT_L(0); PG8_BAR; PG8_MMA(0, 0, At, B0); PG8_MMA(0, 1, At, B1); PG8_BAR; PG8_SCHED;
;             PG8_LDA(At, 0, 1); PG8_STAGE(PG8_SB(0, 0), b2, voffB); PG8_STAGE(PG8_SB(0, 1), b2 + hstepB, voffB); PG8_STAGE(PG8_SA(0, 0), a2, voffA);
;             PG8_WAIT_V(8); PG8_WAIT_L(0); PG8_BAR; PG8_MMA(1, 0, At, B0); PG8_MMA(1, 1, At, B1); PG8_BAR; PG8_SCHED;
.LBB0_1338:
	ds_read_b128 v[128:131], v173
	ds_read_b128 v[132:135], v173 offset:1024
	ds_read_b128 v[136:139], v173 offset:2048
	ds_read_b128 v[140:143], v173 offset:3072
	ds_read_b128 v[144:147], v175
	ds_read_b128 v[148:151], v175 offset:1024
	ds_read_b128 v[176:179], v175 offset:2048
	ds_read_b128 v[184:187], v175 offset:3072
	s_add_i32 s20, s10, 2
	s_add_u32 s11, s8, 0xfff80080
	s_addc_u32 s12, s9, -1
	s_cmp_eq_u32 s56, s10
	s_cselect_b32 s10, s17, s18
	s_cselect_b32 s13, s1, s12
	s_cselect_b32 s12, s15, s11
	s_cselect_b32 s11, s16, s19
	v_lshl_add_u64 v[224:225], s[8:9], 0, v[164:165]
	s_add_i32 m0, s47, 0xc000
	ds_read_b128 v[188:191], v181
	ds_read_b128 v[192:195], v181 offset:1024
	ds_read_b128 v[196:199], v181 offset:2048
	ds_read_b128 v[200:203], v181 offset:3072
	ds_read_b128 v[208:211], v181 offset:4096
	ds_read_b128 v[212:215], v181 offset:5120
	ds_read_b128 v[216:219], v181 offset:6144
	ds_read_b128 v[220:223], v181 offset:7168
	global_load_lds_dwordx4 v[224:225], off
	v_lshl_add_u64 v[224:225], s[8:9], 0, v[166:167]
	s_add_i32 m0, s47, 0xe000
	s_nop 0
	global_load_lds_dwordx4 v[224:225], off
	s_waitcnt vmcnt(8)
	s_waitcnt lgkmcnt(0)
	s_setprio 1
	s_barrier
	s_waitcnt lgkmcnt(0)
	v_mfma_f32_16x16x32_bf16 v[124:127], v[128:131], v[188:191], v[124:127]
	v_mfma_f32_16x16x32_bf16 v[124:127], v[132:135], v[192:195], v[124:127]
	v_mfma_f32_16x16x32_bf16 v[120:123], v[140:143], v[192:195], v[120:123]
	v_mfma_f32_16x16x32_bf16 v[120:123], v[136:139], v[188:191], v[120:123]
	v_mfma_f32_16x16x32_bf16 v[116:119], v[144:147], v[188:191], v[116:119]
	v_mfma_f32_16x16x32_bf16 v[116:119], v[148:151], v[192:195], v[116:119]
	v_mfma_f32_16x16x32_bf16 v[112:115], v[184:187], v[192:195], v[112:115]
	v_mfma_f32_16x16x32_bf16 v[112:115], v[176:179], v[188:191], v[112:115]
	v_mfma_f32_16x16x32_bf16 v[96:99], v[176:179], v[196:199], v[96:99]
	v_mfma_f32_16x16x32_bf16 v[96:99], v[184:187], v[200:203], v[96:99]
	v_mfma_f32_16x16x32_bf16 v[100:103], v[148:151], v[200:203], v[100:103]
	v_mfma_f32_16x16x32_bf16 v[100:103], v[144:147], v[196:199], v[100:103]
	v_mfma_f32_16x16x32_bf16 v[104:107], v[136:139], v[196:199], v[104:107]
	v_mfma_f32_16x16x32_bf16 v[104:107], v[140:143], v[200:203], v[104:107]
	v_mfma_f32_16x16x32_bf16 v[108:111], v[132:135], v[200:203], v[108:111]
	v_mfma_f32_16x16x32_bf16 v[108:111], v[128:131], v[196:199], v[108:111]
	s_setprio 0
	s_setprio 1
	v_mfma_f32_16x16x32_bf16 v[92:95], v[128:131], v[208:211], v[92:95]
	v_mfma_f32_16x16x32_bf16 v[92:95], v[132:135], v[212:215], v[92:95]
	v_mfma_f32_16x16x32_bf16 v[88:91], v[140:143], v[212:215], v[88:91]
	v_mfma_f32_16x16x32_bf16 v[88:91], v[136:139], v[208:211], v[88:91]
	v_mfma_f32_16x16x32_bf16 v[84:87], v[144:147], v[208:211], v[84:87]
	v_mfma_f32_16x16x32_bf16 v[84:87], v[148:151], v[212:215], v[84:87]
	v_mfma_f32_16x16x32_bf16 v[80:83], v[184:187], v[212:215], v[80:83]
	v_mfma_f32_16x16x32_bf16 v[80:83], v[176:179], v[208:211], v[80:83]
	v_mfma_f32_16x16x32_bf16 v[64:67], v[176:179], v[216:219], v[64:67]
	v_mfma_f32_16x16x32_bf16 v[64:67], v[184:187], v[220:223], v[64:67]
	v_mfma_f32_16x16x32_bf16 v[68:71], v[148:151], v[220:223], v[68:71]
	v_mfma_f32_16x16x32_bf16 v[68:71], v[144:147], v[216:219], v[68:71]
	v_mfma_f32_16x16x32_bf16 v[72:75], v[136:139], v[216:219], v[72:75]
	v_mfma_f32_16x16x32_bf16 v[72:75], v[140:143], v[220:223], v[72:75]
	v_mfma_f32_16x16x32_bf16 v[76:79], v[132:135], v[220:223], v[76:79]
	v_mfma_f32_16x16x32_bf16 v[76:79], v[128:131], v[216:219], v[76:79]
	s_setprio 0
	s_barrier
	s_add_i32 s21, s59, s46
	v_lshl_add_u64 v[224:225], s[10:11], 0, v[154:155]
	s_mov_b32 m0, s21
	ds_read_b128 v[188:191], v181 offset:16384
	ds_read_b128 v[192:195], v181 offset:17408
	ds_read_b128 v[196:199], v181 offset:18432
	ds_read_b128 v[200:203], v181 offset:19456
	ds_read_b128 v[208:211], v181 offset:20480
	ds_read_b128 v[212:215], v181 offset:21504
	ds_read_b128 v[216:219], v181 offset:22528
	ds_read_b128 v[220:223], v181 offset:23552
	global_load_lds_dwordx4 v[224:225], off
	s_add_i32 m0, s21, 0x2000
	s_add_u32 s68, s10, 0x80000
	v_lshl_add_u64 v[226:227], s[10:11], 0, v[158:159]
	s_addc_u32 s69, s11, 0
	s_add_i32 s21, s60, s46
	global_load_lds_dwordx4 v[226:227], off
	v_lshl_add_u64 v[230:231], s[68:69], 0, v[154:155]
	s_mov_b32 m0, s21
	v_lshl_add_u64 v[232:233], s[12:13], 0, v[156:157]
	global_load_lds_dwordx4 v[230:231], off
	v_lshl_add_u64 v[230:231], s[68:69], 0, v[158:159]
	s_add_i32 m0, s21, 0x2000
	s_nop 0
	global_load_lds_dwordx4 v[230:231], off
	v_lshl_add_u64 v[230:231], s[12:13], 0, v[152:153]
	s_mov_b32 m0, s47
	s_nop 0
	global_load_lds_dwordx4 v[230:231], off
	s_mov_b32 m0, s48
	s_nop 0
	global_load_lds_dwordx4 v[232:233], off
	s_waitcnt vmcnt(8)
	s_waitcnt lgkmcnt(0)
	s_setprio 1
	s_barrier
; #define PG8_STAGE(bufoff, gbase, voff) do { _Pragma("unroll") for (int _i = 0; _i < 2; ++_i) \
;         __builtin_amdgcn_global_load_lds((const unsigned*)((const char*)(gbase) + (voff)[_i]), (LAS unsigned*)(lds + (bufoff) + ldsw + _i * 8192), 16, 0, 0); } while (0)
; #define PG8_LDA(dst, b, h) do { _Pragma("unroll") for (int m = 0; m < 4; ++m) _Pragma("unroll") for (int k = 0; k < 2; ++k) dst[m][k] = *(const LAS bf16x8*)(lds + PG8_SA(b, h) + aoff + m * 2048 + k * 1024); } while (0)
; #define PG8_LDB(dst, b, h) do { _Pragma("unroll") for (int n = 0; n < 2; ++n) _Pragma("unroll") for (int k = 0; k < 2; ++k) dst[n][k] = *(const LAS bf16x8*)(lds + PG8_SB(b, h) + boff + n * 2048 + k * 1024); } while (0)
; #define PG8_MMA(ai, bj, At, Bt) do { __builtin_amdgcn_s_setprio(1); _Pragma("unroll") for (int m = 0; m < 4; ++m) _Pragma("unroll") for (int n = 0; n < 2; ++n) _Pragma("unroll") for (int k = 0; k < 2; ++k) \
;         acc[ai][bj][m][n] = __builtin_amdgcn_mfma_f32_16x16x32_bf16(Bt[n][k], At[m][k], acc[ai][bj][m][n], 0, 0, 0); __builtin_amdgcn_s_setprio(0); } while (0)
; #define PG8_WAIT_V(n) asm volatile("s_waitcnt vmcnt(" #n ")" ::: "memory")
; #define PG8_WAIT_L(n) asm volatile("s_waitcnt lgkmcnt(" #n ")" ::: "memory")
; #define PG8_BAR __builtin_amdgcn_s_barrier()
; #define PG8_SCHED __builtin_amdgcn_sched_barrier(0)
; template <class Epi>
; __device__ __forceinline__ void gemm_phase(LAS unsigned char* lds, const Gemm g, const StaticOrder& S, const Epi& E) {
;     ...
;             PG8_WAIT_V(8); PG8_WAIT_L(0); PG8_BAR; PG8_MMA(1, 0, At, B0); PG8_MMA(1, 1, At, B1); PG8_BAR; PG8_SCHED;
;             PG8_LDB(B0, 1, 0); PG8_LDB(B1, 1, 1); PG8_SCHED; PG8_LDA(At, 1, 0); PG8_STAGE(PG8_SA(0, 1), a2 + hstepA, voffA);
;             PG8_WAIT_V(8); PG8_WAIT_L(0); PG8_BAR; PG8_MMA(0, 0, At, B0); PG8_MMA(0, 1, At, B1); PG8_BAR; PG8_SCHED;
	s_waitcnt lgkmcnt(0)
	v_mfma_f32_16x16x32_bf16 v[60:63], v[128:131], v[188:191], v[60:63]
	v_mfma_f32_16x16x32_bf16 v[60:63], v[132:135], v[192:195], v[60:63]
	v_mfma_f32_16x16x32_bf16 v[56:59], v[140:143], v[192:195], v[56:59]
	v_mfma_f32_16x16x32_bf16 v[56:59], v[136:139], v[188:191], v[56:59]
	v_mfma_f32_16x16x32_bf16 v[52:55], v[144:147], v[188:191], v[52:55]
	v_mfma_f32_16x16x32_bf16 v[52:55], v[148:151], v[192:195], v[52:55]
	v_mfma_f32_16x16x32_bf16 v[48:51], v[184:187], v[192:195], v[48:51]
	v_mfma_f32_16x16x32_bf16 v[48:51], v[176:179], v[188:191], v[48:51]
	v_mfma_f32_16x16x32_bf16 v[32:35], v[176:179], v[196:199], v[32:35]
	v_mfma_f32_16x16x32_bf16 v[32:35], v[184:187], v[200:203], v[32:35]
	v_mfma_f32_16x16x32_bf16 v[36:39], v[148:151], v[200:203], v[36:39]
	v_mfma_f32_16x16x32_bf16 v[36:39], v[144:147], v[196:199], v[36:39]
	v_mfma_f32_16x16x32_bf16 v[40:43], v[136:139], v[196:199], v[40:43]
	v_mfma_f32_16x16x32_bf16 v[40:43], v[140:143], v[200:203], v[40:43]
	v_mfma_f32_16x16x32_bf16 v[44:47], v[132:135], v[200:203], v[44:47]
	v_mfma_f32_16x16x32_bf16 v[44:47], v[128:131], v[196:199], v[44:47]
	s_setprio 0
	s_setprio 1
	v_mfma_f32_16x16x32_bf16 v[28:31], v[128:131], v[208:211], v[28:31]
	v_mfma_f32_16x16x32_bf16 v[28:31], v[132:135], v[212:215], v[28:31]
	v_mfma_f32_16x16x32_bf16 v[24:27], v[140:143], v[212:215], v[24:27]
	v_mfma_f32_16x16x32_bf16 v[24:27], v[136:139], v[208:211], v[24:27]
	v_mfma_f32_16x16x32_bf16 v[20:23], v[144:147], v[208:211], v[20:23]
	v_mfma_f32_16x16x32_bf16 v[20:23], v[148:151], v[212:215], v[20:23]
	v_mfma_f32_16x16x32_bf16 v[16:19], v[184:187], v[212:215], v[16:19]
	v_mfma_f32_16x16x32_bf16 v[16:19], v[176:179], v[208:211], v[16:19]
	v_mfma_f32_16x16x32_bf16 v[0:3], v[176:179], v[216:219], v[0:3]
	v_mfma_f32_16x16x32_bf16 v[0:3], v[184:187], v[220:223], v[0:3]
	v_mfma_f32_16x16x32_bf16 v[4:7], v[148:151], v[220:223], v[4:7]
	v_mfma_f32_16x16x32_bf16 v[4:7], v[144:147], v[216:219], v[4:7]
	v_mfma_f32_16x16x32_bf16 v[8:11], v[136:139], v[216:219], v[8:11]
	v_mfma_f32_16x16x32_bf16 v[8:11], v[140:143], v[220:223], v[8:11]
	v_mfma_f32_16x16x32_bf16 v[12:15], v[132:135], v[220:223], v[12:15]
	v_mfma_f32_16x16x32_bf16 v[12:15], v[128:131], v[216:219], v[12:15]
	s_setprio 0
	s_barrier
	s_add_i32 s21, 0, 0x18000
	s_add_i32 s33, 0, 0x1c000
	v_add_u32_e32 v140, s21, v163
	v_add_u32_e32 v172, s33, v163
	ds_read_b128 v[128:131], v140
	ds_read_b128 v[132:135], v140 offset:1024
	ds_read_b128 v[136:139], v140 offset:2048
	ds_read_b128 v[140:143], v140 offset:3072
	ds_read_b128 v[144:147], v172
	ds_read_b128 v[148:151], v172 offset:1024
	ds_read_b128 v[176:179], v172 offset:2048
	ds_read_b128 v[184:187], v172 offset:3072
	s_add_u32 s12, s12, 0x80000
	s_addc_u32 s13, s13, 0
	s_mov_b32 m0, s49
	v_lshl_add_u64 v[234:235], s[12:13], 0, v[152:153]
	ds_read_b128 v[188:191], v181 offset:32768
	ds_read_b128 v[192:195], v181 offset:33792
	ds_read_b128 v[196:199], v181 offset:34816
	ds_read_b128 v[200:203], v181 offset:35840
	ds_read_b128 v[208:211], v181 offset:36864
	ds_read_b128 v[212:215], v181 offset:37888
	ds_read_b128 v[216:219], v181 offset:38912
	ds_read_b128 v[220:223], v181 offset:39936
	global_load_lds_dwordx4 v[234:235], off
	v_lshl_add_u64 v[234:235], s[12:13], 0, v[156:157]
	s_mov_b32 m0, s50
	s_nop 0
	global_load_lds_dwordx4 v[234:235], off
	s_waitcnt vmcnt(8)
	s_waitcnt lgkmcnt(0)
	s_setprio 1
	s_barrier
	s_waitcnt lgkmcnt(0)
	v_mfma_f32_16x16x32_bf16 v[124:127], v[128:131], v[188:191], v[124:127]
	v_mfma_f32_16x16x32_bf16 v[124:127], v[132:135], v[192:195], v[124:127]
	v_mfma_f32_16x16x32_bf16 v[120:123], v[140:143], v[192:195], v[120:123]
	v_mfma_f32_16x16x32_bf16 v[120:123], v[136:139], v[188:191], v[120:123]
	v_mfma_f32_16x16x32_bf16 v[116:119], v[144:147], v[188:191], v[116:119]
	v_mfma_f32_16x16x32_bf16 v[116:119], v[148:151], v[192:195], v[116:119]
	v_mfma_f32_16x16x32_bf16 v[112:115], v[184:187], v[192:195], v[112:115]
	v_mfma_f32_16x16x32_bf16 v[112:115], v[176:179], v[188:191], v[112:115]
	v_mfma_f32_16x16x32_bf16 v[96:99], v[176:179], v[196:199], v[96:99]
	v_mfma_f32_16x16x32_bf16 v[96:99], v[184:187], v[200:203], v[96:99]
	v_mfma_f32_16x16x32_bf16 v[100:103], v[148:151], v[200:203], v[100:103]
	v_mfma_f32_16x16x32_bf16 v[100:103], v[144:147], v[196:199], v[100:103]
	v_mfma_f32_16x16x32_bf16 v[104:107], v[136:139], v[196:199], v[104:107]
	v_mfma_f32_16x16x32_bf16 v[104:107], v[140:143], v[200:203], v[104:107]
	v_mfma_f32_16x16x32_bf16 v[108:111], v[132:135], v[200:203], v[108:111]
	v_mfma_f32_16x16x32_bf16 v[108:111], v[128:131], v[196:199], v[108:111]
	s_setprio 0
	s_setprio 1
	v_mfma_f32_16x16x32_bf16 v[92:95], v[128:131], v[208:211], v[92:95]
	v_mfma_f32_16x16x32_bf16 v[92:95], v[132:135], v[212:215], v[92:95]
	v_mfma_f32_16x16x32_bf16 v[88:91], v[140:143], v[212:215], v[88:91]
	v_mfma_f32_16x16x32_bf16 v[88:91], v[136:139], v[208:211], v[88:91]
	v_mfma_f32_16x16x32_bf16 v[84:87], v[144:147], v[208:211], v[84:87]
	v_mfma_f32_16x16x32_bf16 v[84:87], v[148:151], v[212:215], v[84:87]
	v_mfma_f32_16x16x32_bf16 v[80:83], v[184:187], v[212:215], v[80:83]
	v_mfma_f32_16x16x32_bf16 v[80:83], v[176:179], v[208:211], v[80:83]
	v_mfma_f32_16x16x32_bf16 v[64:67], v[176:179], v[216:219], v[64:67]
	v_mfma_f32_16x16x32_bf16 v[64:67], v[184:187], v[220:223], v[64:67]
	v_mfma_f32_16x16x32_bf16 v[68:71], v[148:151], v[220:223], v[68:71]
	v_mfma_f32_16x16x32_bf16 v[68:71], v[144:147], v[216:219], v[68:71]
	v_mfma_f32_16x16x32_bf16 v[72:75], v[136:139], v[216:219], v[72:75]
	v_mfma_f32_16x16x32_bf16 v[72:75], v[140:143], v[220:223], v[72:75]
	v_mfma_f32_16x16x32_bf16 v[76:79], v[132:135], v[220:223], v[76:79]
	v_mfma_f32_16x16x32_bf16 v[76:79], v[128:131], v[216:219], v[76:79]
	s_setprio 0
	s_barrier
; #define PG8_STAGE(bufoff, gbase, voff) do { _Pragma("unroll") for (int _i = 0; _i < 2; ++_i) \
;         __builtin_amdgcn_global_load_lds((const unsigned*)((const char*)(gbase) + (voff)[_i]), (LAS unsigned*)(lds + (bufoff) + ldsw + _i * 8192), 16, 0, 0); } while (0)
; #define PG8_LDA(dst, b, h) do { _Pragma("unroll") for (int m = 0; m < 4; ++m) _Pragma("unroll") for (int k = 0; k < 2; ++k) dst[m][k] = *(const LAS bf16x8*)(lds + PG8_SA(b, h) + aoff + m * 2048 + k * 1024); } while (0)
; #define PG8_MMA(ai, bj, At, Bt) do { __builtin_amdgcn_s_setprio(1); _Pragma("unroll") for (int m = 0; m < 4; ++m) _Pragma("unroll") for (int n = 0; n < 2; ++n) _Pragma("unroll") for (int k = 0; k < 2; ++k) \
;         acc[ai][bj][m][n] = __builtin_amdgcn_mfma_f32_16x16x32_bf16(Bt[n][k], At[m][k], acc[ai][bj][m][n], 0, 0, 0); __builtin_amdgcn_s_setprio(0); } while (0)
; #define PG8_WAIT_V(n) asm volatile("s_waitcnt vmcnt(" #n ")" ::: "memory")
; #define PG8_WAIT_L(n) asm volatile("s_waitcnt lgkmcnt(" #n ")" ::: "memory")
; #define PG8_BAR __builtin_amdgcn_s_barrier()
; #define PG8_SCHED __builtin_amdgcn_sched_barrier(0)
; template <class Epi>
; __device__ __forceinline__ void gemm_phase(LAS unsigned char* lds, const Gemm g, const StaticOrder& S, const Epi& E) {
;     ...
;             PG8_LDA(At, 1, 1); PG8_STAGE(PG8_SB(1, 0), b3, voffB); PG8_STAGE(PG8_SB(1, 1), b3 + hstepB, voffB); PG8_STAGE(PG8_SA(1, 0), a3, voffA);
;             PG8_WAIT_V(8); PG8_WAIT_L(0); PG8_BAR; PG8_MMA(1, 0, At, B0); PG8_MMA(1, 1, At, B1); PG8_BAR; PG8_SCHED;
	s_add_i32 s12, s21, s46
	v_lshl_add_u64 v[224:225], v[224:225], 0, s[28:29]
	s_mov_b32 m0, s12
	ds_read_b128 v[188:191], v181 offset:49152
	ds_read_b128 v[192:195], v181 offset:50176
	ds_read_b128 v[196:199], v181 offset:51200
	ds_read_b128 v[200:203], v181 offset:52224
	ds_read_b128 v[208:211], v181 offset:53248
	ds_read_b128 v[212:215], v181 offset:54272
	ds_read_b128 v[216:219], v181 offset:55296
	ds_read_b128 v[220:223], v181 offset:56320
	global_load_lds_dwordx4 v[224:225], off
	s_add_i32 m0, s12, 0x2000
	s_add_u32 s10, s10, 0x80080
	v_lshl_add_u64 v[224:225], v[226:227], 0, s[28:29]
	s_addc_u32 s11, s11, 0
	s_add_i32 s12, s33, s46
	global_load_lds_dwordx4 v[224:225], off
	v_lshl_add_u64 v[224:225], s[10:11], 0, v[154:155]
	s_mov_b32 m0, s12
	s_nop 0
	global_load_lds_dwordx4 v[224:225], off
	v_lshl_add_u64 v[224:225], s[10:11], 0, v[158:159]
	s_add_i32 m0, s12, 0x2000
	s_nop 0
	global_load_lds_dwordx4 v[224:225], off
	v_lshl_add_u64 v[224:225], v[230:231], 0, s[28:29]
	s_mov_b32 m0, s54
	s_nop 0
	global_load_lds_dwordx4 v[224:225], off
	v_lshl_add_u64 v[224:225], v[232:233], 0, s[28:29]
	s_mov_b32 m0, s55
	s_nop 0
	global_load_lds_dwordx4 v[224:225], off
	s_waitcnt vmcnt(8)
	s_waitcnt lgkmcnt(0)
	s_setprio 1
	s_barrier
	s_waitcnt lgkmcnt(0)
	v_mfma_f32_16x16x32_bf16 v[60:63], v[128:131], v[188:191], v[60:63]
	v_mfma_f32_16x16x32_bf16 v[60:63], v[132:135], v[192:195], v[60:63]
	v_mfma_f32_16x16x32_bf16 v[56:59], v[140:143], v[192:195], v[56:59]
	v_mfma_f32_16x16x32_bf16 v[56:59], v[136:139], v[188:191], v[56:59]
	v_mfma_f32_16x16x32_bf16 v[52:55], v[144:147], v[188:191], v[52:55]
	v_mfma_f32_16x16x32_bf16 v[52:55], v[148:151], v[192:195], v[52:55]
	v_mfma_f32_16x16x32_bf16 v[48:51], v[184:187], v[192:195], v[48:51]
	v_mfma_f32_16x16x32_bf16 v[48:51], v[176:179], v[188:191], v[48:51]
	v_mfma_f32_16x16x32_bf16 v[32:35], v[176:179], v[196:199], v[32:35]
	v_mfma_f32_16x16x32_bf16 v[32:35], v[184:187], v[200:203], v[32:35]
	v_mfma_f32_16x16x32_bf16 v[36:39], v[148:151], v[200:203], v[36:39]
	v_mfma_f32_16x16x32_bf16 v[36:39], v[144:147], v[196:199], v[36:39]
	v_mfma_f32_16x16x32_bf16 v[40:43], v[136:139], v[196:199], v[40:43]
	v_mfma_f32_16x16x32_bf16 v[40:43], v[140:143], v[200:203], v[40:43]
	v_mfma_f32_16x16x32_bf16 v[44:47], v[132:135], v[200:203], v[44:47]
	v_mfma_f32_16x16x32_bf16 v[44:47], v[128:131], v[196:199], v[44:47]
	s_setprio 0
	s_setprio 1
	v_mfma_f32_16x16x32_bf16 v[28:31], v[128:131], v[208:211], v[28:31]
	v_mfma_f32_16x16x32_bf16 v[28:31], v[132:135], v[212:215], v[28:31]
	v_mfma_f32_16x16x32_bf16 v[24:27], v[140:143], v[212:215], v[24:27]
	v_mfma_f32_16x16x32_bf16 v[24:27], v[136:139], v[208:211], v[24:27]
	v_mfma_f32_16x16x32_bf16 v[20:23], v[144:147], v[208:211], v[20:23]
	v_mfma_f32_16x16x32_bf16 v[20:23], v[148:151], v[212:215], v[20:23]
	v_mfma_f32_16x16x32_bf16 v[16:19], v[184:187], v[212:215], v[16:19]
	v_mfma_f32_16x16x32_bf16 v[16:19], v[176:179], v[208:211], v[16:19]
	v_mfma_f32_16x16x32_bf16 v[0:3], v[176:179], v[216:219], v[0:3]
	v_mfma_f32_16x16x32_bf16 v[0:3], v[184:187], v[220:223], v[0:3]
	v_mfma_f32_16x16x32_bf16 v[4:7], v[148:151], v[220:223], v[4:7]
	v_mfma_f32_16x16x32_bf16 v[4:7], v[144:147], v[216:219], v[4:7]
	v_mfma_f32_16x16x32_bf16 v[8:11], v[136:139], v[216:219], v[8:11]
	v_mfma_f32_16x16x32_bf16 v[8:11], v[140:143], v[220:223], v[8:11]
	v_mfma_f32_16x16x32_bf16 v[12:15], v[132:135], v[220:223], v[12:15]
	v_mfma_f32_16x16x32_bf16 v[12:15], v[128:131], v[216:219], v[12:15]
	s_setprio 0
	s_barrier
	s_add_u32 s8, s8, 0x100
	s_addc_u32 s9, s9, 0
	s_add_u32 s18, s18, 0x100
	s_addc_u32 s19, s19, 0
	s_cmp_ge_i32 s20, s53
	s_mov_b32 s10, s20
	s_cbranch_scc0 .LBB0_1338
